# GEMM phase blocks: the two K-half MFMAs of each accumulator issued back-to-back (accumulate chain), snake order over operands otherwise
# speedup vs baseline: 1.0131x; 1.0131x over previous
; #define PG8_STAGE(bufoff, gbase, voff) do { _Pragma("unroll") for (int _i = 0; _i < 2; ++_i) \
;         __builtin_amdgcn_global_load_lds((const unsigned*)((const char*)(gbase) + (voff)[_i]), (LAS unsigned*)(lds + (bufoff) + ldsw + _i * 8192), 16, 0, 0); } while (0)
; #define PG8_LDA(dst, b, h) do { _Pragma("unroll") for (int m = 0; m < 4; ++m) _Pragma("unroll") for (int k = 0; k < 2; ++k) dst[m][k] = *(const LAS bf16x8*)(lds + PG8_SA(b, h) + aoff + m * 2048 + k * 1024); } while (0)
; #define PG8_LDB(dst, b, h) do { _Pragma("unroll") for (int n = 0; n < 2; ++n) _Pragma("unroll") for (int k = 0; k < 2; ++k) dst[n][k] = *(const LAS bf16x8*)(lds + PG8_SB(b, h) + boff + n * 2048 + k * 1024); } while (0)
; #define PG8_MMA(ai, bj, At, Bt) do { __builtin_amdgcn_s_setprio(1); _Pragma("unroll") for (int m = 0; m < 4; ++m) _Pragma("unroll") for (int n = 0; n < 2; ++n) _Pragma("unroll") for (int k = 0; k < 2; ++k) \
;         acc[ai][bj][m][n] = __builtin_amdgcn_mfma_f32_16x16x32_bf16(Bt[n][k], At[m][k], acc[ai][bj][m][n], 0, 0, 0); __builtin_amdgcn_s_setprio(0); } while (0)
; #define PG8_WAIT_V(n) asm volatile("s_waitcnt vmcnt(" #n ")" ::: "memory")
; #define PG8_WAIT_L(n) asm volatile("s_waitcnt lgkmcnt(" #n ")" ::: "memory")
; #define PG8_BAR __builtin_amdgcn_s_barrier()
; #define PG8_SCHED __builtin_amdgcn_sched_barrier(0)
; template <class Epi>
; __device__ __forceinline__ void gemm_phase(LAS unsigned char* lds, const Gemm g, const StaticOrder& S, const Epi& E) {
;     ...
;             PG8_LDB(B0, 0, 0); PG8_LDB(B1, 0, 1); PG8_SCHED; PG8_LDA(At, 0, 0); PG8_STAGE(PG8_SA(1, 1), a1 + hstepA, voffA);
;             PG8_WAIT_V(8); PG8_WAIT_L(0); PG8_BAR; PG8_MMA(0, 0, At, B0); PG8_MMA(0, 1, At, B1); PG8_BAR; PG8_SCHED;
;             PG8_LDA(At, 0, 1); PG8_STAGE(PG8_SB(0, 0), b2, voffB); PG8_STAGE(PG8_SB(0, 1), b2 + hstepB, voffB); PG8_STAGE(PG8_SA(0, 0), a2, voffA);
;             PG8_WAIT_V(8); PG8_WAIT_L(0); PG8_BAR; PG8_MMA(1, 0, At, B0); PG8_MMA(1, 1, At, B1); PG8_BAR; PG8_SCHED;
.LBB0_245:
	ds_read_b128 v[152:155], v148
	ds_read_b128 v[156:159], v148 offset:1024
	ds_read_b128 v[160:163], v148 offset:2048
	ds_read_b128 v[164:167], v148 offset:3072
	ds_read_b128 v[168:171], v149
	ds_read_b128 v[172:175], v149 offset:1024
	ds_read_b128 v[176:179], v149 offset:2048
	ds_read_b128 v[180:183], v149 offset:3072
	s_add_i32 s64, s26, 2
	s_add_u32 s27, s24, 0xfff80080
	s_addc_u32 s30, s25, -1
	s_cmp_eq_u32 s54, s26
	s_cselect_b32 s26, s61, s62
	s_cselect_b32 s31, s15, s30
	s_cselect_b32 s30, s17, s27
	s_cselect_b32 s27, s60, s63
	v_lshl_add_u64 v[220:221], s[24:25], 0, v[138:139]
	s_add_i32 m0, s44, 0xc000
	ds_read_b128 v[184:187], v150
	ds_read_b128 v[188:191], v150 offset:1024
	ds_read_b128 v[192:195], v150 offset:2048
	ds_read_b128 v[196:199], v150 offset:3072
	ds_read_b128 v[200:203], v150 offset:4096
	ds_read_b128 v[208:211], v150 offset:5120
	ds_read_b128 v[212:215], v150 offset:6144
	ds_read_b128 v[216:219], v150 offset:7168
	global_load_lds_dwordx4 v[220:221], off
	v_lshl_add_u64 v[220:221], s[24:25], 0, v[140:141]
	s_add_i32 m0, s44, 0xe000
	s_nop 0
	global_load_lds_dwordx4 v[220:221], off
	s_waitcnt vmcnt(8)
	s_waitcnt lgkmcnt(0)
	s_barrier
	s_setprio 1
	s_waitcnt lgkmcnt(0)
	v_mfma_f32_16x16x32_bf16 v[120:123], v[152:155], v[184:187], v[120:123]
	v_mfma_f32_16x16x32_bf16 v[120:123], v[156:159], v[188:191], v[120:123]
	v_mfma_f32_16x16x32_bf16 v[116:119], v[160:163], v[184:187], v[116:119]
	v_mfma_f32_16x16x32_bf16 v[116:119], v[164:167], v[188:191], v[116:119]
	v_mfma_f32_16x16x32_bf16 v[124:127], v[168:171], v[184:187], v[124:127]
	v_mfma_f32_16x16x32_bf16 v[124:127], v[172:175], v[188:191], v[124:127]
	v_mfma_f32_16x16x32_bf16 v[112:115], v[176:179], v[184:187], v[112:115]
	v_mfma_f32_16x16x32_bf16 v[112:115], v[180:183], v[188:191], v[112:115]
	v_mfma_f32_16x16x32_bf16 v[96:99], v[176:179], v[192:195], v[96:99]
	v_mfma_f32_16x16x32_bf16 v[96:99], v[180:183], v[196:199], v[96:99]
	v_mfma_f32_16x16x32_bf16 v[104:107], v[168:171], v[192:195], v[104:107]
	v_mfma_f32_16x16x32_bf16 v[104:107], v[172:175], v[196:199], v[104:107]
	v_mfma_f32_16x16x32_bf16 v[100:103], v[160:163], v[192:195], v[100:103]
	v_mfma_f32_16x16x32_bf16 v[100:103], v[164:167], v[196:199], v[100:103]
	v_mfma_f32_16x16x32_bf16 v[108:111], v[152:155], v[192:195], v[108:111]
	v_mfma_f32_16x16x32_bf16 v[108:111], v[156:159], v[196:199], v[108:111]
	s_setprio 0
	s_setprio 1
	v_mfma_f32_16x16x32_bf16 v[92:95], v[152:155], v[200:203], v[92:95]
	v_mfma_f32_16x16x32_bf16 v[92:95], v[156:159], v[208:211], v[92:95]
	v_mfma_f32_16x16x32_bf16 v[84:87], v[160:163], v[200:203], v[84:87]
	v_mfma_f32_16x16x32_bf16 v[84:87], v[164:167], v[208:211], v[84:87]
	v_mfma_f32_16x16x32_bf16 v[88:91], v[168:171], v[200:203], v[88:91]
	v_mfma_f32_16x16x32_bf16 v[88:91], v[172:175], v[208:211], v[88:91]
	v_mfma_f32_16x16x32_bf16 v[80:83], v[176:179], v[200:203], v[80:83]
	v_mfma_f32_16x16x32_bf16 v[80:83], v[180:183], v[208:211], v[80:83]
	v_mfma_f32_16x16x32_bf16 v[64:67], v[176:179], v[212:215], v[64:67]
	v_mfma_f32_16x16x32_bf16 v[64:67], v[180:183], v[216:219], v[64:67]
	v_mfma_f32_16x16x32_bf16 v[72:75], v[168:171], v[212:215], v[72:75]
	v_mfma_f32_16x16x32_bf16 v[72:75], v[172:175], v[216:219], v[72:75]
	v_mfma_f32_16x16x32_bf16 v[68:71], v[160:163], v[212:215], v[68:71]
	v_mfma_f32_16x16x32_bf16 v[68:71], v[164:167], v[216:219], v[68:71]
	v_mfma_f32_16x16x32_bf16 v[76:79], v[152:155], v[212:215], v[76:79]
	v_mfma_f32_16x16x32_bf16 v[76:79], v[156:159], v[216:219], v[76:79]
	s_setprio 0
	s_barrier
	s_add_i32 s65, s57, s33
	v_lshl_add_u64 v[220:221], s[26:27], 0, v[132:133]
	s_mov_b32 m0, s65
	ds_read_b128 v[184:187], v150 offset:16384
	ds_read_b128 v[188:191], v150 offset:17408
	ds_read_b128 v[192:195], v150 offset:18432
	ds_read_b128 v[196:199], v150 offset:19456
	ds_read_b128 v[200:203], v150 offset:20480
	ds_read_b128 v[208:211], v150 offset:21504
	ds_read_b128 v[212:215], v150 offset:22528
	ds_read_b128 v[216:219], v150 offset:23552
	global_load_lds_dwordx4 v[220:221], off
	s_add_i32 m0, s65, 0x2000
	s_add_u32 s66, s26, 0x80000
	v_lshl_add_u64 v[222:223], s[26:27], 0, v[128:129]
	s_addc_u32 s67, s27, 0
	s_add_i32 s65, s58, s33
	global_load_lds_dwordx4 v[222:223], off
	v_lshl_add_u64 v[224:225], s[66:67], 0, v[132:133]
	s_mov_b32 m0, s65
	v_lshl_add_u64 v[226:227], s[30:31], 0, v[130:131]
	global_load_lds_dwordx4 v[224:225], off
	v_lshl_add_u64 v[224:225], s[66:67], 0, v[128:129]
	s_add_i32 m0, s65, 0x2000
	s_nop 0
	global_load_lds_dwordx4 v[224:225], off
	v_lshl_add_u64 v[224:225], s[30:31], 0, v[134:135]
	s_mov_b32 m0, s44
	s_nop 0
	global_load_lds_dwordx4 v[224:225], off
	s_mov_b32 m0, s45
	s_nop 0
	global_load_lds_dwordx4 v[226:227], off
	s_waitcnt vmcnt(8)
	s_waitcnt lgkmcnt(0)
	s_barrier
; #define PG8_STAGE(bufoff, gbase, voff) do { _Pragma("unroll") for (int _i = 0; _i < 2; ++_i) \
;         __builtin_amdgcn_global_load_lds((const unsigned*)((const char*)(gbase) + (voff)[_i]), (LAS unsigned*)(lds + (bufoff) + ldsw + _i * 8192), 16, 0, 0); } while (0)
; #define PG8_LDA(dst, b, h) do { _Pragma("unroll") for (int m = 0; m < 4; ++m) _Pragma("unroll") for (int k = 0; k < 2; ++k) dst[m][k] = *(const LAS bf16x8*)(lds + PG8_SA(b, h) + aoff + m * 2048 + k * 1024); } while (0)
; #define PG8_LDB(dst, b, h) do { _Pragma("unroll") for (int n = 0; n < 2; ++n) _Pragma("unroll") for (int k = 0; k < 2; ++k) dst[n][k] = *(const LAS bf16x8*)(lds + PG8_SB(b, h) + boff + n * 2048 + k * 1024); } while (0)
; #define PG8_MMA(ai, bj, At, Bt) do { __builtin_amdgcn_s_setprio(1); _Pragma("unroll") for (int m = 0; m < 4; ++m) _Pragma("unroll") for (int n = 0; n < 2; ++n) _Pragma("unroll") for (int k = 0; k < 2; ++k) \
;         acc[ai][bj][m][n] = __builtin_amdgcn_mfma_f32_16x16x32_bf16(Bt[n][k], At[m][k], acc[ai][bj][m][n], 0, 0, 0); __builtin_amdgcn_s_setprio(0); } while (0)
; #define PG8_WAIT_V(n) asm volatile("s_waitcnt vmcnt(" #n ")" ::: "memory")
; #define PG8_WAIT_L(n) asm volatile("s_waitcnt lgkmcnt(" #n ")" ::: "memory")
; #define PG8_BAR __builtin_amdgcn_s_barrier()
; #define PG8_SCHED __builtin_amdgcn_sched_barrier(0)
; template <class Epi>
; __device__ __forceinline__ void gemm_phase(LAS unsigned char* lds, const Gemm g, const StaticOrder& S, const Epi& E) {
;     ...
;             PG8_WAIT_V(8); PG8_WAIT_L(0); PG8_BAR; PG8_MMA(1, 0, At, B0); PG8_MMA(1, 1, At, B1); PG8_BAR; PG8_SCHED;
;             PG8_LDB(B0, 1, 0); PG8_LDB(B1, 1, 1); PG8_SCHED; PG8_LDA(At, 1, 0); PG8_STAGE(PG8_SA(0, 1), a2 + hstepA, voffA);
;             PG8_WAIT_V(8); PG8_WAIT_L(0); PG8_BAR; PG8_MMA(0, 0, At, B0); PG8_MMA(0, 1, At, B1); PG8_BAR; PG8_SCHED;
	s_setprio 1
	s_waitcnt lgkmcnt(0)
	v_mfma_f32_16x16x32_bf16 v[60:63], v[152:155], v[184:187], v[60:63]
	v_mfma_f32_16x16x32_bf16 v[60:63], v[156:159], v[188:191], v[60:63]
	v_mfma_f32_16x16x32_bf16 v[52:55], v[160:163], v[184:187], v[52:55]
	v_mfma_f32_16x16x32_bf16 v[52:55], v[164:167], v[188:191], v[52:55]
	v_mfma_f32_16x16x32_bf16 v[56:59], v[168:171], v[184:187], v[56:59]
	v_mfma_f32_16x16x32_bf16 v[56:59], v[172:175], v[188:191], v[56:59]
	v_mfma_f32_16x16x32_bf16 v[48:51], v[176:179], v[184:187], v[48:51]
	v_mfma_f32_16x16x32_bf16 v[48:51], v[180:183], v[188:191], v[48:51]
	v_mfma_f32_16x16x32_bf16 v[32:35], v[176:179], v[192:195], v[32:35]
	v_mfma_f32_16x16x32_bf16 v[32:35], v[180:183], v[196:199], v[32:35]
	v_mfma_f32_16x16x32_bf16 v[40:43], v[168:171], v[192:195], v[40:43]
	v_mfma_f32_16x16x32_bf16 v[40:43], v[172:175], v[196:199], v[40:43]
	v_mfma_f32_16x16x32_bf16 v[36:39], v[160:163], v[192:195], v[36:39]
	v_mfma_f32_16x16x32_bf16 v[36:39], v[164:167], v[196:199], v[36:39]
	v_mfma_f32_16x16x32_bf16 v[44:47], v[152:155], v[192:195], v[44:47]
	v_mfma_f32_16x16x32_bf16 v[44:47], v[156:159], v[196:199], v[44:47]
	s_setprio 0
	s_setprio 1
	v_mfma_f32_16x16x32_bf16 v[28:31], v[152:155], v[200:203], v[28:31]
	v_mfma_f32_16x16x32_bf16 v[28:31], v[156:159], v[208:211], v[28:31]
	v_mfma_f32_16x16x32_bf16 v[20:23], v[160:163], v[200:203], v[20:23]
	v_mfma_f32_16x16x32_bf16 v[20:23], v[164:167], v[208:211], v[20:23]
	v_mfma_f32_16x16x32_bf16 v[24:27], v[168:171], v[200:203], v[24:27]
	v_mfma_f32_16x16x32_bf16 v[24:27], v[172:175], v[208:211], v[24:27]
	v_mfma_f32_16x16x32_bf16 v[16:19], v[176:179], v[200:203], v[16:19]
	v_mfma_f32_16x16x32_bf16 v[16:19], v[180:183], v[208:211], v[16:19]
	v_mfma_f32_16x16x32_bf16 v[0:3], v[176:179], v[212:215], v[0:3]
	v_mfma_f32_16x16x32_bf16 v[0:3], v[180:183], v[216:219], v[0:3]
	v_mfma_f32_16x16x32_bf16 v[8:11], v[168:171], v[212:215], v[8:11]
	v_mfma_f32_16x16x32_bf16 v[8:11], v[172:175], v[216:219], v[8:11]
	v_mfma_f32_16x16x32_bf16 v[4:7], v[160:163], v[212:215], v[4:7]
	v_mfma_f32_16x16x32_bf16 v[4:7], v[164:167], v[216:219], v[4:7]
	v_mfma_f32_16x16x32_bf16 v[12:15], v[152:155], v[212:215], v[12:15]
	v_mfma_f32_16x16x32_bf16 v[12:15], v[156:159], v[216:219], v[12:15]
	s_setprio 0
	s_barrier
	s_add_i32 s65, 0, 0x18000
	v_add_u32_e32 v151, s65, v146
	s_add_i32 s66, 0, 0x1c000
	ds_read_b128 v[152:155], v151
	ds_read_b128 v[156:159], v151 offset:1024
	ds_read_b128 v[160:163], v151 offset:2048
	ds_read_b128 v[164:167], v151 offset:3072
	v_add_u32_e32 v151, s66, v146
	ds_read_b128 v[168:171], v151
	ds_read_b128 v[172:175], v151 offset:1024
	ds_read_b128 v[176:179], v151 offset:2048
	ds_read_b128 v[180:183], v151 offset:3072
	s_add_u32 s30, s30, 0x80000
	s_addc_u32 s31, s31, 0
	s_mov_b32 m0, s46
	v_lshl_add_u64 v[230:231], s[30:31], 0, v[134:135]
	ds_read_b128 v[184:187], v150 offset:32768
	ds_read_b128 v[188:191], v150 offset:33792
	ds_read_b128 v[192:195], v150 offset:34816
	ds_read_b128 v[196:199], v150 offset:35840
	ds_read_b128 v[200:203], v150 offset:36864
	ds_read_b128 v[208:211], v150 offset:37888
	ds_read_b128 v[212:215], v150 offset:38912
	ds_read_b128 v[216:219], v150 offset:39936
	global_load_lds_dwordx4 v[230:231], off
	v_lshl_add_u64 v[230:231], s[30:31], 0, v[130:131]
	s_mov_b32 m0, s47
	s_nop 0
	global_load_lds_dwordx4 v[230:231], off
	s_waitcnt vmcnt(8)
	s_waitcnt lgkmcnt(0)
	s_barrier
	s_setprio 1
	s_waitcnt lgkmcnt(0)
	v_mfma_f32_16x16x32_bf16 v[120:123], v[152:155], v[184:187], v[120:123]
	v_mfma_f32_16x16x32_bf16 v[120:123], v[156:159], v[188:191], v[120:123]
	v_mfma_f32_16x16x32_bf16 v[116:119], v[160:163], v[184:187], v[116:119]
	v_mfma_f32_16x16x32_bf16 v[116:119], v[164:167], v[188:191], v[116:119]
	v_mfma_f32_16x16x32_bf16 v[124:127], v[168:171], v[184:187], v[124:127]
	v_mfma_f32_16x16x32_bf16 v[124:127], v[172:175], v[188:191], v[124:127]
	v_mfma_f32_16x16x32_bf16 v[112:115], v[176:179], v[184:187], v[112:115]
	v_mfma_f32_16x16x32_bf16 v[112:115], v[180:183], v[188:191], v[112:115]
	v_mfma_f32_16x16x32_bf16 v[96:99], v[176:179], v[192:195], v[96:99]
	v_mfma_f32_16x16x32_bf16 v[96:99], v[180:183], v[196:199], v[96:99]
	v_mfma_f32_16x16x32_bf16 v[104:107], v[168:171], v[192:195], v[104:107]
	v_mfma_f32_16x16x32_bf16 v[104:107], v[172:175], v[196:199], v[104:107]
	v_mfma_f32_16x16x32_bf16 v[100:103], v[160:163], v[192:195], v[100:103]
	v_mfma_f32_16x16x32_bf16 v[100:103], v[164:167], v[196:199], v[100:103]
	v_mfma_f32_16x16x32_bf16 v[108:111], v[152:155], v[192:195], v[108:111]
	v_mfma_f32_16x16x32_bf16 v[108:111], v[156:159], v[196:199], v[108:111]
	s_setprio 0
	s_setprio 1
	v_mfma_f32_16x16x32_bf16 v[92:95], v[152:155], v[200:203], v[92:95]
	v_mfma_f32_16x16x32_bf16 v[92:95], v[156:159], v[208:211], v[92:95]
	v_mfma_f32_16x16x32_bf16 v[84:87], v[160:163], v[200:203], v[84:87]
	v_mfma_f32_16x16x32_bf16 v[84:87], v[164:167], v[208:211], v[84:87]
	v_mfma_f32_16x16x32_bf16 v[88:91], v[168:171], v[200:203], v[88:91]
	v_mfma_f32_16x16x32_bf16 v[88:91], v[172:175], v[208:211], v[88:91]
	v_mfma_f32_16x16x32_bf16 v[80:83], v[176:179], v[200:203], v[80:83]
	v_mfma_f32_16x16x32_bf16 v[80:83], v[180:183], v[208:211], v[80:83]
	v_mfma_f32_16x16x32_bf16 v[64:67], v[176:179], v[212:215], v[64:67]
	v_mfma_f32_16x16x32_bf16 v[64:67], v[180:183], v[216:219], v[64:67]
	v_mfma_f32_16x16x32_bf16 v[72:75], v[168:171], v[212:215], v[72:75]
	v_mfma_f32_16x16x32_bf16 v[72:75], v[172:175], v[216:219], v[72:75]
	v_mfma_f32_16x16x32_bf16 v[68:71], v[160:163], v[212:215], v[68:71]
	v_mfma_f32_16x16x32_bf16 v[68:71], v[164:167], v[216:219], v[68:71]
	v_mfma_f32_16x16x32_bf16 v[76:79], v[152:155], v[212:215], v[76:79]
	v_mfma_f32_16x16x32_bf16 v[76:79], v[156:159], v[216:219], v[76:79]
	s_setprio 0
	s_barrier
; #define PG8_STAGE(bufoff, gbase, voff) do { _Pragma("unroll") for (int _i = 0; _i < 2; ++_i) \
;         __builtin_amdgcn_global_load_lds((const unsigned*)((const char*)(gbase) + (voff)[_i]), (LAS unsigned*)(lds + (bufoff) + ldsw + _i * 8192), 16, 0, 0); } while (0)
; #define PG8_LDA(dst, b, h) do { _Pragma("unroll") for (int m = 0; m < 4; ++m) _Pragma("unroll") for (int k = 0; k < 2; ++k) dst[m][k] = *(const LAS bf16x8*)(lds + PG8_SA(b, h) + aoff + m * 2048 + k * 1024); } while (0)
; #define PG8_MMA(ai, bj, At, Bt) do { __builtin_amdgcn_s_setprio(1); _Pragma("unroll") for (int m = 0; m < 4; ++m) _Pragma("unroll") for (int n = 0; n < 2; ++n) _Pragma("unroll") for (int k = 0; k < 2; ++k) \
;         acc[ai][bj][m][n] = __builtin_amdgcn_mfma_f32_16x16x32_bf16(Bt[n][k], At[m][k], acc[ai][bj][m][n], 0, 0, 0); __builtin_amdgcn_s_setprio(0); } while (0)
; #define PG8_WAIT_V(n) asm volatile("s_waitcnt vmcnt(" #n ")" ::: "memory")
; #define PG8_WAIT_L(n) asm volatile("s_waitcnt lgkmcnt(" #n ")" ::: "memory")
; #define PG8_BAR __builtin_amdgcn_s_barrier()
; #define PG8_SCHED __builtin_amdgcn_sched_barrier(0)
; template <class Epi>
; __device__ __forceinline__ void gemm_phase(LAS unsigned char* lds, const Gemm g, const StaticOrder& S, const Epi& E) {
;     ...
;             PG8_LDA(At, 1, 1); PG8_STAGE(PG8_SB(1, 0), b3, voffB); PG8_STAGE(PG8_SB(1, 1), b3 + hstepB, voffB); PG8_STAGE(PG8_SA(1, 0), a3, voffA);
;             PG8_WAIT_V(8); PG8_WAIT_L(0); PG8_BAR; PG8_MMA(1, 0, At, B0); PG8_MMA(1, 1, At, B1); PG8_BAR; PG8_SCHED;
;         }
	s_add_i32 s30, s65, s33
	v_lshl_add_u64 v[220:221], v[220:221], 0, s[8:9]
	s_mov_b32 m0, s30
	ds_read_b128 v[184:187], v150 offset:49152
	ds_read_b128 v[188:191], v150 offset:50176
	ds_read_b128 v[192:195], v150 offset:51200
	ds_read_b128 v[196:199], v150 offset:52224
	ds_read_b128 v[200:203], v150 offset:53248
	ds_read_b128 v[208:211], v150 offset:54272
	ds_read_b128 v[212:215], v150 offset:55296
	ds_read_b128 v[216:219], v150 offset:56320
	global_load_lds_dwordx4 v[220:221], off
	s_add_i32 m0, s30, 0x2000
	s_add_u32 s26, s26, 0x80080
	v_lshl_add_u64 v[220:221], v[222:223], 0, s[8:9]
	s_addc_u32 s27, s27, 0
	s_add_i32 s30, s66, s33
	global_load_lds_dwordx4 v[220:221], off
	v_lshl_add_u64 v[220:221], s[26:27], 0, v[132:133]
	s_mov_b32 m0, s30
	s_nop 0
	global_load_lds_dwordx4 v[220:221], off
	v_lshl_add_u64 v[220:221], s[26:27], 0, v[128:129]
	s_add_i32 m0, s30, 0x2000
	s_nop 0
	global_load_lds_dwordx4 v[220:221], off
	v_lshl_add_u64 v[220:221], v[224:225], 0, s[8:9]
	s_mov_b32 m0, s52
	s_nop 0
	global_load_lds_dwordx4 v[220:221], off
	v_lshl_add_u64 v[220:221], v[226:227], 0, s[8:9]
	s_mov_b32 m0, s53
	s_nop 0
	global_load_lds_dwordx4 v[220:221], off
	s_waitcnt vmcnt(8)
	s_waitcnt lgkmcnt(0)
	s_barrier
	s_setprio 1
	s_waitcnt lgkmcnt(0)
	v_mfma_f32_16x16x32_bf16 v[60:63], v[152:155], v[184:187], v[60:63]
	v_mfma_f32_16x16x32_bf16 v[60:63], v[156:159], v[188:191], v[60:63]
	v_mfma_f32_16x16x32_bf16 v[52:55], v[160:163], v[184:187], v[52:55]
	v_mfma_f32_16x16x32_bf16 v[52:55], v[164:167], v[188:191], v[52:55]
	v_mfma_f32_16x16x32_bf16 v[56:59], v[168:171], v[184:187], v[56:59]
	v_mfma_f32_16x16x32_bf16 v[56:59], v[172:175], v[188:191], v[56:59]
	v_mfma_f32_16x16x32_bf16 v[48:51], v[176:179], v[184:187], v[48:51]
	v_mfma_f32_16x16x32_bf16 v[48:51], v[180:183], v[188:191], v[48:51]
	v_mfma_f32_16x16x32_bf16 v[32:35], v[176:179], v[192:195], v[32:35]
	v_mfma_f32_16x16x32_bf16 v[32:35], v[180:183], v[196:199], v[32:35]
	v_mfma_f32_16x16x32_bf16 v[40:43], v[168:171], v[192:195], v[40:43]
	v_mfma_f32_16x16x32_bf16 v[40:43], v[172:175], v[196:199], v[40:43]
	v_mfma_f32_16x16x32_bf16 v[36:39], v[160:163], v[192:195], v[36:39]
	v_mfma_f32_16x16x32_bf16 v[36:39], v[164:167], v[196:199], v[36:39]
	v_mfma_f32_16x16x32_bf16 v[44:47], v[152:155], v[192:195], v[44:47]
	v_mfma_f32_16x16x32_bf16 v[44:47], v[156:159], v[196:199], v[44:47]
	s_setprio 0
	s_setprio 1
	v_mfma_f32_16x16x32_bf16 v[28:31], v[152:155], v[200:203], v[28:31]
	v_mfma_f32_16x16x32_bf16 v[28:31], v[156:159], v[208:211], v[28:31]
	v_mfma_f32_16x16x32_bf16 v[20:23], v[160:163], v[200:203], v[20:23]
	v_mfma_f32_16x16x32_bf16 v[20:23], v[164:167], v[208:211], v[20:23]
	v_mfma_f32_16x16x32_bf16 v[24:27], v[168:171], v[200:203], v[24:27]
	v_mfma_f32_16x16x32_bf16 v[24:27], v[172:175], v[208:211], v[24:27]
	v_mfma_f32_16x16x32_bf16 v[16:19], v[176:179], v[200:203], v[16:19]
	v_mfma_f32_16x16x32_bf16 v[16:19], v[180:183], v[208:211], v[16:19]
	v_mfma_f32_16x16x32_bf16 v[0:3], v[176:179], v[212:215], v[0:3]
	v_mfma_f32_16x16x32_bf16 v[0:3], v[180:183], v[216:219], v[0:3]
	v_mfma_f32_16x16x32_bf16 v[8:11], v[168:171], v[212:215], v[8:11]
	v_mfma_f32_16x16x32_bf16 v[8:11], v[172:175], v[216:219], v[8:11]
	v_mfma_f32_16x16x32_bf16 v[4:7], v[160:163], v[212:215], v[4:7]
	v_mfma_f32_16x16x32_bf16 v[4:7], v[164:167], v[216:219], v[4:7]
	v_mfma_f32_16x16x32_bf16 v[12:15], v[152:155], v[212:215], v[12:15]
	v_mfma_f32_16x16x32_bf16 v[12:15], v[156:159], v[216:219], v[12:15]
	s_setprio 0
	s_barrier
	s_add_u32 s24, s24, 0x100
	s_addc_u32 s25, s25, 0
	s_add_u32 s62, s62, 0x100
	s_addc_u32 s63, s63, 0
	s_cmp_ge_i32 s64, s49
	s_mov_b32 s26, s64
	s_cbranch_scc0 .LBB0_245

; #define PG8_STAGE(bufoff, gbase, voff) do { _Pragma("unroll") for (int _i = 0; _i < 2; ++_i) \
;         __builtin_amdgcn_global_load_lds((const unsigned*)((const char*)(gbase) + (voff)[_i]), (LAS unsigned*)(lds + (bufoff) + ldsw + _i * 8192), 16, 0, 0); } while (0)
; #define PG8_LDA(dst, b, h) do { _Pragma("unroll") for (int m = 0; m < 4; ++m) _Pragma("unroll") for (int k = 0; k < 2; ++k) dst[m][k] = *(const LAS bf16x8*)(lds + PG8_SA(b, h) + aoff + m * 2048 + k * 1024); } while (0)
; #define PG8_LDB(dst, b, h) do { _Pragma("unroll") for (int n = 0; n < 2; ++n) _Pragma("unroll") for (int k = 0; k < 2; ++k) dst[n][k] = *(const LAS bf16x8*)(lds + PG8_SB(b, h) + boff + n * 2048 + k * 1024); } while (0)
; #define PG8_MMA(ai, bj, At, Bt) do { __builtin_amdgcn_s_setprio(1); _Pragma("unroll") for (int m = 0; m < 4; ++m) _Pragma("unroll") for (int n = 0; n < 2; ++n) _Pragma("unroll") for (int k = 0; k < 2; ++k) \
;         acc[ai][bj][m][n] = __builtin_amdgcn_mfma_f32_16x16x32_bf16(Bt[n][k], At[m][k], acc[ai][bj][m][n], 0, 0, 0); __builtin_amdgcn_s_setprio(0); } while (0)
; #define PG8_WAIT_V(n) asm volatile("s_waitcnt vmcnt(" #n ")" ::: "memory")
; #define PG8_WAIT_L(n) asm volatile("s_waitcnt lgkmcnt(" #n ")" ::: "memory")
; #define PG8_BAR __builtin_amdgcn_s_barrier()
; #define PG8_SCHED __builtin_amdgcn_sched_barrier(0)
; template <class Epi>
; __device__ __forceinline__ void gemm_phase(LAS unsigned char* lds, const Gemm g, const StaticOrder& S, const Epi& E) {
;     ...
;             PG8_LDB(B0, 0, 0); PG8_LDB(B1, 0, 1); PG8_SCHED; PG8_LDA(At, 0, 0); PG8_STAGE(PG8_SA(1, 1), a1 + hstepA, voffA);
;             PG8_WAIT_V(8); PG8_WAIT_L(0); PG8_BAR; PG8_MMA(0, 0, At, B0); PG8_MMA(0, 1, At, B1); PG8_BAR; PG8_SCHED;
;             PG8_LDA(At, 0, 1); PG8_STAGE(PG8_SB(0, 0), b2, voffB); PG8_STAGE(PG8_SB(0, 1), b2 + hstepB, voffB); PG8_STAGE(PG8_SA(0, 0), a2, voffA);
;             PG8_WAIT_V(8); PG8_WAIT_L(0); PG8_BAR; PG8_MMA(1, 0, At, B0); PG8_MMA(1, 1, At, B1); PG8_BAR; PG8_SCHED;
.LBB0_445:
	ds_read_b128 v[148:151], v218
	ds_read_b128 v[152:155], v218 offset:1024
	ds_read_b128 v[156:159], v218 offset:2048
	ds_read_b128 v[160:163], v218 offset:3072
	ds_read_b128 v[164:167], v219
	ds_read_b128 v[168:171], v219 offset:1024
	ds_read_b128 v[172:175], v219 offset:2048
	ds_read_b128 v[176:179], v219 offset:3072
	s_add_i32 s65, s34, 2
	s_add_u32 s30, s4, 0x100
	s_addc_u32 s31, s5, 0
	s_cmp_eq_u32 s49, s34
	s_cselect_b32 s34, s26, s1
	s_cselect_b32 s37, s11, s31
	s_cselect_b32 s36, s10, s30
	s_cselect_b32 s35, s27, s64
	v_lshl_add_u64 v[216:217], s[4:5], 0, v[140:141]
	s_add_i32 m0, s41, 0xc000
	ds_read_b128 v[180:183], v220
	ds_read_b128 v[184:187], v220 offset:1024
	ds_read_b128 v[188:191], v220 offset:2048
	ds_read_b128 v[192:195], v220 offset:3072
	ds_read_b128 v[196:199], v220 offset:4096
	ds_read_b128 v[200:203], v220 offset:5120
	ds_read_b128 v[208:211], v220 offset:6144
	ds_read_b128 v[212:215], v220 offset:7168
	global_load_lds_dwordx4 v[216:217], off
	v_lshl_add_u64 v[216:217], s[4:5], 0, v[142:143]
	s_add_i32 m0, s41, 0xe000
	s_nop 0
	global_load_lds_dwordx4 v[216:217], off
	s_waitcnt vmcnt(8)
	s_waitcnt lgkmcnt(0)
	s_barrier
	s_setprio 1
	s_waitcnt lgkmcnt(0)
	v_mfma_f32_16x16x32_bf16 v[124:127], v[148:151], v[180:183], v[124:127]
	v_mfma_f32_16x16x32_bf16 v[124:127], v[152:155], v[184:187], v[124:127]
	v_mfma_f32_16x16x32_bf16 v[120:123], v[156:159], v[180:183], v[120:123]
	v_mfma_f32_16x16x32_bf16 v[120:123], v[160:163], v[184:187], v[120:123]
	v_mfma_f32_16x16x32_bf16 v[108:111], v[164:167], v[180:183], v[108:111]
	v_mfma_f32_16x16x32_bf16 v[108:111], v[168:171], v[184:187], v[108:111]
	v_mfma_f32_16x16x32_bf16 v[100:103], v[172:175], v[180:183], v[100:103]
	v_mfma_f32_16x16x32_bf16 v[100:103], v[176:179], v[184:187], v[100:103]
	v_mfma_f32_16x16x32_bf16 v[84:87], v[172:175], v[188:191], v[84:87]
	v_mfma_f32_16x16x32_bf16 v[84:87], v[176:179], v[192:195], v[84:87]
	v_mfma_f32_16x16x32_bf16 v[92:95], v[164:167], v[188:191], v[92:95]
	v_mfma_f32_16x16x32_bf16 v[92:95], v[168:171], v[192:195], v[92:95]
	v_mfma_f32_16x16x32_bf16 v[112:115], v[156:159], v[188:191], v[112:115]
	v_mfma_f32_16x16x32_bf16 v[112:115], v[160:163], v[192:195], v[112:115]
	v_mfma_f32_16x16x32_bf16 v[116:119], v[148:151], v[188:191], v[116:119]
	v_mfma_f32_16x16x32_bf16 v[116:119], v[152:155], v[192:195], v[116:119]
	s_setprio 0
	s_setprio 1
	v_mfma_f32_16x16x32_bf16 v[104:107], v[148:151], v[196:199], v[104:107]
	v_mfma_f32_16x16x32_bf16 v[104:107], v[152:155], v[200:203], v[104:107]
	v_mfma_f32_16x16x32_bf16 v[96:99], v[156:159], v[196:199], v[96:99]
	v_mfma_f32_16x16x32_bf16 v[96:99], v[160:163], v[200:203], v[96:99]
	v_mfma_f32_16x16x32_bf16 v[76:79], v[164:167], v[196:199], v[76:79]
	v_mfma_f32_16x16x32_bf16 v[76:79], v[168:171], v[200:203], v[76:79]
	v_mfma_f32_16x16x32_bf16 v[72:75], v[172:175], v[196:199], v[72:75]
	v_mfma_f32_16x16x32_bf16 v[72:75], v[176:179], v[200:203], v[72:75]
	v_mfma_f32_16x16x32_bf16 v[64:67], v[172:175], v[208:211], v[64:67]
	v_mfma_f32_16x16x32_bf16 v[64:67], v[176:179], v[212:215], v[64:67]
	v_mfma_f32_16x16x32_bf16 v[68:71], v[164:167], v[208:211], v[68:71]
	v_mfma_f32_16x16x32_bf16 v[68:71], v[168:171], v[212:215], v[68:71]
	v_mfma_f32_16x16x32_bf16 v[80:83], v[156:159], v[208:211], v[80:83]
	v_mfma_f32_16x16x32_bf16 v[80:83], v[160:163], v[212:215], v[80:83]
	v_mfma_f32_16x16x32_bf16 v[88:91], v[148:151], v[208:211], v[88:91]
	v_mfma_f32_16x16x32_bf16 v[88:91], v[152:155], v[212:215], v[88:91]
	s_setprio 0
	s_barrier
	s_add_i32 s4, s54, s40
	v_lshl_add_u64 v[216:217], s[34:35], 0, v[130:131]
	s_mov_b32 m0, s4
	ds_read_b128 v[180:183], v220 offset:16384
	ds_read_b128 v[184:187], v220 offset:17408
	ds_read_b128 v[188:191], v220 offset:18432
	ds_read_b128 v[192:195], v220 offset:19456
	ds_read_b128 v[196:199], v220 offset:20480
	ds_read_b128 v[200:203], v220 offset:21504
	ds_read_b128 v[208:211], v220 offset:22528
	ds_read_b128 v[212:215], v220 offset:23552
	global_load_lds_dwordx4 v[216:217], off
	s_add_i32 m0, s4, 0x2000
	s_add_u32 s4, s34, 0x158000
	v_lshl_add_u64 v[222:223], s[34:35], 0, v[134:135]
	s_addc_u32 s5, s35, 0
	s_add_i32 s66, s55, s40
	global_load_lds_dwordx4 v[222:223], off
	v_lshl_add_u64 v[224:225], s[4:5], 0, v[130:131]
	s_mov_b32 m0, s66
	v_lshl_add_u64 v[226:227], s[36:37], 0, v[132:133]
	global_load_lds_dwordx4 v[224:225], off
	v_lshl_add_u64 v[224:225], s[4:5], 0, v[134:135]
	s_add_i32 m0, s66, 0x2000
	s_nop 0
	global_load_lds_dwordx4 v[224:225], off
	v_lshl_add_u64 v[224:225], s[36:37], 0, v[128:129]
	s_mov_b32 m0, s41
	s_nop 0
	global_load_lds_dwordx4 v[224:225], off
	s_mov_b32 m0, s42
	s_nop 0
	global_load_lds_dwordx4 v[226:227], off
	s_waitcnt vmcnt(8)
	s_waitcnt lgkmcnt(0)
	s_barrier
; #define PG8_STAGE(bufoff, gbase, voff) do { _Pragma("unroll") for (int _i = 0; _i < 2; ++_i) \
;         __builtin_amdgcn_global_load_lds((const unsigned*)((const char*)(gbase) + (voff)[_i]), (LAS unsigned*)(lds + (bufoff) + ldsw + _i * 8192), 16, 0, 0); } while (0)
; #define PG8_LDA(dst, b, h) do { _Pragma("unroll") for (int m = 0; m < 4; ++m) _Pragma("unroll") for (int k = 0; k < 2; ++k) dst[m][k] = *(const LAS bf16x8*)(lds + PG8_SA(b, h) + aoff + m * 2048 + k * 1024); } while (0)
; #define PG8_LDB(dst, b, h) do { _Pragma("unroll") for (int n = 0; n < 2; ++n) _Pragma("unroll") for (int k = 0; k < 2; ++k) dst[n][k] = *(const LAS bf16x8*)(lds + PG8_SB(b, h) + boff + n * 2048 + k * 1024); } while (0)
; #define PG8_MMA(ai, bj, At, Bt) do { __builtin_amdgcn_s_setprio(1); _Pragma("unroll") for (int m = 0; m < 4; ++m) _Pragma("unroll") for (int n = 0; n < 2; ++n) _Pragma("unroll") for (int k = 0; k < 2; ++k) \
;         acc[ai][bj][m][n] = __builtin_amdgcn_mfma_f32_16x16x32_bf16(Bt[n][k], At[m][k], acc[ai][bj][m][n], 0, 0, 0); __builtin_amdgcn_s_setprio(0); } while (0)
; #define PG8_WAIT_V(n) asm volatile("s_waitcnt vmcnt(" #n ")" ::: "memory")
; #define PG8_WAIT_L(n) asm volatile("s_waitcnt lgkmcnt(" #n ")" ::: "memory")
; #define PG8_BAR __builtin_amdgcn_s_barrier()
; #define PG8_SCHED __builtin_amdgcn_sched_barrier(0)
; template <class Epi>
; __device__ __forceinline__ void gemm_phase(LAS unsigned char* lds, const Gemm g, const StaticOrder& S, const Epi& E) {
;     ...
;             PG8_WAIT_V(8); PG8_WAIT_L(0); PG8_BAR; PG8_MMA(1, 0, At, B0); PG8_MMA(1, 1, At, B1); PG8_BAR; PG8_SCHED;
;             PG8_LDB(B0, 1, 0); PG8_LDB(B1, 1, 1); PG8_SCHED; PG8_LDA(At, 1, 0); PG8_STAGE(PG8_SA(0, 1), a2 + hstepA, voffA);
;             PG8_WAIT_V(8); PG8_WAIT_L(0); PG8_BAR; PG8_MMA(0, 0, At, B0); PG8_MMA(0, 1, At, B1); PG8_BAR; PG8_SCHED;
	s_setprio 1
	s_waitcnt lgkmcnt(0)
	v_mfma_f32_16x16x32_bf16 v[60:63], v[148:151], v[180:183], v[60:63]
	v_mfma_f32_16x16x32_bf16 v[60:63], v[152:155], v[184:187], v[60:63]
	v_mfma_f32_16x16x32_bf16 v[56:59], v[156:159], v[180:183], v[56:59]
	v_mfma_f32_16x16x32_bf16 v[56:59], v[160:163], v[184:187], v[56:59]
	v_mfma_f32_16x16x32_bf16 v[44:47], v[164:167], v[180:183], v[44:47]
	v_mfma_f32_16x16x32_bf16 v[44:47], v[168:171], v[184:187], v[44:47]
	v_mfma_f32_16x16x32_bf16 v[36:39], v[172:175], v[180:183], v[36:39]
	v_mfma_f32_16x16x32_bf16 v[36:39], v[176:179], v[184:187], v[36:39]
	v_mfma_f32_16x16x32_bf16 v[20:23], v[172:175], v[188:191], v[20:23]
	v_mfma_f32_16x16x32_bf16 v[20:23], v[176:179], v[192:195], v[20:23]
	v_mfma_f32_16x16x32_bf16 v[28:31], v[164:167], v[188:191], v[28:31]
	v_mfma_f32_16x16x32_bf16 v[28:31], v[168:171], v[192:195], v[28:31]
	v_mfma_f32_16x16x32_bf16 v[48:51], v[156:159], v[188:191], v[48:51]
	v_mfma_f32_16x16x32_bf16 v[48:51], v[160:163], v[192:195], v[48:51]
	v_mfma_f32_16x16x32_bf16 v[52:55], v[148:151], v[188:191], v[52:55]
	v_mfma_f32_16x16x32_bf16 v[52:55], v[152:155], v[192:195], v[52:55]
	s_setprio 0
	s_setprio 1
	v_mfma_f32_16x16x32_bf16 v[40:43], v[148:151], v[196:199], v[40:43]
	v_mfma_f32_16x16x32_bf16 v[40:43], v[152:155], v[200:203], v[40:43]
	v_mfma_f32_16x16x32_bf16 v[32:35], v[156:159], v[196:199], v[32:35]
	v_mfma_f32_16x16x32_bf16 v[32:35], v[160:163], v[200:203], v[32:35]
	v_mfma_f32_16x16x32_bf16 v[12:15], v[164:167], v[196:199], v[12:15]
	v_mfma_f32_16x16x32_bf16 v[12:15], v[168:171], v[200:203], v[12:15]
	v_mfma_f32_16x16x32_bf16 v[8:11], v[172:175], v[196:199], v[8:11]
	v_mfma_f32_16x16x32_bf16 v[8:11], v[176:179], v[200:203], v[8:11]
	v_mfma_f32_16x16x32_bf16 v[0:3], v[172:175], v[208:211], v[0:3]
	v_mfma_f32_16x16x32_bf16 v[0:3], v[176:179], v[212:215], v[0:3]
	v_mfma_f32_16x16x32_bf16 v[4:7], v[164:167], v[208:211], v[4:7]
	v_mfma_f32_16x16x32_bf16 v[4:7], v[168:171], v[212:215], v[4:7]
	v_mfma_f32_16x16x32_bf16 v[16:19], v[156:159], v[208:211], v[16:19]
	v_mfma_f32_16x16x32_bf16 v[16:19], v[160:163], v[212:215], v[16:19]
	v_mfma_f32_16x16x32_bf16 v[24:27], v[148:151], v[208:211], v[24:27]
	v_mfma_f32_16x16x32_bf16 v[24:27], v[152:155], v[212:215], v[24:27]
	s_setprio 0
	s_barrier
	s_add_i32 s66, 0, 0x18000
	s_add_i32 s67, 0, 0x1c000
	v_add_u32_e32 v160, s66, v207
	v_add_u32_e32 v176, s67, v207
	ds_read_b128 v[148:151], v160
	ds_read_b128 v[152:155], v160 offset:1024
	ds_read_b128 v[156:159], v160 offset:2048
	ds_read_b128 v[160:163], v160 offset:3072
	ds_read_b128 v[164:167], v176
	ds_read_b128 v[168:171], v176 offset:1024
	ds_read_b128 v[172:175], v176 offset:2048
	ds_read_b128 v[176:179], v176 offset:3072
	s_add_u32 s4, s36, 0x158000
	s_addc_u32 s5, s37, 0
	s_mov_b32 m0, s43
	v_lshl_add_u64 v[230:231], s[4:5], 0, v[128:129]
	ds_read_b128 v[180:183], v220 offset:32768
	ds_read_b128 v[184:187], v220 offset:33792
	ds_read_b128 v[188:191], v220 offset:34816
	ds_read_b128 v[192:195], v220 offset:35840
	ds_read_b128 v[196:199], v220 offset:36864
	ds_read_b128 v[200:203], v220 offset:37888
	ds_read_b128 v[208:211], v220 offset:38912
	ds_read_b128 v[212:215], v220 offset:39936
	global_load_lds_dwordx4 v[230:231], off
	v_lshl_add_u64 v[230:231], s[4:5], 0, v[132:133]
	s_mov_b32 m0, s44
	s_nop 0
	global_load_lds_dwordx4 v[230:231], off
	s_waitcnt vmcnt(8)
	s_waitcnt lgkmcnt(0)
	s_barrier
	s_setprio 1
	s_waitcnt lgkmcnt(0)
	v_mfma_f32_16x16x32_bf16 v[124:127], v[148:151], v[180:183], v[124:127]
	v_mfma_f32_16x16x32_bf16 v[124:127], v[152:155], v[184:187], v[124:127]
	v_mfma_f32_16x16x32_bf16 v[120:123], v[156:159], v[180:183], v[120:123]
	v_mfma_f32_16x16x32_bf16 v[120:123], v[160:163], v[184:187], v[120:123]
	v_mfma_f32_16x16x32_bf16 v[108:111], v[164:167], v[180:183], v[108:111]
	v_mfma_f32_16x16x32_bf16 v[108:111], v[168:171], v[184:187], v[108:111]
	v_mfma_f32_16x16x32_bf16 v[100:103], v[172:175], v[180:183], v[100:103]
	v_mfma_f32_16x16x32_bf16 v[100:103], v[176:179], v[184:187], v[100:103]
	v_mfma_f32_16x16x32_bf16 v[84:87], v[172:175], v[188:191], v[84:87]
	v_mfma_f32_16x16x32_bf16 v[84:87], v[176:179], v[192:195], v[84:87]
	v_mfma_f32_16x16x32_bf16 v[92:95], v[164:167], v[188:191], v[92:95]
	v_mfma_f32_16x16x32_bf16 v[92:95], v[168:171], v[192:195], v[92:95]
	v_mfma_f32_16x16x32_bf16 v[112:115], v[156:159], v[188:191], v[112:115]
	v_mfma_f32_16x16x32_bf16 v[112:115], v[160:163], v[192:195], v[112:115]
	v_mfma_f32_16x16x32_bf16 v[116:119], v[148:151], v[188:191], v[116:119]
	v_mfma_f32_16x16x32_bf16 v[116:119], v[152:155], v[192:195], v[116:119]
	s_setprio 0
	s_setprio 1
	v_mfma_f32_16x16x32_bf16 v[104:107], v[148:151], v[196:199], v[104:107]
	v_mfma_f32_16x16x32_bf16 v[104:107], v[152:155], v[200:203], v[104:107]
	v_mfma_f32_16x16x32_bf16 v[96:99], v[156:159], v[196:199], v[96:99]
	v_mfma_f32_16x16x32_bf16 v[96:99], v[160:163], v[200:203], v[96:99]
	v_mfma_f32_16x16x32_bf16 v[76:79], v[164:167], v[196:199], v[76:79]
	v_mfma_f32_16x16x32_bf16 v[76:79], v[168:171], v[200:203], v[76:79]
	v_mfma_f32_16x16x32_bf16 v[72:75], v[172:175], v[196:199], v[72:75]
	v_mfma_f32_16x16x32_bf16 v[72:75], v[176:179], v[200:203], v[72:75]
	v_mfma_f32_16x16x32_bf16 v[64:67], v[172:175], v[208:211], v[64:67]
	v_mfma_f32_16x16x32_bf16 v[64:67], v[176:179], v[212:215], v[64:67]
	v_mfma_f32_16x16x32_bf16 v[68:71], v[164:167], v[208:211], v[68:71]
	v_mfma_f32_16x16x32_bf16 v[68:71], v[168:171], v[212:215], v[68:71]
	v_mfma_f32_16x16x32_bf16 v[80:83], v[156:159], v[208:211], v[80:83]
	v_mfma_f32_16x16x32_bf16 v[80:83], v[160:163], v[212:215], v[80:83]
	v_mfma_f32_16x16x32_bf16 v[88:91], v[148:151], v[208:211], v[88:91]
	v_mfma_f32_16x16x32_bf16 v[88:91], v[152:155], v[212:215], v[88:91]
	s_setprio 0
	s_barrier
; #define PG8_STAGE(bufoff, gbase, voff) do { _Pragma("unroll") for (int _i = 0; _i < 2; ++_i) \
;         __builtin_amdgcn_global_load_lds((const unsigned*)((const char*)(gbase) + (voff)[_i]), (LAS unsigned*)(lds + (bufoff) + ldsw + _i * 8192), 16, 0, 0); } while (0)
; #define PG8_LDA(dst, b, h) do { _Pragma("unroll") for (int m = 0; m < 4; ++m) _Pragma("unroll") for (int k = 0; k < 2; ++k) dst[m][k] = *(const LAS bf16x8*)(lds + PG8_SA(b, h) + aoff + m * 2048 + k * 1024); } while (0)
; #define PG8_MMA(ai, bj, At, Bt) do { __builtin_amdgcn_s_setprio(1); _Pragma("unroll") for (int m = 0; m < 4; ++m) _Pragma("unroll") for (int n = 0; n < 2; ++n) _Pragma("unroll") for (int k = 0; k < 2; ++k) \
;         acc[ai][bj][m][n] = __builtin_amdgcn_mfma_f32_16x16x32_bf16(Bt[n][k], At[m][k], acc[ai][bj][m][n], 0, 0, 0); __builtin_amdgcn_s_setprio(0); } while (0)
; #define PG8_WAIT_V(n) asm volatile("s_waitcnt vmcnt(" #n ")" ::: "memory")
; #define PG8_WAIT_L(n) asm volatile("s_waitcnt lgkmcnt(" #n ")" ::: "memory")
; #define PG8_BAR __builtin_amdgcn_s_barrier()
; #define PG8_SCHED __builtin_amdgcn_sched_barrier(0)
; template <class Epi>
; __device__ __forceinline__ void gemm_phase(LAS unsigned char* lds, const Gemm g, const StaticOrder& S, const Epi& E) {
;     ...
;             PG8_LDA(At, 1, 1); PG8_STAGE(PG8_SB(1, 0), b3, voffB); PG8_STAGE(PG8_SB(1, 1), b3 + hstepB, voffB); PG8_STAGE(PG8_SA(1, 0), a3, voffA);
;             PG8_WAIT_V(8); PG8_WAIT_L(0); PG8_BAR; PG8_MMA(1, 0, At, B0); PG8_MMA(1, 1, At, B1); PG8_BAR; PG8_SCHED;
;         }
	s_add_i32 s4, s66, s40
	v_lshl_add_u64 v[216:217], v[216:217], 0, s[16:17]
	s_mov_b32 m0, s4
	ds_read_b128 v[180:183], v220 offset:49152
	ds_read_b128 v[184:187], v220 offset:50176
	ds_read_b128 v[188:191], v220 offset:51200
	ds_read_b128 v[192:195], v220 offset:52224
	ds_read_b128 v[196:199], v220 offset:53248
	ds_read_b128 v[200:203], v220 offset:54272
	ds_read_b128 v[208:211], v220 offset:55296
	ds_read_b128 v[212:215], v220 offset:56320
	global_load_lds_dwordx4 v[216:217], off
	s_add_i32 m0, s4, 0x2000
	s_add_u32 s4, s34, 0x158080
	v_lshl_add_u64 v[216:217], v[222:223], 0, s[16:17]
	s_addc_u32 s5, s35, 0
	s_add_i32 s34, s67, s40
	global_load_lds_dwordx4 v[216:217], off
	v_lshl_add_u64 v[216:217], s[4:5], 0, v[130:131]
	s_mov_b32 m0, s34
	s_nop 0
	global_load_lds_dwordx4 v[216:217], off
	v_lshl_add_u64 v[216:217], s[4:5], 0, v[134:135]
	s_add_i32 m0, s34, 0x2000
	s_nop 0
	global_load_lds_dwordx4 v[216:217], off
	v_lshl_add_u64 v[216:217], v[224:225], 0, s[16:17]
	s_mov_b32 m0, s47
	s_nop 0
	global_load_lds_dwordx4 v[216:217], off
	v_lshl_add_u64 v[216:217], v[226:227], 0, s[16:17]
	s_mov_b32 m0, s48
	s_nop 0
	global_load_lds_dwordx4 v[216:217], off
	s_waitcnt vmcnt(8)
	s_waitcnt lgkmcnt(0)
	s_barrier
	s_setprio 1
	s_waitcnt lgkmcnt(0)
	v_mfma_f32_16x16x32_bf16 v[60:63], v[148:151], v[180:183], v[60:63]
	v_mfma_f32_16x16x32_bf16 v[60:63], v[152:155], v[184:187], v[60:63]
	v_mfma_f32_16x16x32_bf16 v[56:59], v[156:159], v[180:183], v[56:59]
	v_mfma_f32_16x16x32_bf16 v[56:59], v[160:163], v[184:187], v[56:59]
	v_mfma_f32_16x16x32_bf16 v[44:47], v[164:167], v[180:183], v[44:47]
	v_mfma_f32_16x16x32_bf16 v[44:47], v[168:171], v[184:187], v[44:47]
	v_mfma_f32_16x16x32_bf16 v[36:39], v[172:175], v[180:183], v[36:39]
	v_mfma_f32_16x16x32_bf16 v[36:39], v[176:179], v[184:187], v[36:39]
	v_mfma_f32_16x16x32_bf16 v[20:23], v[172:175], v[188:191], v[20:23]
	v_mfma_f32_16x16x32_bf16 v[20:23], v[176:179], v[192:195], v[20:23]
	v_mfma_f32_16x16x32_bf16 v[28:31], v[164:167], v[188:191], v[28:31]
	v_mfma_f32_16x16x32_bf16 v[28:31], v[168:171], v[192:195], v[28:31]
	v_mfma_f32_16x16x32_bf16 v[48:51], v[156:159], v[188:191], v[48:51]
	v_mfma_f32_16x16x32_bf16 v[48:51], v[160:163], v[192:195], v[48:51]
	v_mfma_f32_16x16x32_bf16 v[52:55], v[148:151], v[188:191], v[52:55]
	v_mfma_f32_16x16x32_bf16 v[52:55], v[152:155], v[192:195], v[52:55]
	s_setprio 0
	s_setprio 1
	v_mfma_f32_16x16x32_bf16 v[40:43], v[148:151], v[196:199], v[40:43]
	v_mfma_f32_16x16x32_bf16 v[40:43], v[152:155], v[200:203], v[40:43]
	v_mfma_f32_16x16x32_bf16 v[32:35], v[156:159], v[196:199], v[32:35]
	v_mfma_f32_16x16x32_bf16 v[32:35], v[160:163], v[200:203], v[32:35]
	v_mfma_f32_16x16x32_bf16 v[12:15], v[164:167], v[196:199], v[12:15]
	v_mfma_f32_16x16x32_bf16 v[12:15], v[168:171], v[200:203], v[12:15]
	v_mfma_f32_16x16x32_bf16 v[8:11], v[172:175], v[196:199], v[8:11]
	v_mfma_f32_16x16x32_bf16 v[8:11], v[176:179], v[200:203], v[8:11]
	v_mfma_f32_16x16x32_bf16 v[0:3], v[172:175], v[208:211], v[0:3]
	v_mfma_f32_16x16x32_bf16 v[0:3], v[176:179], v[212:215], v[0:3]
	v_mfma_f32_16x16x32_bf16 v[4:7], v[164:167], v[208:211], v[4:7]
	v_mfma_f32_16x16x32_bf16 v[4:7], v[168:171], v[212:215], v[4:7]
	v_mfma_f32_16x16x32_bf16 v[16:19], v[156:159], v[208:211], v[16:19]
	v_mfma_f32_16x16x32_bf16 v[16:19], v[160:163], v[212:215], v[16:19]
	v_mfma_f32_16x16x32_bf16 v[24:27], v[148:151], v[208:211], v[24:27]
	v_mfma_f32_16x16x32_bf16 v[24:27], v[152:155], v[212:215], v[24:27]
	s_setprio 0
	s_barrier
	s_add_u32 s1, s1, 0x100
	s_addc_u32 s64, s64, 0
	s_cmp_ge_i32 s65, s46
	s_mov_b64 s[4:5], s[30:31]
	s_mov_b32 s34, s65
	s_cbranch_scc0 .LBB0_445
	v_pk_mul_f32 v[164:165], v[126:127], 0.5 op_sel_hi:[1,0]
	v_pk_mul_f32 v[200:201], v[124:125], 0.5 op_sel_hi:[1,0]
	v_pk_mul_f32 v[202:203], v[122:123], 0.5 op_sel_hi:[1,0]
	v_pk_mul_f32 v[208:209], v[120:121], 0.5 op_sel_hi:[1,0]
	v_pk_mul_f32 v[210:211], v[110:111], 0.5 op_sel_hi:[1,0]
	v_pk_mul_f32 v[212:213], v[108:109], 0.5 op_sel_hi:[1,0]
	v_pk_mul_f32 v[214:215], v[102:103], 0.5 op_sel_hi:[1,0]
	v_pk_mul_f32 v[216:217], v[100:101], 0.5 op_sel_hi:[1,0]
	v_pk_mul_f32 v[188:189], v[118:119], 0.5 op_sel_hi:[1,0]
	v_pk_mul_f32 v[186:187], v[116:117], 0.5 op_sel_hi:[1,0]
	v_pk_mul_f32 v[184:185], v[114:115], 0.5 op_sel_hi:[1,0]
	v_pk_mul_f32 v[182:183], v[112:113], 0.5 op_sel_hi:[1,0]
	v_pk_mul_f32 v[196:197], v[94:95], 0.5 op_sel_hi:[1,0]
	v_pk_mul_f32 v[194:195], v[92:93], 0.5 op_sel_hi:[1,0]
	v_pk_mul_f32 v[192:193], v[86:87], 0.5 op_sel_hi:[1,0]
	v_pk_mul_f32 v[190:191], v[84:85], 0.5 op_sel_hi:[1,0]
	v_pk_mul_f32 v[166:167], v[106:107], 0.5 op_sel_hi:[1,0]
	v_pk_mul_f32 v[168:169], v[104:105], 0.5 op_sel_hi:[1,0]
	v_pk_mul_f32 v[170:171], v[98:99], 0.5 op_sel_hi:[1,0]
	v_pk_mul_f32 v[172:173], v[96:97], 0.5 op_sel_hi:[1,0]
	v_pk_mul_f32 v[174:175], v[78:79], 0.5 op_sel_hi:[1,0]
	v_pk_mul_f32 v[176:177], v[76:77], 0.5 op_sel_hi:[1,0]
	v_pk_mul_f32 v[178:179], v[74:75], 0.5 op_sel_hi:[1,0]
	v_pk_mul_f32 v[180:181], v[72:73], 0.5 op_sel_hi:[1,0]
	v_pk_mul_f32 v[154:155], v[90:91], 0.5 op_sel_hi:[1,0]
	v_pk_mul_f32 v[152:153], v[88:89], 0.5 op_sel_hi:[1,0]
	v_pk_mul_f32 v[150:151], v[82:83], 0.5 op_sel_hi:[1,0]
	v_pk_mul_f32 v[148:149], v[80:81], 0.5 op_sel_hi:[1,0]
	v_pk_mul_f32 v[162:163], v[70:71], 0.5 op_sel_hi:[1,0]
	v_pk_mul_f32 v[160:161], v[68:69], 0.5 op_sel_hi:[1,0]
	v_pk_mul_f32 v[158:159], v[66:67], 0.5 op_sel_hi:[1,0]
	v_pk_mul_f32 v[156:157], v[64:65], 0.5 op_sel_hi:[1,0]
	v_pk_mul_f32 v[112:113], v[62:63], 0.5 op_sel_hi:[1,0]
	v_pk_mul_f32 v[114:115], v[60:61], 0.5 op_sel_hi:[1,0]
	v_pk_mul_f32 v[116:117], v[58:59], 0.5 op_sel_hi:[1,0]
	v_pk_mul_f32 v[118:119], v[56:57], 0.5 op_sel_hi:[1,0]
	v_pk_mul_f32 v[120:121], v[46:47], 0.5 op_sel_hi:[1,0]
	v_pk_mul_f32 v[122:123], v[44:45], 0.5 op_sel_hi:[1,0]
	v_pk_mul_f32 v[124:125], v[38:39], 0.5 op_sel_hi:[1,0]
	v_pk_mul_f32 v[126:127], v[36:37], 0.5 op_sel_hi:[1,0]
	v_pk_mul_f32 v[102:103], v[54:55], 0.5 op_sel_hi:[1,0]
	v_pk_mul_f32 v[100:101], v[52:53], 0.5 op_sel_hi:[1,0]
	v_pk_mul_f32 v[98:99], v[50:51], 0.5 op_sel_hi:[1,0]
	v_pk_mul_f32 v[96:97], v[48:49], 0.5 op_sel_hi:[1,0]
	v_pk_mul_f32 v[110:111], v[30:31], 0.5 op_sel_hi:[1,0]
	v_pk_mul_f32 v[108:109], v[28:29], 0.5 op_sel_hi:[1,0]
	v_pk_mul_f32 v[106:107], v[22:23], 0.5 op_sel_hi:[1,0]
	v_pk_mul_f32 v[104:105], v[20:21], 0.5 op_sel_hi:[1,0]
	v_pk_mul_f32 v[86:87], v[42:43], 0.5 op_sel_hi:[1,0]
	v_pk_mul_f32 v[84:85], v[40:41], 0.5 op_sel_hi:[1,0]
	v_pk_mul_f32 v[82:83], v[34:35], 0.5 op_sel_hi:[1,0]
	v_pk_mul_f32 v[80:81], v[32:33], 0.5 op_sel_hi:[1,0]
	v_pk_mul_f32 v[94:95], v[14:15], 0.5 op_sel_hi:[1,0]
	v_pk_mul_f32 v[92:93], v[12:13], 0.5 op_sel_hi:[1,0]
	v_pk_mul_f32 v[90:91], v[10:11], 0.5 op_sel_hi:[1,0]
	v_pk_mul_f32 v[88:89], v[8:9], 0.5 op_sel_hi:[1,0]
	v_pk_mul_f32 v[70:71], v[26:27], 0.5 op_sel_hi:[1,0]
	v_pk_mul_f32 v[68:69], v[24:25], 0.5 op_sel_hi:[1,0]
	v_pk_mul_f32 v[66:67], v[18:19], 0.5 op_sel_hi:[1,0]
	v_pk_mul_f32 v[64:65], v[16:17], 0.5 op_sel_hi:[1,0]
	v_pk_mul_f32 v[78:79], v[6:7], 0.5 op_sel_hi:[1,0]
	v_pk_mul_f32 v[76:77], v[4:5], 0.5 op_sel_hi:[1,0]
	v_pk_mul_f32 v[74:75], v[2:3], 0.5 op_sel_hi:[1,0]
	v_pk_mul_f32 v[72:73], v[0:1], 0.5 op_sel_hi:[1,0]

; #define PG8_STAGE(bufoff, gbase, voff) do { _Pragma("unroll") for (int _i = 0; _i < 2; ++_i) \
;         __builtin_amdgcn_global_load_lds((const unsigned*)((const char*)(gbase) + (voff)[_i]), (LAS unsigned*)(lds + (bufoff) + ldsw + _i * 8192), 16, 0, 0); } while (0)
; #define PG8_LDA(dst, b, h) do { _Pragma("unroll") for (int m = 0; m < 4; ++m) _Pragma("unroll") for (int k = 0; k < 2; ++k) dst[m][k] = *(const LAS bf16x8*)(lds + PG8_SA(b, h) + aoff + m * 2048 + k * 1024); } while (0)
; #define PG8_LDB(dst, b, h) do { _Pragma("unroll") for (int n = 0; n < 2; ++n) _Pragma("unroll") for (int k = 0; k < 2; ++k) dst[n][k] = *(const LAS bf16x8*)(lds + PG8_SB(b, h) + boff + n * 2048 + k * 1024); } while (0)
; #define PG8_MMA(ai, bj, At, Bt) do { __builtin_amdgcn_s_setprio(1); _Pragma("unroll") for (int m = 0; m < 4; ++m) _Pragma("unroll") for (int n = 0; n < 2; ++n) _Pragma("unroll") for (int k = 0; k < 2; ++k) \
;         acc[ai][bj][m][n] = __builtin_amdgcn_mfma_f32_16x16x32_bf16(Bt[n][k], At[m][k], acc[ai][bj][m][n], 0, 0, 0); __builtin_amdgcn_s_setprio(0); } while (0)
; #define PG8_WAIT_V(n) asm volatile("s_waitcnt vmcnt(" #n ")" ::: "memory")
; #define PG8_WAIT_L(n) asm volatile("s_waitcnt lgkmcnt(" #n ")" ::: "memory")
; #define PG8_BAR __builtin_amdgcn_s_barrier()
; #define PG8_SCHED __builtin_amdgcn_sched_barrier(0)
; template <class Epi>
; __device__ __forceinline__ void gemm_phase(LAS unsigned char* lds, const Gemm g, const StaticOrder& S, const Epi& E) {
;     ...
;             PG8_LDB(B0, 0, 0); PG8_LDB(B1, 0, 1); PG8_SCHED; PG8_LDA(At, 0, 0); PG8_STAGE(PG8_SA(1, 1), a1 + hstepA, voffA);
;             PG8_WAIT_V(8); PG8_WAIT_L(0); PG8_BAR; PG8_MMA(0, 0, At, B0); PG8_MMA(0, 1, At, B1); PG8_BAR; PG8_SCHED;
;             PG8_LDA(At, 0, 1); PG8_STAGE(PG8_SB(0, 0), b2, voffB); PG8_STAGE(PG8_SB(0, 1), b2 + hstepB, voffB); PG8_STAGE(PG8_SA(0, 0), a2, voffA);
;             PG8_WAIT_V(8); PG8_WAIT_L(0); PG8_BAR; PG8_MMA(1, 0, At, B0); PG8_MMA(1, 1, At, B1); PG8_BAR; PG8_SCHED;
.LBB0_541:
	ds_read_b128 v[148:151], v155
	ds_read_b128 v[160:163], v155 offset:1024
	ds_read_b128 v[164:167], v155 offset:2048
	ds_read_b128 v[168:171], v155 offset:3072
	ds_read_b128 v[172:175], v156
	ds_read_b128 v[176:179], v156 offset:1024
	ds_read_b128 v[180:183], v156 offset:2048
	ds_read_b128 v[184:187], v156 offset:3072
	s_add_i32 s35, s26, 2
	s_add_u32 s27, s8, 0xfff80080
	s_addc_u32 s30, s9, -1
	s_cmp_eq_u32 s49, s26
	s_cselect_b32 s26, s21, s33
	s_cselect_b32 s31, s1, s30
	s_cselect_b32 s30, s5, s27
	s_cselect_b32 s27, s19, s34
	v_lshl_add_u64 v[224:225], s[8:9], 0, v[140:141]
	s_add_i32 m0, s39, 0xc000
	ds_read_b128 v[188:191], v157
	ds_read_b128 v[192:195], v157 offset:1024
	ds_read_b128 v[196:199], v157 offset:2048
	ds_read_b128 v[200:203], v157 offset:3072
	ds_read_b128 v[208:211], v157 offset:4096
	ds_read_b128 v[212:215], v157 offset:5120
	ds_read_b128 v[216:219], v157 offset:6144
	ds_read_b128 v[220:223], v157 offset:7168
	global_load_lds_dwordx4 v[224:225], off
	v_lshl_add_u64 v[224:225], s[8:9], 0, v[142:143]
	s_add_i32 m0, s39, 0xe000
	s_nop 0
	global_load_lds_dwordx4 v[224:225], off
	s_waitcnt vmcnt(8)
	s_waitcnt lgkmcnt(0)
	s_barrier
	s_setprio 1
	s_waitcnt lgkmcnt(0)
	v_mfma_f32_16x16x32_bf16 v[120:123], v[148:151], v[188:191], v[120:123]
	v_mfma_f32_16x16x32_bf16 v[120:123], v[160:163], v[192:195], v[120:123]
	v_mfma_f32_16x16x32_bf16 v[124:127], v[164:167], v[188:191], v[124:127]
	v_mfma_f32_16x16x32_bf16 v[124:127], v[168:171], v[192:195], v[124:127]
	v_mfma_f32_16x16x32_bf16 v[116:119], v[172:175], v[188:191], v[116:119]
	v_mfma_f32_16x16x32_bf16 v[116:119], v[176:179], v[192:195], v[116:119]
	v_mfma_f32_16x16x32_bf16 v[112:115], v[180:183], v[188:191], v[112:115]
	v_mfma_f32_16x16x32_bf16 v[112:115], v[184:187], v[192:195], v[112:115]
	v_mfma_f32_16x16x32_bf16 v[96:99], v[180:183], v[196:199], v[96:99]
	v_mfma_f32_16x16x32_bf16 v[96:99], v[184:187], v[200:203], v[96:99]
	v_mfma_f32_16x16x32_bf16 v[100:103], v[172:175], v[196:199], v[100:103]
	v_mfma_f32_16x16x32_bf16 v[100:103], v[176:179], v[200:203], v[100:103]
	v_mfma_f32_16x16x32_bf16 v[104:107], v[164:167], v[196:199], v[104:107]
	v_mfma_f32_16x16x32_bf16 v[104:107], v[168:171], v[200:203], v[104:107]
	v_mfma_f32_16x16x32_bf16 v[108:111], v[148:151], v[196:199], v[108:111]
	v_mfma_f32_16x16x32_bf16 v[108:111], v[160:163], v[200:203], v[108:111]
	s_setprio 0
	s_setprio 1
	v_mfma_f32_16x16x32_bf16 v[92:95], v[148:151], v[208:211], v[92:95]
	v_mfma_f32_16x16x32_bf16 v[92:95], v[160:163], v[212:215], v[92:95]
	v_mfma_f32_16x16x32_bf16 v[88:91], v[164:167], v[208:211], v[88:91]
	v_mfma_f32_16x16x32_bf16 v[88:91], v[168:171], v[212:215], v[88:91]
	v_mfma_f32_16x16x32_bf16 v[84:87], v[172:175], v[208:211], v[84:87]
	v_mfma_f32_16x16x32_bf16 v[84:87], v[176:179], v[212:215], v[84:87]
	v_mfma_f32_16x16x32_bf16 v[80:83], v[180:183], v[208:211], v[80:83]
	v_mfma_f32_16x16x32_bf16 v[80:83], v[184:187], v[212:215], v[80:83]
	v_mfma_f32_16x16x32_bf16 v[64:67], v[180:183], v[216:219], v[64:67]
	v_mfma_f32_16x16x32_bf16 v[64:67], v[184:187], v[220:223], v[64:67]
	v_mfma_f32_16x16x32_bf16 v[68:71], v[172:175], v[216:219], v[68:71]
	v_mfma_f32_16x16x32_bf16 v[68:71], v[176:179], v[220:223], v[68:71]
	v_mfma_f32_16x16x32_bf16 v[72:75], v[164:167], v[216:219], v[72:75]
	v_mfma_f32_16x16x32_bf16 v[72:75], v[168:171], v[220:223], v[72:75]
	v_mfma_f32_16x16x32_bf16 v[76:79], v[148:151], v[216:219], v[76:79]
	v_mfma_f32_16x16x32_bf16 v[76:79], v[160:163], v[220:223], v[76:79]
	s_setprio 0
	s_barrier
	s_add_i32 s58, s54, s38
	v_lshl_add_u64 v[224:225], s[26:27], 0, v[130:131]
	s_mov_b32 m0, s58
	ds_read_b128 v[188:191], v157 offset:16384
	ds_read_b128 v[192:195], v157 offset:17408
	ds_read_b128 v[196:199], v157 offset:18432
	ds_read_b128 v[200:203], v157 offset:19456
	ds_read_b128 v[208:211], v157 offset:20480
	ds_read_b128 v[212:215], v157 offset:21504
	ds_read_b128 v[216:219], v157 offset:22528
	ds_read_b128 v[220:223], v157 offset:23552
	global_load_lds_dwordx4 v[224:225], off
	s_add_i32 m0, s58, 0x2000
	s_add_u32 s58, s26, 0x80000
	v_lshl_add_u64 v[226:227], s[26:27], 0, v[134:135]
	s_addc_u32 s59, s27, 0
	s_add_i32 s60, s55, s38
	global_load_lds_dwordx4 v[226:227], off
	v_lshl_add_u64 v[230:231], s[58:59], 0, v[130:131]
	s_mov_b32 m0, s60
	v_lshl_add_u64 v[232:233], s[30:31], 0, v[132:133]
	global_load_lds_dwordx4 v[230:231], off
	v_lshl_add_u64 v[230:231], s[58:59], 0, v[134:135]
	s_add_i32 m0, s60, 0x2000
	s_nop 0
	global_load_lds_dwordx4 v[230:231], off
	v_lshl_add_u64 v[230:231], s[30:31], 0, v[128:129]
	s_mov_b32 m0, s39
	s_nop 0
	global_load_lds_dwordx4 v[230:231], off
	s_mov_b32 m0, s40
	s_nop 0
	global_load_lds_dwordx4 v[232:233], off
	s_waitcnt vmcnt(8)
	s_waitcnt lgkmcnt(0)
	s_barrier
; #define PG8_STAGE(bufoff, gbase, voff) do { _Pragma("unroll") for (int _i = 0; _i < 2; ++_i) \
;         __builtin_amdgcn_global_load_lds((const unsigned*)((const char*)(gbase) + (voff)[_i]), (LAS unsigned*)(lds + (bufoff) + ldsw + _i * 8192), 16, 0, 0); } while (0)
; #define PG8_LDA(dst, b, h) do { _Pragma("unroll") for (int m = 0; m < 4; ++m) _Pragma("unroll") for (int k = 0; k < 2; ++k) dst[m][k] = *(const LAS bf16x8*)(lds + PG8_SA(b, h) + aoff + m * 2048 + k * 1024); } while (0)
; #define PG8_LDB(dst, b, h) do { _Pragma("unroll") for (int n = 0; n < 2; ++n) _Pragma("unroll") for (int k = 0; k < 2; ++k) dst[n][k] = *(const LAS bf16x8*)(lds + PG8_SB(b, h) + boff + n * 2048 + k * 1024); } while (0)
; #define PG8_MMA(ai, bj, At, Bt) do { __builtin_amdgcn_s_setprio(1); _Pragma("unroll") for (int m = 0; m < 4; ++m) _Pragma("unroll") for (int n = 0; n < 2; ++n) _Pragma("unroll") for (int k = 0; k < 2; ++k) \
;         acc[ai][bj][m][n] = __builtin_amdgcn_mfma_f32_16x16x32_bf16(Bt[n][k], At[m][k], acc[ai][bj][m][n], 0, 0, 0); __builtin_amdgcn_s_setprio(0); } while (0)
; #define PG8_WAIT_V(n) asm volatile("s_waitcnt vmcnt(" #n ")" ::: "memory")
; #define PG8_WAIT_L(n) asm volatile("s_waitcnt lgkmcnt(" #n ")" ::: "memory")
; #define PG8_BAR __builtin_amdgcn_s_barrier()
; #define PG8_SCHED __builtin_amdgcn_sched_barrier(0)
; template <class Epi>
; __device__ __forceinline__ void gemm_phase(LAS unsigned char* lds, const Gemm g, const StaticOrder& S, const Epi& E) {
;     ...
;             PG8_WAIT_V(8); PG8_WAIT_L(0); PG8_BAR; PG8_MMA(1, 0, At, B0); PG8_MMA(1, 1, At, B1); PG8_BAR; PG8_SCHED;
;             PG8_LDB(B0, 1, 0); PG8_LDB(B1, 1, 1); PG8_SCHED; PG8_LDA(At, 1, 0); PG8_STAGE(PG8_SA(0, 1), a2 + hstepA, voffA);
;             PG8_WAIT_V(8); PG8_WAIT_L(0); PG8_BAR; PG8_MMA(0, 0, At, B0); PG8_MMA(0, 1, At, B1); PG8_BAR; PG8_SCHED;
	s_setprio 1
	s_waitcnt lgkmcnt(0)
	v_mfma_f32_16x16x32_bf16 v[60:63], v[148:151], v[188:191], v[60:63]
	v_mfma_f32_16x16x32_bf16 v[60:63], v[160:163], v[192:195], v[60:63]
	v_mfma_f32_16x16x32_bf16 v[56:59], v[164:167], v[188:191], v[56:59]
	v_mfma_f32_16x16x32_bf16 v[56:59], v[168:171], v[192:195], v[56:59]
	v_mfma_f32_16x16x32_bf16 v[52:55], v[172:175], v[188:191], v[52:55]
	v_mfma_f32_16x16x32_bf16 v[52:55], v[176:179], v[192:195], v[52:55]
	v_mfma_f32_16x16x32_bf16 v[48:51], v[180:183], v[188:191], v[48:51]
	v_mfma_f32_16x16x32_bf16 v[48:51], v[184:187], v[192:195], v[48:51]
	v_mfma_f32_16x16x32_bf16 v[32:35], v[180:183], v[196:199], v[32:35]
	v_mfma_f32_16x16x32_bf16 v[32:35], v[184:187], v[200:203], v[32:35]
	v_mfma_f32_16x16x32_bf16 v[36:39], v[172:175], v[196:199], v[36:39]
	v_mfma_f32_16x16x32_bf16 v[36:39], v[176:179], v[200:203], v[36:39]
	v_mfma_f32_16x16x32_bf16 v[40:43], v[164:167], v[196:199], v[40:43]
	v_mfma_f32_16x16x32_bf16 v[40:43], v[168:171], v[200:203], v[40:43]
	v_mfma_f32_16x16x32_bf16 v[44:47], v[148:151], v[196:199], v[44:47]
	v_mfma_f32_16x16x32_bf16 v[44:47], v[160:163], v[200:203], v[44:47]
	s_setprio 0
	s_setprio 1
	v_mfma_f32_16x16x32_bf16 v[28:31], v[148:151], v[208:211], v[28:31]
	v_mfma_f32_16x16x32_bf16 v[28:31], v[160:163], v[212:215], v[28:31]
	v_mfma_f32_16x16x32_bf16 v[24:27], v[164:167], v[208:211], v[24:27]
	v_mfma_f32_16x16x32_bf16 v[24:27], v[168:171], v[212:215], v[24:27]
	v_mfma_f32_16x16x32_bf16 v[20:23], v[172:175], v[208:211], v[20:23]
	v_mfma_f32_16x16x32_bf16 v[20:23], v[176:179], v[212:215], v[20:23]
	v_mfma_f32_16x16x32_bf16 v[16:19], v[180:183], v[208:211], v[16:19]
	v_mfma_f32_16x16x32_bf16 v[16:19], v[184:187], v[212:215], v[16:19]
	v_mfma_f32_16x16x32_bf16 v[0:3], v[180:183], v[216:219], v[0:3]
	v_mfma_f32_16x16x32_bf16 v[0:3], v[184:187], v[220:223], v[0:3]
	v_mfma_f32_16x16x32_bf16 v[4:7], v[172:175], v[216:219], v[4:7]
	v_mfma_f32_16x16x32_bf16 v[4:7], v[176:179], v[220:223], v[4:7]
	v_mfma_f32_16x16x32_bf16 v[8:11], v[164:167], v[216:219], v[8:11]
	v_mfma_f32_16x16x32_bf16 v[8:11], v[168:171], v[220:223], v[8:11]
	v_mfma_f32_16x16x32_bf16 v[12:15], v[148:151], v[216:219], v[12:15]
	v_mfma_f32_16x16x32_bf16 v[12:15], v[160:163], v[220:223], v[12:15]
	s_setprio 0
	s_barrier
	s_add_i32 s58, 0, 0x18000
	v_add_u32_e32 v136, s58, v154
	s_add_i32 s59, 0, 0x1c000
	ds_read_b128 v[148:151], v136
	ds_read_b128 v[160:163], v136 offset:1024
	ds_read_b128 v[164:167], v136 offset:2048
	ds_read_b128 v[168:171], v136 offset:3072
	v_add_u32_e32 v136, s59, v154
	ds_read_b128 v[172:175], v136
	ds_read_b128 v[176:179], v136 offset:1024
	ds_read_b128 v[180:183], v136 offset:2048
	ds_read_b128 v[184:187], v136 offset:3072
	s_add_u32 s30, s30, 0x80000
	s_addc_u32 s31, s31, 0
	s_mov_b32 m0, s41
	v_lshl_add_u64 v[234:235], s[30:31], 0, v[128:129]
	ds_read_b128 v[188:191], v157 offset:32768
	ds_read_b128 v[192:195], v157 offset:33792
	ds_read_b128 v[196:199], v157 offset:34816
	ds_read_b128 v[200:203], v157 offset:35840
	ds_read_b128 v[208:211], v157 offset:36864
	ds_read_b128 v[212:215], v157 offset:37888
	ds_read_b128 v[216:219], v157 offset:38912
	ds_read_b128 v[220:223], v157 offset:39936
	global_load_lds_dwordx4 v[234:235], off
	v_lshl_add_u64 v[234:235], s[30:31], 0, v[132:133]
	s_mov_b32 m0, s42
	s_nop 0
	global_load_lds_dwordx4 v[234:235], off
	s_waitcnt vmcnt(8)
	s_waitcnt lgkmcnt(0)
	s_barrier
	s_setprio 1
	s_waitcnt lgkmcnt(0)
	v_mfma_f32_16x16x32_bf16 v[120:123], v[148:151], v[188:191], v[120:123]
	v_mfma_f32_16x16x32_bf16 v[120:123], v[160:163], v[192:195], v[120:123]
	v_mfma_f32_16x16x32_bf16 v[124:127], v[164:167], v[188:191], v[124:127]
	v_mfma_f32_16x16x32_bf16 v[124:127], v[168:171], v[192:195], v[124:127]
	v_mfma_f32_16x16x32_bf16 v[116:119], v[172:175], v[188:191], v[116:119]
	v_mfma_f32_16x16x32_bf16 v[116:119], v[176:179], v[192:195], v[116:119]
	v_mfma_f32_16x16x32_bf16 v[112:115], v[180:183], v[188:191], v[112:115]
	v_mfma_f32_16x16x32_bf16 v[112:115], v[184:187], v[192:195], v[112:115]
	v_mfma_f32_16x16x32_bf16 v[96:99], v[180:183], v[196:199], v[96:99]
	v_mfma_f32_16x16x32_bf16 v[96:99], v[184:187], v[200:203], v[96:99]
	v_mfma_f32_16x16x32_bf16 v[100:103], v[172:175], v[196:199], v[100:103]
	v_mfma_f32_16x16x32_bf16 v[100:103], v[176:179], v[200:203], v[100:103]
	v_mfma_f32_16x16x32_bf16 v[104:107], v[164:167], v[196:199], v[104:107]
	v_mfma_f32_16x16x32_bf16 v[104:107], v[168:171], v[200:203], v[104:107]
	v_mfma_f32_16x16x32_bf16 v[108:111], v[148:151], v[196:199], v[108:111]
	v_mfma_f32_16x16x32_bf16 v[108:111], v[160:163], v[200:203], v[108:111]
	s_setprio 0
	s_setprio 1
	v_mfma_f32_16x16x32_bf16 v[92:95], v[148:151], v[208:211], v[92:95]
	v_mfma_f32_16x16x32_bf16 v[92:95], v[160:163], v[212:215], v[92:95]
	v_mfma_f32_16x16x32_bf16 v[88:91], v[164:167], v[208:211], v[88:91]
	v_mfma_f32_16x16x32_bf16 v[88:91], v[168:171], v[212:215], v[88:91]
	v_mfma_f32_16x16x32_bf16 v[84:87], v[172:175], v[208:211], v[84:87]
	v_mfma_f32_16x16x32_bf16 v[84:87], v[176:179], v[212:215], v[84:87]
	v_mfma_f32_16x16x32_bf16 v[80:83], v[180:183], v[208:211], v[80:83]
	v_mfma_f32_16x16x32_bf16 v[80:83], v[184:187], v[212:215], v[80:83]
	v_mfma_f32_16x16x32_bf16 v[64:67], v[180:183], v[216:219], v[64:67]
	v_mfma_f32_16x16x32_bf16 v[64:67], v[184:187], v[220:223], v[64:67]
	v_mfma_f32_16x16x32_bf16 v[68:71], v[172:175], v[216:219], v[68:71]
	v_mfma_f32_16x16x32_bf16 v[68:71], v[176:179], v[220:223], v[68:71]
	v_mfma_f32_16x16x32_bf16 v[72:75], v[164:167], v[216:219], v[72:75]
	v_mfma_f32_16x16x32_bf16 v[72:75], v[168:171], v[220:223], v[72:75]
	v_mfma_f32_16x16x32_bf16 v[76:79], v[148:151], v[216:219], v[76:79]
	v_mfma_f32_16x16x32_bf16 v[76:79], v[160:163], v[220:223], v[76:79]
	s_setprio 0
	s_barrier
; #define PG8_STAGE(bufoff, gbase, voff) do { _Pragma("unroll") for (int _i = 0; _i < 2; ++_i) \
;         __builtin_amdgcn_global_load_lds((const unsigned*)((const char*)(gbase) + (voff)[_i]), (LAS unsigned*)(lds + (bufoff) + ldsw + _i * 8192), 16, 0, 0); } while (0)
; #define PG8_LDA(dst, b, h) do { _Pragma("unroll") for (int m = 0; m < 4; ++m) _Pragma("unroll") for (int k = 0; k < 2; ++k) dst[m][k] = *(const LAS bf16x8*)(lds + PG8_SA(b, h) + aoff + m * 2048 + k * 1024); } while (0)
; #define PG8_MMA(ai, bj, At, Bt) do { __builtin_amdgcn_s_setprio(1); _Pragma("unroll") for (int m = 0; m < 4; ++m) _Pragma("unroll") for (int n = 0; n < 2; ++n) _Pragma("unroll") for (int k = 0; k < 2; ++k) \
;         acc[ai][bj][m][n] = __builtin_amdgcn_mfma_f32_16x16x32_bf16(Bt[n][k], At[m][k], acc[ai][bj][m][n], 0, 0, 0); __builtin_amdgcn_s_setprio(0); } while (0)
; #define PG8_WAIT_V(n) asm volatile("s_waitcnt vmcnt(" #n ")" ::: "memory")
; #define PG8_WAIT_L(n) asm volatile("s_waitcnt lgkmcnt(" #n ")" ::: "memory")
; #define PG8_BAR __builtin_amdgcn_s_barrier()
; #define PG8_SCHED __builtin_amdgcn_sched_barrier(0)
; template <class Epi>
; __device__ __forceinline__ void gemm_phase(LAS unsigned char* lds, const Gemm g, const StaticOrder& S, const Epi& E) {
;     ...
;             PG8_LDA(At, 1, 1); PG8_STAGE(PG8_SB(1, 0), b3, voffB); PG8_STAGE(PG8_SB(1, 1), b3 + hstepB, voffB); PG8_STAGE(PG8_SA(1, 0), a3, voffA);
;             PG8_WAIT_V(8); PG8_WAIT_L(0); PG8_BAR; PG8_MMA(1, 0, At, B0); PG8_MMA(1, 1, At, B1); PG8_BAR; PG8_SCHED;
;         }
	s_add_i32 s30, s58, s38
	v_lshl_add_u64 v[224:225], v[224:225], 0, s[12:13]
	s_mov_b32 m0, s30
	ds_read_b128 v[188:191], v157 offset:49152
	ds_read_b128 v[192:195], v157 offset:50176
	ds_read_b128 v[196:199], v157 offset:51200
	ds_read_b128 v[200:203], v157 offset:52224
	ds_read_b128 v[208:211], v157 offset:53248
	ds_read_b128 v[212:215], v157 offset:54272
	ds_read_b128 v[216:219], v157 offset:55296
	ds_read_b128 v[220:223], v157 offset:56320
	global_load_lds_dwordx4 v[224:225], off
	s_add_i32 m0, s30, 0x2000
	s_add_u32 s26, s26, 0x80080
	v_lshl_add_u64 v[224:225], v[226:227], 0, s[12:13]
	s_addc_u32 s27, s27, 0
	s_add_i32 s30, s59, s38
	global_load_lds_dwordx4 v[224:225], off
	v_lshl_add_u64 v[224:225], s[26:27], 0, v[130:131]
	s_mov_b32 m0, s30
	s_nop 0
	global_load_lds_dwordx4 v[224:225], off
	v_lshl_add_u64 v[224:225], s[26:27], 0, v[134:135]
	s_add_i32 m0, s30, 0x2000
	s_nop 0
	global_load_lds_dwordx4 v[224:225], off
	v_lshl_add_u64 v[224:225], v[230:231], 0, s[12:13]
	s_mov_b32 m0, s47
	s_nop 0
	global_load_lds_dwordx4 v[224:225], off
	v_lshl_add_u64 v[224:225], v[232:233], 0, s[12:13]
	s_mov_b32 m0, s48
	s_nop 0
	global_load_lds_dwordx4 v[224:225], off
	s_waitcnt vmcnt(8)
	s_waitcnt lgkmcnt(0)
	s_barrier
	s_setprio 1
	s_waitcnt lgkmcnt(0)
	v_mfma_f32_16x16x32_bf16 v[60:63], v[148:151], v[188:191], v[60:63]
	v_mfma_f32_16x16x32_bf16 v[60:63], v[160:163], v[192:195], v[60:63]
	v_mfma_f32_16x16x32_bf16 v[56:59], v[164:167], v[188:191], v[56:59]
	v_mfma_f32_16x16x32_bf16 v[56:59], v[168:171], v[192:195], v[56:59]
	v_mfma_f32_16x16x32_bf16 v[52:55], v[172:175], v[188:191], v[52:55]
	v_mfma_f32_16x16x32_bf16 v[52:55], v[176:179], v[192:195], v[52:55]
	v_mfma_f32_16x16x32_bf16 v[48:51], v[180:183], v[188:191], v[48:51]
	v_mfma_f32_16x16x32_bf16 v[48:51], v[184:187], v[192:195], v[48:51]
	v_mfma_f32_16x16x32_bf16 v[32:35], v[180:183], v[196:199], v[32:35]
	v_mfma_f32_16x16x32_bf16 v[32:35], v[184:187], v[200:203], v[32:35]
	v_mfma_f32_16x16x32_bf16 v[36:39], v[172:175], v[196:199], v[36:39]
	v_mfma_f32_16x16x32_bf16 v[36:39], v[176:179], v[200:203], v[36:39]
	v_mfma_f32_16x16x32_bf16 v[40:43], v[164:167], v[196:199], v[40:43]
	v_mfma_f32_16x16x32_bf16 v[40:43], v[168:171], v[200:203], v[40:43]
	v_mfma_f32_16x16x32_bf16 v[44:47], v[148:151], v[196:199], v[44:47]
	v_mfma_f32_16x16x32_bf16 v[44:47], v[160:163], v[200:203], v[44:47]
	s_setprio 0
	s_setprio 1
	v_mfma_f32_16x16x32_bf16 v[28:31], v[148:151], v[208:211], v[28:31]
	v_mfma_f32_16x16x32_bf16 v[28:31], v[160:163], v[212:215], v[28:31]
	v_mfma_f32_16x16x32_bf16 v[24:27], v[164:167], v[208:211], v[24:27]
	v_mfma_f32_16x16x32_bf16 v[24:27], v[168:171], v[212:215], v[24:27]
	v_mfma_f32_16x16x32_bf16 v[20:23], v[172:175], v[208:211], v[20:23]
	v_mfma_f32_16x16x32_bf16 v[20:23], v[176:179], v[212:215], v[20:23]
	v_mfma_f32_16x16x32_bf16 v[16:19], v[180:183], v[208:211], v[16:19]
	v_mfma_f32_16x16x32_bf16 v[16:19], v[184:187], v[212:215], v[16:19]
	v_mfma_f32_16x16x32_bf16 v[0:3], v[180:183], v[216:219], v[0:3]
	v_mfma_f32_16x16x32_bf16 v[0:3], v[184:187], v[220:223], v[0:3]
	v_mfma_f32_16x16x32_bf16 v[4:7], v[172:175], v[216:219], v[4:7]
	v_mfma_f32_16x16x32_bf16 v[4:7], v[176:179], v[220:223], v[4:7]
	v_mfma_f32_16x16x32_bf16 v[8:11], v[164:167], v[216:219], v[8:11]
	v_mfma_f32_16x16x32_bf16 v[8:11], v[168:171], v[220:223], v[8:11]
	v_mfma_f32_16x16x32_bf16 v[12:15], v[148:151], v[216:219], v[12:15]
	v_mfma_f32_16x16x32_bf16 v[12:15], v[160:163], v[220:223], v[12:15]
	s_setprio 0
	s_barrier
	s_add_u32 s8, s8, 0x100
	s_addc_u32 s9, s9, 0
	s_add_u32 s33, s33, 0x100
	s_addc_u32 s34, s34, 0
	s_cmp_ge_i32 s35, s44
	s_mov_b32 s26, s35
	s_cbranch_scc0 .LBB0_541

; #define PG8_STAGE(bufoff, gbase, voff) do { _Pragma("unroll") for (int _i = 0; _i < 2; ++_i) \
;         __builtin_amdgcn_global_load_lds((const unsigned*)((const char*)(gbase) + (voff)[_i]), (LAS unsigned*)(lds + (bufoff) + ldsw + _i * 8192), 16, 0, 0); } while (0)
; #define PG8_LDA(dst, b, h) do { _Pragma("unroll") for (int m = 0; m < 4; ++m) _Pragma("unroll") for (int k = 0; k < 2; ++k) dst[m][k] = *(const LAS bf16x8*)(lds + PG8_SA(b, h) + aoff + m * 2048 + k * 1024); } while (0)
; #define PG8_LDB(dst, b, h) do { _Pragma("unroll") for (int n = 0; n < 2; ++n) _Pragma("unroll") for (int k = 0; k < 2; ++k) dst[n][k] = *(const LAS bf16x8*)(lds + PG8_SB(b, h) + boff + n * 2048 + k * 1024); } while (0)
; #define PG8_MMA(ai, bj, At, Bt) do { __builtin_amdgcn_s_setprio(1); _Pragma("unroll") for (int m = 0; m < 4; ++m) _Pragma("unroll") for (int n = 0; n < 2; ++n) _Pragma("unroll") for (int k = 0; k < 2; ++k) \
;         acc[ai][bj][m][n] = __builtin_amdgcn_mfma_f32_16x16x32_bf16(Bt[n][k], At[m][k], acc[ai][bj][m][n], 0, 0, 0); __builtin_amdgcn_s_setprio(0); } while (0)
; #define PG8_WAIT_V(n) asm volatile("s_waitcnt vmcnt(" #n ")" ::: "memory")
; #define PG8_WAIT_L(n) asm volatile("s_waitcnt lgkmcnt(" #n ")" ::: "memory")
; #define PG8_BAR __builtin_amdgcn_s_barrier()
; #define PG8_SCHED __builtin_amdgcn_sched_barrier(0)
; template <class Epi>
; __device__ __forceinline__ void gemm_phase(LAS unsigned char* lds, const Gemm g, const StaticOrder& S, const Epi& E) {
;     ...
;             PG8_LDB(B0, 0, 0); PG8_LDB(B1, 0, 1); PG8_SCHED; PG8_LDA(At, 0, 0); PG8_STAGE(PG8_SA(1, 1), a1 + hstepA, voffA);
;             PG8_WAIT_V(8); PG8_WAIT_L(0); PG8_BAR; PG8_MMA(0, 0, At, B0); PG8_MMA(0, 1, At, B1); PG8_BAR; PG8_SCHED;
;             PG8_LDA(At, 0, 1); PG8_STAGE(PG8_SB(0, 0), b2, voffB); PG8_STAGE(PG8_SB(0, 1), b2 + hstepB, voffB); PG8_STAGE(PG8_SA(0, 0), a2, voffA);
;             PG8_WAIT_V(8); PG8_WAIT_L(0); PG8_BAR; PG8_MMA(1, 0, At, B0); PG8_MMA(1, 1, At, B1); PG8_BAR; PG8_SCHED;
.LBB0_685:
	ds_read_b128 v[88:91], v85
	ds_read_b128 v[92:95], v85 offset:1024
	ds_read_b128 v[96:99], v85 offset:2048
	ds_read_b128 v[100:103], v85 offset:3072
	s_add_i32 s61, s34, 2
	s_add_u32 s8, s30, 0x100
	s_addc_u32 s9, s31, 0
	s_cmp_eq_u32 s53, s34
	s_cselect_b32 s34, s25, s59
	s_cselect_b32 s37, s27, s9
	s_cselect_b32 s36, s26, s8
	s_cselect_b32 s35, s17, s60
	v_lshl_add_u64 v[136:137], s[30:31], 0, v[76:77]
	s_add_i32 m0, s40, 0xc000
	ds_read_b128 v[104:107], v86
	ds_read_b128 v[108:111], v86 offset:1024
	ds_read_b128 v[112:115], v86 offset:2048
	ds_read_b128 v[116:119], v86 offset:3072
	ds_read_b128 v[120:123], v86 offset:4096
	ds_read_b128 v[124:127], v86 offset:5120
	ds_read_b128 v[128:131], v86 offset:6144
	ds_read_b128 v[132:135], v86 offset:7168
	global_load_lds_dwordx4 v[136:137], off
	v_lshl_add_u64 v[136:137], s[30:31], 0, v[78:79]
	s_add_i32 m0, s40, 0xe000
	s_nop 0
	global_load_lds_dwordx4 v[136:137], off
	s_waitcnt vmcnt(8)
	s_waitcnt lgkmcnt(0)
	s_barrier
	s_setprio 1
	s_waitcnt lgkmcnt(0)
	v_mfma_f32_16x16x32_bf16 v[60:63], v[88:91], v[104:107], v[60:63]
	v_mfma_f32_16x16x32_bf16 v[60:63], v[92:95], v[108:111], v[60:63]
	v_mfma_f32_16x16x32_bf16 v[56:59], v[96:99], v[104:107], v[56:59]
	v_mfma_f32_16x16x32_bf16 v[56:59], v[100:103], v[108:111], v[56:59]
	v_mfma_f32_16x16x32_bf16 v[48:51], v[96:99], v[112:115], v[48:51]
	v_mfma_f32_16x16x32_bf16 v[48:51], v[100:103], v[116:119], v[48:51]
	v_mfma_f32_16x16x32_bf16 v[52:55], v[88:91], v[112:115], v[52:55]
	v_mfma_f32_16x16x32_bf16 v[52:55], v[92:95], v[116:119], v[52:55]
	v_mfma_f32_16x16x32_bf16 v[44:47], v[88:91], v[120:123], v[44:47]
	v_mfma_f32_16x16x32_bf16 v[44:47], v[92:95], v[124:127], v[44:47]
	v_mfma_f32_16x16x32_bf16 v[40:43], v[96:99], v[120:123], v[40:43]
	v_mfma_f32_16x16x32_bf16 v[40:43], v[100:103], v[124:127], v[40:43]
	v_mfma_f32_16x16x32_bf16 v[32:35], v[96:99], v[128:131], v[32:35]
	v_mfma_f32_16x16x32_bf16 v[32:35], v[100:103], v[132:135], v[32:35]
	v_mfma_f32_16x16x32_bf16 v[36:39], v[88:91], v[128:131], v[36:39]
	v_mfma_f32_16x16x32_bf16 v[36:39], v[92:95], v[132:135], v[36:39]
	s_setprio 0
	s_setprio 1
	s_setprio 0
	s_barrier
	s_add_i32 s30, s56, s39
	v_lshl_add_u64 v[136:137], s[34:35], 0, v[66:67]
	s_mov_b32 m0, s30
	ds_read_b128 v[104:107], v86 offset:16384
	ds_read_b128 v[108:111], v86 offset:17408
	ds_read_b128 v[112:115], v86 offset:18432
	ds_read_b128 v[116:119], v86 offset:19456
	ds_read_b128 v[120:123], v86 offset:20480
	ds_read_b128 v[124:127], v86 offset:21504
	ds_read_b128 v[128:131], v86 offset:22528
	ds_read_b128 v[132:135], v86 offset:23552
	global_load_lds_dwordx4 v[136:137], off
	s_add_i32 m0, s30, 0x2000
	s_add_u32 s30, s34, 0x10000
	v_lshl_add_u64 v[138:139], s[34:35], 0, v[70:71]
	s_addc_u32 s31, s35, 0
	global_load_lds_dwordx4 v[138:139], off
	v_lshl_add_u64 v[140:141], s[30:31], 0, v[66:67]
	s_mov_b32 m0, s41
	v_lshl_add_u64 v[142:143], s[36:37], 0, v[68:69]
	global_load_lds_dwordx4 v[140:141], off
	v_lshl_add_u64 v[140:141], s[30:31], 0, v[70:71]
	s_mov_b32 m0, s42
	s_nop 0
	global_load_lds_dwordx4 v[140:141], off
	v_lshl_add_u64 v[140:141], s[36:37], 0, v[64:65]
	s_mov_b32 m0, s40
	s_nop 0
	global_load_lds_dwordx4 v[140:141], off
	s_mov_b32 m0, s43
	s_nop 0
	global_load_lds_dwordx4 v[142:143], off
	s_waitcnt vmcnt(8)
	s_waitcnt lgkmcnt(0)
	s_barrier
	s_setprio 1
	s_waitcnt lgkmcnt(0)
	v_mfma_f32_16x16x32_bf16 v[28:31], v[88:91], v[104:107], v[28:31]
	v_mfma_f32_16x16x32_bf16 v[28:31], v[92:95], v[108:111], v[28:31]
	v_mfma_f32_16x16x32_bf16 v[24:27], v[96:99], v[104:107], v[24:27]
	v_mfma_f32_16x16x32_bf16 v[24:27], v[100:103], v[108:111], v[24:27]
	v_mfma_f32_16x16x32_bf16 v[16:19], v[96:99], v[112:115], v[16:19]
	v_mfma_f32_16x16x32_bf16 v[16:19], v[100:103], v[116:119], v[16:19]
	v_mfma_f32_16x16x32_bf16 v[20:23], v[88:91], v[112:115], v[20:23]
	v_mfma_f32_16x16x32_bf16 v[20:23], v[92:95], v[116:119], v[20:23]
	v_mfma_f32_16x16x32_bf16 v[12:15], v[88:91], v[120:123], v[12:15]
	v_mfma_f32_16x16x32_bf16 v[12:15], v[92:95], v[124:127], v[12:15]
	v_mfma_f32_16x16x32_bf16 v[8:11], v[96:99], v[120:123], v[8:11]
	v_mfma_f32_16x16x32_bf16 v[8:11], v[100:103], v[124:127], v[8:11]
	v_mfma_f32_16x16x32_bf16 v[0:3], v[96:99], v[128:131], v[0:3]
	v_mfma_f32_16x16x32_bf16 v[0:3], v[100:103], v[132:135], v[0:3]
	v_mfma_f32_16x16x32_bf16 v[4:7], v[88:91], v[128:131], v[4:7]
	v_mfma_f32_16x16x32_bf16 v[4:7], v[92:95], v[132:135], v[4:7]
	s_setprio 0
	s_setprio 1
	s_setprio 0
	s_barrier
; #define PG8_STAGE(bufoff, gbase, voff) do { _Pragma("unroll") for (int _i = 0; _i < 2; ++_i) \
;         __builtin_amdgcn_global_load_lds((const unsigned*)((const char*)(gbase) + (voff)[_i]), (LAS unsigned*)(lds + (bufoff) + ldsw + _i * 8192), 16, 0, 0); } while (0)
; #define PG8_LDA(dst, b, h) do { _Pragma("unroll") for (int m = 0; m < 4; ++m) _Pragma("unroll") for (int k = 0; k < 2; ++k) dst[m][k] = *(const LAS bf16x8*)(lds + PG8_SA(b, h) + aoff + m * 2048 + k * 1024); } while (0)
; #define PG8_LDB(dst, b, h) do { _Pragma("unroll") for (int n = 0; n < 2; ++n) _Pragma("unroll") for (int k = 0; k < 2; ++k) dst[n][k] = *(const LAS bf16x8*)(lds + PG8_SB(b, h) + boff + n * 2048 + k * 1024); } while (0)
; #define PG8_MMA(ai, bj, At, Bt) do { __builtin_amdgcn_s_setprio(1); _Pragma("unroll") for (int m = 0; m < 4; ++m) _Pragma("unroll") for (int n = 0; n < 2; ++n) _Pragma("unroll") for (int k = 0; k < 2; ++k) \
;         acc[ai][bj][m][n] = __builtin_amdgcn_mfma_f32_16x16x32_bf16(Bt[n][k], At[m][k], acc[ai][bj][m][n], 0, 0, 0); __builtin_amdgcn_s_setprio(0); } while (0)
; #define PG8_WAIT_V(n) asm volatile("s_waitcnt vmcnt(" #n ")" ::: "memory")
; #define PG8_WAIT_L(n) asm volatile("s_waitcnt lgkmcnt(" #n ")" ::: "memory")
; #define PG8_BAR __builtin_amdgcn_s_barrier()
; #define PG8_SCHED __builtin_amdgcn_sched_barrier(0)
; template <class Epi>
; __device__ __forceinline__ void gemm_phase(LAS unsigned char* lds, const Gemm g, const StaticOrder& S, const Epi& E) {
;     ...
;             PG8_LDB(B0, 1, 0); PG8_LDB(B1, 1, 1); PG8_SCHED; PG8_LDA(At, 1, 0); PG8_STAGE(PG8_SA(0, 1), a2 + hstepA, voffA);
;             PG8_WAIT_V(8); PG8_WAIT_L(0); PG8_BAR; PG8_MMA(0, 0, At, B0); PG8_MMA(0, 1, At, B1); PG8_BAR; PG8_SCHED;
;             PG8_LDA(At, 1, 1); PG8_STAGE(PG8_SB(1, 0), b3, voffB); PG8_STAGE(PG8_SB(1, 1), b3 + hstepB, voffB); PG8_STAGE(PG8_SA(1, 0), a3, voffA);
;             PG8_WAIT_V(8); PG8_WAIT_L(0); PG8_BAR; PG8_MMA(1, 0, At, B0); PG8_MMA(1, 1, At, B1); PG8_BAR; PG8_SCHED;
;         }
	s_add_i32 s62, 0, 0x18000
	v_add_u32_e32 v87, s62, v84
	ds_read_b128 v[88:91], v87
	ds_read_b128 v[92:95], v87 offset:1024
	ds_read_b128 v[96:99], v87 offset:2048
	ds_read_b128 v[100:103], v87 offset:3072
	s_add_u32 s30, s36, 0x18000
	s_addc_u32 s31, s37, 0
	s_mov_b32 m0, s44
	v_lshl_add_u64 v[144:145], s[30:31], 0, v[64:65]
	ds_read_b128 v[104:107], v86 offset:32768
	ds_read_b128 v[108:111], v86 offset:33792
	ds_read_b128 v[112:115], v86 offset:34816
	ds_read_b128 v[116:119], v86 offset:35840
	ds_read_b128 v[120:123], v86 offset:36864
	ds_read_b128 v[124:127], v86 offset:37888
	ds_read_b128 v[128:131], v86 offset:38912
	ds_read_b128 v[132:135], v86 offset:39936
	global_load_lds_dwordx4 v[144:145], off
	v_lshl_add_u64 v[144:145], s[30:31], 0, v[68:69]
	s_mov_b32 m0, s45
	s_nop 0
	global_load_lds_dwordx4 v[144:145], off
	s_waitcnt vmcnt(8)
	s_waitcnt lgkmcnt(0)
	s_barrier
	s_setprio 1
	s_waitcnt lgkmcnt(0)
	v_mfma_f32_16x16x32_bf16 v[60:63], v[88:91], v[104:107], v[60:63]
	v_mfma_f32_16x16x32_bf16 v[60:63], v[92:95], v[108:111], v[60:63]
	v_mfma_f32_16x16x32_bf16 v[56:59], v[96:99], v[104:107], v[56:59]
	v_mfma_f32_16x16x32_bf16 v[56:59], v[100:103], v[108:111], v[56:59]
	v_mfma_f32_16x16x32_bf16 v[48:51], v[96:99], v[112:115], v[48:51]
	v_mfma_f32_16x16x32_bf16 v[48:51], v[100:103], v[116:119], v[48:51]
	v_mfma_f32_16x16x32_bf16 v[52:55], v[88:91], v[112:115], v[52:55]
	v_mfma_f32_16x16x32_bf16 v[52:55], v[92:95], v[116:119], v[52:55]
	v_mfma_f32_16x16x32_bf16 v[44:47], v[88:91], v[120:123], v[44:47]
	v_mfma_f32_16x16x32_bf16 v[44:47], v[92:95], v[124:127], v[44:47]
	v_mfma_f32_16x16x32_bf16 v[40:43], v[96:99], v[120:123], v[40:43]
	v_mfma_f32_16x16x32_bf16 v[40:43], v[100:103], v[124:127], v[40:43]
	v_mfma_f32_16x16x32_bf16 v[32:35], v[96:99], v[128:131], v[32:35]
	v_mfma_f32_16x16x32_bf16 v[32:35], v[100:103], v[132:135], v[32:35]
	v_mfma_f32_16x16x32_bf16 v[36:39], v[88:91], v[128:131], v[36:39]
	v_mfma_f32_16x16x32_bf16 v[36:39], v[92:95], v[132:135], v[36:39]
	s_setprio 0
	s_setprio 1
	s_setprio 0
	s_barrier
	s_add_i32 s30, s62, s39
	v_lshl_add_u64 v[136:137], v[136:137], 0, s[10:11]
	s_mov_b32 m0, s30
	ds_read_b128 v[104:107], v86 offset:49152
	ds_read_b128 v[108:111], v86 offset:50176
	ds_read_b128 v[112:115], v86 offset:51200
	ds_read_b128 v[116:119], v86 offset:52224
	ds_read_b128 v[120:123], v86 offset:53248
	ds_read_b128 v[124:127], v86 offset:54272
	ds_read_b128 v[128:131], v86 offset:55296
	ds_read_b128 v[132:135], v86 offset:56320
	global_load_lds_dwordx4 v[136:137], off
	s_add_i32 m0, s30, 0x2000
	s_add_u32 s30, s34, 0x10080
	v_lshl_add_u64 v[136:137], v[138:139], 0, s[10:11]
	s_addc_u32 s31, s35, 0
	global_load_lds_dwordx4 v[136:137], off
	v_lshl_add_u64 v[136:137], s[30:31], 0, v[66:67]
	s_mov_b32 m0, s49
	s_nop 0
	global_load_lds_dwordx4 v[136:137], off
	v_lshl_add_u64 v[136:137], s[30:31], 0, v[70:71]
	s_mov_b32 m0, s52
	s_nop 0
	global_load_lds_dwordx4 v[136:137], off
	v_lshl_add_u64 v[136:137], v[140:141], 0, s[10:11]
	s_mov_b32 m0, s47
	s_nop 0
	global_load_lds_dwordx4 v[136:137], off
	v_lshl_add_u64 v[136:137], v[142:143], 0, s[10:11]
	s_mov_b32 m0, s48
	s_nop 0
	global_load_lds_dwordx4 v[136:137], off
	s_waitcnt vmcnt(8)
	s_waitcnt lgkmcnt(0)
	s_barrier
	s_setprio 1
	s_waitcnt lgkmcnt(0)
	v_mfma_f32_16x16x32_bf16 v[28:31], v[88:91], v[104:107], v[28:31]
	v_mfma_f32_16x16x32_bf16 v[28:31], v[92:95], v[108:111], v[28:31]
	v_mfma_f32_16x16x32_bf16 v[24:27], v[96:99], v[104:107], v[24:27]
	v_mfma_f32_16x16x32_bf16 v[24:27], v[100:103], v[108:111], v[24:27]
	v_mfma_f32_16x16x32_bf16 v[16:19], v[96:99], v[112:115], v[16:19]
	v_mfma_f32_16x16x32_bf16 v[16:19], v[100:103], v[116:119], v[16:19]
	v_mfma_f32_16x16x32_bf16 v[20:23], v[88:91], v[112:115], v[20:23]
	v_mfma_f32_16x16x32_bf16 v[20:23], v[92:95], v[116:119], v[20:23]
	v_mfma_f32_16x16x32_bf16 v[12:15], v[88:91], v[120:123], v[12:15]
	v_mfma_f32_16x16x32_bf16 v[12:15], v[92:95], v[124:127], v[12:15]
	v_mfma_f32_16x16x32_bf16 v[8:11], v[96:99], v[120:123], v[8:11]
	v_mfma_f32_16x16x32_bf16 v[8:11], v[100:103], v[124:127], v[8:11]
	v_mfma_f32_16x16x32_bf16 v[0:3], v[96:99], v[128:131], v[0:3]
	v_mfma_f32_16x16x32_bf16 v[0:3], v[100:103], v[132:135], v[0:3]
	v_mfma_f32_16x16x32_bf16 v[4:7], v[88:91], v[128:131], v[4:7]
	v_mfma_f32_16x16x32_bf16 v[4:7], v[92:95], v[132:135], v[4:7]
	s_setprio 0
	s_setprio 1
	s_setprio 0
	s_barrier
	s_add_u32 s59, s59, 0x100
	s_addc_u32 s60, s60, 0
	s_cmp_ge_i32 s61, s46
	s_mov_b64 s[30:31], s[8:9]
	s_mov_b32 s34, s61
	s_cbranch_scc0 .LBB0_685

; #define PG8_STAGE(bufoff, gbase, voff) do { _Pragma("unroll") for (int _i = 0; _i < 2; ++_i) \
;         __builtin_amdgcn_global_load_lds((const unsigned*)((const char*)(gbase) + (voff)[_i]), (LAS unsigned*)(lds + (bufoff) + ldsw + _i * 8192), 16, 0, 0); } while (0)
; #define PG8_LDA(dst, b, h) do { _Pragma("unroll") for (int m = 0; m < 4; ++m) _Pragma("unroll") for (int k = 0; k < 2; ++k) dst[m][k] = *(const LAS bf16x8*)(lds + PG8_SA(b, h) + aoff + m * 2048 + k * 1024); } while (0)
; #define PG8_LDB(dst, b, h) do { _Pragma("unroll") for (int n = 0; n < 2; ++n) _Pragma("unroll") for (int k = 0; k < 2; ++k) dst[n][k] = *(const LAS bf16x8*)(lds + PG8_SB(b, h) + boff + n * 2048 + k * 1024); } while (0)
; #define PG8_MMA(ai, bj, At, Bt) do { __builtin_amdgcn_s_setprio(1); _Pragma("unroll") for (int m = 0; m < 4; ++m) _Pragma("unroll") for (int n = 0; n < 2; ++n) _Pragma("unroll") for (int k = 0; k < 2; ++k) \
;         acc[ai][bj][m][n] = __builtin_amdgcn_mfma_f32_16x16x32_bf16(Bt[n][k], At[m][k], acc[ai][bj][m][n], 0, 0, 0); __builtin_amdgcn_s_setprio(0); } while (0)
; #define PG8_WAIT_V(n) asm volatile("s_waitcnt vmcnt(" #n ")" ::: "memory")
; #define PG8_WAIT_L(n) asm volatile("s_waitcnt lgkmcnt(" #n ")" ::: "memory")
; #define PG8_BAR __builtin_amdgcn_s_barrier()
; #define PG8_SCHED __builtin_amdgcn_sched_barrier(0)
; template <class Epi>
; __device__ __forceinline__ void gemm_phase(LAS unsigned char* lds, const Gemm g, const StaticOrder& S, const Epi& E) {
;     ...
;             PG8_LDB(B0, 0, 0); PG8_LDB(B1, 0, 1); PG8_SCHED; PG8_LDA(At, 0, 0); PG8_STAGE(PG8_SA(1, 1), a1 + hstepA, voffA);
;             PG8_WAIT_V(8); PG8_WAIT_L(0); PG8_BAR; PG8_MMA(0, 0, At, B0); PG8_MMA(0, 1, At, B1); PG8_BAR; PG8_SCHED;
;             PG8_LDA(At, 0, 1); PG8_STAGE(PG8_SB(0, 0), b2, voffB); PG8_STAGE(PG8_SB(0, 1), b2 + hstepB, voffB); PG8_STAGE(PG8_SA(0, 0), a2, voffA);
;             PG8_WAIT_V(8); PG8_WAIT_L(0); PG8_BAR; PG8_MMA(1, 0, At, B0); PG8_MMA(1, 1, At, B1); PG8_BAR; PG8_SCHED;
.LBB0_834:
	ds_read_b128 v[156:159], v152
	ds_read_b128 v[160:163], v152 offset:1024
	ds_read_b128 v[164:167], v152 offset:2048
	ds_read_b128 v[168:171], v152 offset:3072
	ds_read_b128 v[172:175], v153
	ds_read_b128 v[176:179], v153 offset:1024
	ds_read_b128 v[180:183], v153 offset:2048
	ds_read_b128 v[184:187], v153 offset:3072
	s_add_i32 s49, s22, 2
	s_add_u32 s4, s0, 0x100
	s_addc_u32 s5, s1, 0
	s_cmp_eq_u32 s40, s22
	s_cselect_b32 s22, s20, s47
	s_cselect_b32 s25, s11, s5
	s_cselect_b32 s24, s10, s4
	s_cselect_b32 s23, s21, s48
	v_lshl_add_u64 v[224:225], s[0:1], 0, v[138:139]
	s_add_i32 m0, s29, 0xc000
	ds_read_b128 v[188:191], v154
	ds_read_b128 v[192:195], v154 offset:1024
	ds_read_b128 v[196:199], v154 offset:2048
	ds_read_b128 v[200:203], v154 offset:3072
	ds_read_b128 v[208:211], v154 offset:4096
	ds_read_b128 v[212:215], v154 offset:5120
	ds_read_b128 v[216:219], v154 offset:6144
	ds_read_b128 v[220:223], v154 offset:7168
	global_load_lds_dwordx4 v[224:225], off
	v_lshl_add_u64 v[224:225], s[0:1], 0, v[140:141]
	s_add_i32 m0, s29, 0xe000
	s_nop 0
	global_load_lds_dwordx4 v[224:225], off
	s_waitcnt vmcnt(8)
	s_waitcnt lgkmcnt(0)
	s_barrier
	s_setprio 1
	s_waitcnt lgkmcnt(0)
	v_mfma_f32_16x16x32_bf16 v[124:127], v[156:159], v[188:191], v[124:127]
	v_mfma_f32_16x16x32_bf16 v[124:127], v[160:163], v[192:195], v[124:127]
	v_mfma_f32_16x16x32_bf16 v[120:123], v[164:167], v[188:191], v[120:123]
	v_mfma_f32_16x16x32_bf16 v[120:123], v[168:171], v[192:195], v[120:123]
	v_mfma_f32_16x16x32_bf16 v[116:119], v[172:175], v[188:191], v[116:119]
	v_mfma_f32_16x16x32_bf16 v[116:119], v[176:179], v[192:195], v[116:119]
	v_mfma_f32_16x16x32_bf16 v[112:115], v[180:183], v[188:191], v[112:115]
	v_mfma_f32_16x16x32_bf16 v[112:115], v[184:187], v[192:195], v[112:115]
	v_mfma_f32_16x16x32_bf16 v[96:99], v[180:183], v[196:199], v[96:99]
	v_mfma_f32_16x16x32_bf16 v[96:99], v[184:187], v[200:203], v[96:99]
	v_mfma_f32_16x16x32_bf16 v[100:103], v[172:175], v[196:199], v[100:103]
	v_mfma_f32_16x16x32_bf16 v[100:103], v[176:179], v[200:203], v[100:103]
	v_mfma_f32_16x16x32_bf16 v[104:107], v[164:167], v[196:199], v[104:107]
	v_mfma_f32_16x16x32_bf16 v[104:107], v[168:171], v[200:203], v[104:107]
	v_mfma_f32_16x16x32_bf16 v[108:111], v[156:159], v[196:199], v[108:111]
	v_mfma_f32_16x16x32_bf16 v[108:111], v[160:163], v[200:203], v[108:111]
	s_setprio 0
	s_setprio 1
	v_mfma_f32_16x16x32_bf16 v[92:95], v[156:159], v[208:211], v[92:95]
	v_mfma_f32_16x16x32_bf16 v[92:95], v[160:163], v[212:215], v[92:95]
	v_mfma_f32_16x16x32_bf16 v[88:91], v[164:167], v[208:211], v[88:91]
	v_mfma_f32_16x16x32_bf16 v[88:91], v[168:171], v[212:215], v[88:91]
	v_mfma_f32_16x16x32_bf16 v[84:87], v[172:175], v[208:211], v[84:87]
	v_mfma_f32_16x16x32_bf16 v[84:87], v[176:179], v[212:215], v[84:87]
	v_mfma_f32_16x16x32_bf16 v[80:83], v[180:183], v[208:211], v[80:83]
	v_mfma_f32_16x16x32_bf16 v[80:83], v[184:187], v[212:215], v[80:83]
	v_mfma_f32_16x16x32_bf16 v[64:67], v[180:183], v[216:219], v[64:67]
	v_mfma_f32_16x16x32_bf16 v[64:67], v[184:187], v[220:223], v[64:67]
	v_mfma_f32_16x16x32_bf16 v[68:71], v[172:175], v[216:219], v[68:71]
	v_mfma_f32_16x16x32_bf16 v[68:71], v[176:179], v[220:223], v[68:71]
	v_mfma_f32_16x16x32_bf16 v[72:75], v[164:167], v[216:219], v[72:75]
	v_mfma_f32_16x16x32_bf16 v[72:75], v[168:171], v[220:223], v[72:75]
	v_mfma_f32_16x16x32_bf16 v[76:79], v[156:159], v[216:219], v[76:79]
	v_mfma_f32_16x16x32_bf16 v[76:79], v[160:163], v[220:223], v[76:79]
	s_setprio 0
	s_barrier
	s_add_i32 s0, s43, s28
	v_lshl_add_u64 v[224:225], s[22:23], 0, v[130:131]
	s_mov_b32 m0, s0
	ds_read_b128 v[188:191], v154 offset:16384
	ds_read_b128 v[192:195], v154 offset:17408
	ds_read_b128 v[196:199], v154 offset:18432
	ds_read_b128 v[200:203], v154 offset:19456
	ds_read_b128 v[208:211], v154 offset:20480
	ds_read_b128 v[212:215], v154 offset:21504
	ds_read_b128 v[216:219], v154 offset:22528
	ds_read_b128 v[220:223], v154 offset:23552
	global_load_lds_dwordx4 v[224:225], off
	s_add_i32 m0, s0, 0x2000
	s_add_u32 s0, s22, 0x18000
	v_lshl_add_u64 v[226:227], s[22:23], 0, v[134:135]
	s_addc_u32 s1, s23, 0
	s_add_i32 s50, s44, s28
	global_load_lds_dwordx4 v[226:227], off
	v_lshl_add_u64 v[230:231], s[0:1], 0, v[130:131]
	s_mov_b32 m0, s50
	v_lshl_add_u64 v[232:233], s[24:25], 0, v[132:133]
	global_load_lds_dwordx4 v[230:231], off
	v_lshl_add_u64 v[230:231], s[0:1], 0, v[134:135]
	s_add_i32 m0, s50, 0x2000
	s_nop 0
	global_load_lds_dwordx4 v[230:231], off
	v_lshl_add_u64 v[230:231], s[24:25], 0, v[128:129]
	s_mov_b32 m0, s29
	s_nop 0
	global_load_lds_dwordx4 v[230:231], off
	s_mov_b32 m0, s30
	s_nop 0
	global_load_lds_dwordx4 v[232:233], off
	s_waitcnt vmcnt(8)
	s_waitcnt lgkmcnt(0)
	s_barrier
; #define PG8_STAGE(bufoff, gbase, voff) do { _Pragma("unroll") for (int _i = 0; _i < 2; ++_i) \
;         __builtin_amdgcn_global_load_lds((const unsigned*)((const char*)(gbase) + (voff)[_i]), (LAS unsigned*)(lds + (bufoff) + ldsw + _i * 8192), 16, 0, 0); } while (0)
; #define PG8_LDA(dst, b, h) do { _Pragma("unroll") for (int m = 0; m < 4; ++m) _Pragma("unroll") for (int k = 0; k < 2; ++k) dst[m][k] = *(const LAS bf16x8*)(lds + PG8_SA(b, h) + aoff + m * 2048 + k * 1024); } while (0)
; #define PG8_LDB(dst, b, h) do { _Pragma("unroll") for (int n = 0; n < 2; ++n) _Pragma("unroll") for (int k = 0; k < 2; ++k) dst[n][k] = *(const LAS bf16x8*)(lds + PG8_SB(b, h) + boff + n * 2048 + k * 1024); } while (0)
; #define PG8_MMA(ai, bj, At, Bt) do { __builtin_amdgcn_s_setprio(1); _Pragma("unroll") for (int m = 0; m < 4; ++m) _Pragma("unroll") for (int n = 0; n < 2; ++n) _Pragma("unroll") for (int k = 0; k < 2; ++k) \
;         acc[ai][bj][m][n] = __builtin_amdgcn_mfma_f32_16x16x32_bf16(Bt[n][k], At[m][k], acc[ai][bj][m][n], 0, 0, 0); __builtin_amdgcn_s_setprio(0); } while (0)
; #define PG8_WAIT_V(n) asm volatile("s_waitcnt vmcnt(" #n ")" ::: "memory")
; #define PG8_WAIT_L(n) asm volatile("s_waitcnt lgkmcnt(" #n ")" ::: "memory")
; #define PG8_BAR __builtin_amdgcn_s_barrier()
; #define PG8_SCHED __builtin_amdgcn_sched_barrier(0)
; template <class Epi>
; __device__ __forceinline__ void gemm_phase(LAS unsigned char* lds, const Gemm g, const StaticOrder& S, const Epi& E) {
;     ...
;             PG8_WAIT_V(8); PG8_WAIT_L(0); PG8_BAR; PG8_MMA(1, 0, At, B0); PG8_MMA(1, 1, At, B1); PG8_BAR; PG8_SCHED;
;             PG8_LDB(B0, 1, 0); PG8_LDB(B1, 1, 1); PG8_SCHED; PG8_LDA(At, 1, 0); PG8_STAGE(PG8_SA(0, 1), a2 + hstepA, voffA);
;             PG8_WAIT_V(8); PG8_WAIT_L(0); PG8_BAR; PG8_MMA(0, 0, At, B0); PG8_MMA(0, 1, At, B1); PG8_BAR; PG8_SCHED;
	s_setprio 1
	s_waitcnt lgkmcnt(0)
	v_mfma_f32_16x16x32_bf16 v[60:63], v[156:159], v[188:191], v[60:63]
	v_mfma_f32_16x16x32_bf16 v[60:63], v[160:163], v[192:195], v[60:63]
	v_mfma_f32_16x16x32_bf16 v[56:59], v[164:167], v[188:191], v[56:59]
	v_mfma_f32_16x16x32_bf16 v[56:59], v[168:171], v[192:195], v[56:59]
	v_mfma_f32_16x16x32_bf16 v[52:55], v[172:175], v[188:191], v[52:55]
	v_mfma_f32_16x16x32_bf16 v[52:55], v[176:179], v[192:195], v[52:55]
	v_mfma_f32_16x16x32_bf16 v[48:51], v[180:183], v[188:191], v[48:51]
	v_mfma_f32_16x16x32_bf16 v[48:51], v[184:187], v[192:195], v[48:51]
	v_mfma_f32_16x16x32_bf16 v[32:35], v[180:183], v[196:199], v[32:35]
	v_mfma_f32_16x16x32_bf16 v[32:35], v[184:187], v[200:203], v[32:35]
	v_mfma_f32_16x16x32_bf16 v[36:39], v[172:175], v[196:199], v[36:39]
	v_mfma_f32_16x16x32_bf16 v[36:39], v[176:179], v[200:203], v[36:39]
	v_mfma_f32_16x16x32_bf16 v[40:43], v[164:167], v[196:199], v[40:43]
	v_mfma_f32_16x16x32_bf16 v[40:43], v[168:171], v[200:203], v[40:43]
	v_mfma_f32_16x16x32_bf16 v[44:47], v[156:159], v[196:199], v[44:47]
	v_mfma_f32_16x16x32_bf16 v[44:47], v[160:163], v[200:203], v[44:47]
	s_setprio 0
	s_setprio 1
	v_mfma_f32_16x16x32_bf16 v[28:31], v[156:159], v[208:211], v[28:31]
	v_mfma_f32_16x16x32_bf16 v[28:31], v[160:163], v[212:215], v[28:31]
	v_mfma_f32_16x16x32_bf16 v[24:27], v[164:167], v[208:211], v[24:27]
	v_mfma_f32_16x16x32_bf16 v[24:27], v[168:171], v[212:215], v[24:27]
	v_mfma_f32_16x16x32_bf16 v[20:23], v[172:175], v[208:211], v[20:23]
	v_mfma_f32_16x16x32_bf16 v[20:23], v[176:179], v[212:215], v[20:23]
	v_mfma_f32_16x16x32_bf16 v[16:19], v[180:183], v[208:211], v[16:19]
	v_mfma_f32_16x16x32_bf16 v[16:19], v[184:187], v[212:215], v[16:19]
	v_mfma_f32_16x16x32_bf16 v[0:3], v[180:183], v[216:219], v[0:3]
	v_mfma_f32_16x16x32_bf16 v[0:3], v[184:187], v[220:223], v[0:3]
	v_mfma_f32_16x16x32_bf16 v[4:7], v[172:175], v[216:219], v[4:7]
	v_mfma_f32_16x16x32_bf16 v[4:7], v[176:179], v[220:223], v[4:7]
	v_mfma_f32_16x16x32_bf16 v[8:11], v[164:167], v[216:219], v[8:11]
	v_mfma_f32_16x16x32_bf16 v[8:11], v[168:171], v[220:223], v[8:11]
	v_mfma_f32_16x16x32_bf16 v[12:15], v[156:159], v[216:219], v[12:15]
	v_mfma_f32_16x16x32_bf16 v[12:15], v[160:163], v[220:223], v[12:15]
	s_setprio 0
	s_barrier
	s_add_i32 s50, 0, 0x18000
	v_add_u32_e32 v136, s50, v149
	s_add_i32 s51, 0, 0x1c000
	ds_read_b128 v[156:159], v136
	ds_read_b128 v[160:163], v136 offset:1024
	ds_read_b128 v[164:167], v136 offset:2048
	ds_read_b128 v[168:171], v136 offset:3072
	v_add_u32_e32 v136, s51, v149
	ds_read_b128 v[172:175], v136
	ds_read_b128 v[176:179], v136 offset:1024
	ds_read_b128 v[180:183], v136 offset:2048
	ds_read_b128 v[184:187], v136 offset:3072
	s_add_u32 s0, s24, 0x18000
	s_addc_u32 s1, s25, 0
	s_mov_b32 m0, s31
	v_lshl_add_u64 v[234:235], s[0:1], 0, v[128:129]
	ds_read_b128 v[188:191], v154 offset:32768
	ds_read_b128 v[192:195], v154 offset:33792
	ds_read_b128 v[196:199], v154 offset:34816
	ds_read_b128 v[200:203], v154 offset:35840
	ds_read_b128 v[208:211], v154 offset:36864
	ds_read_b128 v[212:215], v154 offset:37888
	ds_read_b128 v[216:219], v154 offset:38912
	ds_read_b128 v[220:223], v154 offset:39936
	global_load_lds_dwordx4 v[234:235], off
	v_lshl_add_u64 v[234:235], s[0:1], 0, v[132:133]
	s_mov_b32 m0, s34
	s_nop 0
	global_load_lds_dwordx4 v[234:235], off
	s_waitcnt vmcnt(8)
	s_waitcnt lgkmcnt(0)
	s_barrier
	s_setprio 1
	s_waitcnt lgkmcnt(0)
	v_mfma_f32_16x16x32_bf16 v[124:127], v[156:159], v[188:191], v[124:127]
	v_mfma_f32_16x16x32_bf16 v[124:127], v[160:163], v[192:195], v[124:127]
	v_mfma_f32_16x16x32_bf16 v[120:123], v[164:167], v[188:191], v[120:123]
	v_mfma_f32_16x16x32_bf16 v[120:123], v[168:171], v[192:195], v[120:123]
	v_mfma_f32_16x16x32_bf16 v[116:119], v[172:175], v[188:191], v[116:119]
	v_mfma_f32_16x16x32_bf16 v[116:119], v[176:179], v[192:195], v[116:119]
	v_mfma_f32_16x16x32_bf16 v[112:115], v[180:183], v[188:191], v[112:115]
	v_mfma_f32_16x16x32_bf16 v[112:115], v[184:187], v[192:195], v[112:115]
	v_mfma_f32_16x16x32_bf16 v[96:99], v[180:183], v[196:199], v[96:99]
	v_mfma_f32_16x16x32_bf16 v[96:99], v[184:187], v[200:203], v[96:99]
	v_mfma_f32_16x16x32_bf16 v[100:103], v[172:175], v[196:199], v[100:103]
	v_mfma_f32_16x16x32_bf16 v[100:103], v[176:179], v[200:203], v[100:103]
	v_mfma_f32_16x16x32_bf16 v[104:107], v[164:167], v[196:199], v[104:107]
	v_mfma_f32_16x16x32_bf16 v[104:107], v[168:171], v[200:203], v[104:107]
	v_mfma_f32_16x16x32_bf16 v[108:111], v[156:159], v[196:199], v[108:111]
	v_mfma_f32_16x16x32_bf16 v[108:111], v[160:163], v[200:203], v[108:111]
	s_setprio 0
	s_setprio 1
	v_mfma_f32_16x16x32_bf16 v[92:95], v[156:159], v[208:211], v[92:95]
	v_mfma_f32_16x16x32_bf16 v[92:95], v[160:163], v[212:215], v[92:95]
	v_mfma_f32_16x16x32_bf16 v[88:91], v[164:167], v[208:211], v[88:91]
	v_mfma_f32_16x16x32_bf16 v[88:91], v[168:171], v[212:215], v[88:91]
	v_mfma_f32_16x16x32_bf16 v[84:87], v[172:175], v[208:211], v[84:87]
	v_mfma_f32_16x16x32_bf16 v[84:87], v[176:179], v[212:215], v[84:87]
	v_mfma_f32_16x16x32_bf16 v[80:83], v[180:183], v[208:211], v[80:83]
	v_mfma_f32_16x16x32_bf16 v[80:83], v[184:187], v[212:215], v[80:83]
	v_mfma_f32_16x16x32_bf16 v[64:67], v[180:183], v[216:219], v[64:67]
	v_mfma_f32_16x16x32_bf16 v[64:67], v[184:187], v[220:223], v[64:67]
	v_mfma_f32_16x16x32_bf16 v[68:71], v[172:175], v[216:219], v[68:71]
	v_mfma_f32_16x16x32_bf16 v[68:71], v[176:179], v[220:223], v[68:71]
	v_mfma_f32_16x16x32_bf16 v[72:75], v[164:167], v[216:219], v[72:75]
	v_mfma_f32_16x16x32_bf16 v[72:75], v[168:171], v[220:223], v[72:75]
	v_mfma_f32_16x16x32_bf16 v[76:79], v[156:159], v[216:219], v[76:79]
	v_mfma_f32_16x16x32_bf16 v[76:79], v[160:163], v[220:223], v[76:79]
	s_setprio 0
	s_barrier
; #define PG8_STAGE(bufoff, gbase, voff) do { _Pragma("unroll") for (int _i = 0; _i < 2; ++_i) \
;         __builtin_amdgcn_global_load_lds((const unsigned*)((const char*)(gbase) + (voff)[_i]), (LAS unsigned*)(lds + (bufoff) + ldsw + _i * 8192), 16, 0, 0); } while (0)
; #define PG8_LDA(dst, b, h) do { _Pragma("unroll") for (int m = 0; m < 4; ++m) _Pragma("unroll") for (int k = 0; k < 2; ++k) dst[m][k] = *(const LAS bf16x8*)(lds + PG8_SA(b, h) + aoff + m * 2048 + k * 1024); } while (0)
; #define PG8_MMA(ai, bj, At, Bt) do { __builtin_amdgcn_s_setprio(1); _Pragma("unroll") for (int m = 0; m < 4; ++m) _Pragma("unroll") for (int n = 0; n < 2; ++n) _Pragma("unroll") for (int k = 0; k < 2; ++k) \
;         acc[ai][bj][m][n] = __builtin_amdgcn_mfma_f32_16x16x32_bf16(Bt[n][k], At[m][k], acc[ai][bj][m][n], 0, 0, 0); __builtin_amdgcn_s_setprio(0); } while (0)
; #define PG8_WAIT_V(n) asm volatile("s_waitcnt vmcnt(" #n ")" ::: "memory")
; #define PG8_WAIT_L(n) asm volatile("s_waitcnt lgkmcnt(" #n ")" ::: "memory")
; #define PG8_BAR __builtin_amdgcn_s_barrier()
; #define PG8_SCHED __builtin_amdgcn_sched_barrier(0)
; template <class Epi>
; __device__ __forceinline__ void gemm_phase(LAS unsigned char* lds, const Gemm g, const StaticOrder& S, const Epi& E) {
;     ...
;             PG8_LDA(At, 1, 1); PG8_STAGE(PG8_SB(1, 0), b3, voffB); PG8_STAGE(PG8_SB(1, 1), b3 + hstepB, voffB); PG8_STAGE(PG8_SA(1, 0), a3, voffA);
;             PG8_WAIT_V(8); PG8_WAIT_L(0); PG8_BAR; PG8_MMA(1, 0, At, B0); PG8_MMA(1, 1, At, B1); PG8_BAR; PG8_SCHED;
;         }
	s_add_i32 s0, s50, s28
	v_lshl_add_u64 v[224:225], v[224:225], 0, s[14:15]
	s_mov_b32 m0, s0
	ds_read_b128 v[188:191], v154 offset:49152
	ds_read_b128 v[192:195], v154 offset:50176
	ds_read_b128 v[196:199], v154 offset:51200
	ds_read_b128 v[200:203], v154 offset:52224
	ds_read_b128 v[208:211], v154 offset:53248
	ds_read_b128 v[212:215], v154 offset:54272
	ds_read_b128 v[216:219], v154 offset:55296
	ds_read_b128 v[220:223], v154 offset:56320
	global_load_lds_dwordx4 v[224:225], off
	s_add_i32 m0, s0, 0x2000
	s_add_u32 s0, s22, 0x18080
	v_lshl_add_u64 v[224:225], v[226:227], 0, s[14:15]
	s_addc_u32 s1, s23, 0
	s_add_i32 s22, s51, s28
	global_load_lds_dwordx4 v[224:225], off
	v_lshl_add_u64 v[224:225], s[0:1], 0, v[130:131]
	s_mov_b32 m0, s22
	s_nop 0
	global_load_lds_dwordx4 v[224:225], off
	v_lshl_add_u64 v[224:225], s[0:1], 0, v[134:135]
	s_add_i32 m0, s22, 0x2000
	s_nop 0
	global_load_lds_dwordx4 v[224:225], off
	v_lshl_add_u64 v[224:225], v[230:231], 0, s[14:15]
	s_mov_b32 m0, s38
	s_nop 0
	global_load_lds_dwordx4 v[224:225], off
	v_lshl_add_u64 v[224:225], v[232:233], 0, s[14:15]
	s_mov_b32 m0, s39
	s_nop 0
	global_load_lds_dwordx4 v[224:225], off
	s_waitcnt vmcnt(8)
	s_waitcnt lgkmcnt(0)
	s_barrier
	s_setprio 1
	s_waitcnt lgkmcnt(0)
	v_mfma_f32_16x16x32_bf16 v[60:63], v[156:159], v[188:191], v[60:63]
	v_mfma_f32_16x16x32_bf16 v[60:63], v[160:163], v[192:195], v[60:63]
	v_mfma_f32_16x16x32_bf16 v[56:59], v[164:167], v[188:191], v[56:59]
	v_mfma_f32_16x16x32_bf16 v[56:59], v[168:171], v[192:195], v[56:59]
	v_mfma_f32_16x16x32_bf16 v[52:55], v[172:175], v[188:191], v[52:55]
	v_mfma_f32_16x16x32_bf16 v[52:55], v[176:179], v[192:195], v[52:55]
	v_mfma_f32_16x16x32_bf16 v[48:51], v[180:183], v[188:191], v[48:51]
	v_mfma_f32_16x16x32_bf16 v[48:51], v[184:187], v[192:195], v[48:51]
	v_mfma_f32_16x16x32_bf16 v[32:35], v[180:183], v[196:199], v[32:35]
	v_mfma_f32_16x16x32_bf16 v[32:35], v[184:187], v[200:203], v[32:35]
	v_mfma_f32_16x16x32_bf16 v[36:39], v[172:175], v[196:199], v[36:39]
	v_mfma_f32_16x16x32_bf16 v[36:39], v[176:179], v[200:203], v[36:39]
	v_mfma_f32_16x16x32_bf16 v[40:43], v[164:167], v[196:199], v[40:43]
	v_mfma_f32_16x16x32_bf16 v[40:43], v[168:171], v[200:203], v[40:43]
	v_mfma_f32_16x16x32_bf16 v[44:47], v[156:159], v[196:199], v[44:47]
	v_mfma_f32_16x16x32_bf16 v[44:47], v[160:163], v[200:203], v[44:47]
	s_setprio 0
	s_setprio 1
	v_mfma_f32_16x16x32_bf16 v[28:31], v[156:159], v[208:211], v[28:31]
	v_mfma_f32_16x16x32_bf16 v[28:31], v[160:163], v[212:215], v[28:31]
	v_mfma_f32_16x16x32_bf16 v[24:27], v[164:167], v[208:211], v[24:27]
	v_mfma_f32_16x16x32_bf16 v[24:27], v[168:171], v[212:215], v[24:27]
	v_mfma_f32_16x16x32_bf16 v[20:23], v[172:175], v[208:211], v[20:23]
	v_mfma_f32_16x16x32_bf16 v[20:23], v[176:179], v[212:215], v[20:23]
	v_mfma_f32_16x16x32_bf16 v[16:19], v[180:183], v[208:211], v[16:19]
	v_mfma_f32_16x16x32_bf16 v[16:19], v[184:187], v[212:215], v[16:19]
	v_mfma_f32_16x16x32_bf16 v[0:3], v[180:183], v[216:219], v[0:3]
	v_mfma_f32_16x16x32_bf16 v[0:3], v[184:187], v[220:223], v[0:3]
	v_mfma_f32_16x16x32_bf16 v[4:7], v[172:175], v[216:219], v[4:7]
	v_mfma_f32_16x16x32_bf16 v[4:7], v[176:179], v[220:223], v[4:7]
	v_mfma_f32_16x16x32_bf16 v[8:11], v[164:167], v[216:219], v[8:11]
	v_mfma_f32_16x16x32_bf16 v[8:11], v[168:171], v[220:223], v[8:11]
	v_mfma_f32_16x16x32_bf16 v[12:15], v[156:159], v[216:219], v[12:15]
	v_mfma_f32_16x16x32_bf16 v[12:15], v[160:163], v[220:223], v[12:15]
	s_setprio 0
	s_barrier
	s_add_u32 s47, s47, 0x100
	s_addc_u32 s48, s48, 0
	s_cmp_ge_i32 s49, s36
	s_mov_b64 s[0:1], s[4:5]
	s_mov_b32 s22, s49
	s_cbranch_scc0 .LBB0_834

; #define PG8_STAGE(bufoff, gbase, voff) do { _Pragma("unroll") for (int _i = 0; _i < 2; ++_i) \
;         __builtin_amdgcn_global_load_lds((const unsigned*)((const char*)(gbase) + (voff)[_i]), (LAS unsigned*)(lds + (bufoff) + ldsw + _i * 8192), 16, 0, 0); } while (0)
; #define PG8_LDA(dst, b, h) do { _Pragma("unroll") for (int m = 0; m < 4; ++m) _Pragma("unroll") for (int k = 0; k < 2; ++k) dst[m][k] = *(const LAS bf16x8*)(lds + PG8_SA(b, h) + aoff + m * 2048 + k * 1024); } while (0)
; #define PG8_LDB(dst, b, h) do { _Pragma("unroll") for (int n = 0; n < 2; ++n) _Pragma("unroll") for (int k = 0; k < 2; ++k) dst[n][k] = *(const LAS bf16x8*)(lds + PG8_SB(b, h) + boff + n * 2048 + k * 1024); } while (0)
; #define PG8_MMA(ai, bj, At, Bt) do { __builtin_amdgcn_s_setprio(1); _Pragma("unroll") for (int m = 0; m < 4; ++m) _Pragma("unroll") for (int n = 0; n < 2; ++n) _Pragma("unroll") for (int k = 0; k < 2; ++k) \
;         acc[ai][bj][m][n] = __builtin_amdgcn_mfma_f32_16x16x32_bf16(Bt[n][k], At[m][k], acc[ai][bj][m][n], 0, 0, 0); __builtin_amdgcn_s_setprio(0); } while (0)
; #define PG8_WAIT_V(n) asm volatile("s_waitcnt vmcnt(" #n ")" ::: "memory")
; #define PG8_WAIT_L(n) asm volatile("s_waitcnt lgkmcnt(" #n ")" ::: "memory")
; #define PG8_BAR __builtin_amdgcn_s_barrier()
; #define PG8_SCHED __builtin_amdgcn_sched_barrier(0)
; template <class Epi>
; __device__ __forceinline__ void gemm_phase(LAS unsigned char* lds, const Gemm g, const StaticOrder& S, const Epi& E) {
;     ...
;             PG8_LDB(B0, 0, 0); PG8_LDB(B1, 0, 1); PG8_SCHED; PG8_LDA(At, 0, 0); PG8_STAGE(PG8_SA(1, 1), a1 + hstepA, voffA);
;             PG8_WAIT_V(8); PG8_WAIT_L(0); PG8_BAR; PG8_MMA(0, 0, At, B0); PG8_MMA(0, 1, At, B1); PG8_BAR; PG8_SCHED;
;             PG8_LDA(At, 0, 1); PG8_STAGE(PG8_SB(0, 0), b2, voffB); PG8_STAGE(PG8_SB(0, 1), b2 + hstepB, voffB); PG8_STAGE(PG8_SA(0, 0), a2, voffA);
;             PG8_WAIT_V(8); PG8_WAIT_L(0); PG8_BAR; PG8_MMA(1, 0, At, B0); PG8_MMA(1, 1, At, B1); PG8_BAR; PG8_SCHED;
.LBB0_912:
	ds_read_b128 v[96:99], v230
	ds_read_b128 v[100:103], v230 offset:1024
	ds_read_b128 v[104:107], v230 offset:2048
	ds_read_b128 v[116:119], v230 offset:3072
	ds_read_b128 v[120:123], v231
	ds_read_b128 v[124:127], v231 offset:1024
	ds_read_b128 v[136:139], v231 offset:2048
	ds_read_b128 v[148:151], v231 offset:3072
	s_add_i32 s56, s24, 2
	s_add_u32 s25, s4, 0xfffc0080
	s_addc_u32 s26, s5, -1
	s_cmp_eq_u32 s44, s24
	s_cselect_b32 s24, s53, s54
	s_cselect_b32 s27, s17, s26
	s_cselect_b32 s26, s19, s25
	s_cselect_b32 s25, s33, s55
	v_lshl_add_u64 v[192:193], s[4:5], 0, v[220:221]
	s_add_i32 m0, s31, 0xc000
	ds_read_b128 v[160:163], v232
	ds_read_b128 v[164:167], v232 offset:1024
	ds_read_b128 v[168:171], v232 offset:2048
	ds_read_b128 v[172:175], v232 offset:3072
	ds_read_b128 v[176:179], v232 offset:4096
	ds_read_b128 v[180:183], v232 offset:5120
	ds_read_b128 v[184:187], v232 offset:6144
	ds_read_b128 v[188:191], v232 offset:7168
	global_load_lds_dwordx4 v[192:193], off
	v_lshl_add_u64 v[192:193], s[4:5], 0, v[222:223]
	s_add_i32 m0, s31, 0xe000
	s_nop 0
	global_load_lds_dwordx4 v[192:193], off
	s_waitcnt vmcnt(8)
	s_waitcnt lgkmcnt(0)
	s_barrier
	s_setprio 1
	s_waitcnt lgkmcnt(0)
	v_mfma_f32_16x16x32_bf16 v[156:159], v[96:99], v[160:163], v[156:159]
	v_mfma_f32_16x16x32_bf16 v[156:159], v[100:103], v[164:167], v[156:159]
	v_mfma_f32_16x16x32_bf16 v[152:155], v[104:107], v[160:163], v[152:155]
	v_mfma_f32_16x16x32_bf16 v[152:155], v[116:119], v[164:167], v[152:155]
	v_mfma_f32_16x16x32_bf16 v[144:147], v[120:123], v[160:163], v[144:147]
	v_mfma_f32_16x16x32_bf16 v[144:147], v[124:127], v[164:167], v[144:147]
	v_mfma_f32_16x16x32_bf16 v[140:143], v[136:139], v[160:163], v[140:143]
	v_mfma_f32_16x16x32_bf16 v[140:143], v[148:151], v[164:167], v[140:143]
	v_mfma_f32_16x16x32_bf16 v[108:111], v[136:139], v[168:171], v[108:111]
	v_mfma_f32_16x16x32_bf16 v[108:111], v[148:151], v[172:175], v[108:111]
	v_mfma_f32_16x16x32_bf16 v[112:115], v[120:123], v[168:171], v[112:115]
	v_mfma_f32_16x16x32_bf16 v[112:115], v[124:127], v[172:175], v[112:115]
	v_mfma_f32_16x16x32_bf16 v[128:131], v[104:107], v[168:171], v[128:131]
	v_mfma_f32_16x16x32_bf16 v[128:131], v[116:119], v[172:175], v[128:131]
	v_mfma_f32_16x16x32_bf16 v[132:135], v[96:99], v[168:171], v[132:135]
	v_mfma_f32_16x16x32_bf16 v[132:135], v[100:103], v[172:175], v[132:135]
	s_setprio 0
	s_setprio 1
	v_mfma_f32_16x16x32_bf16 v[92:95], v[96:99], v[176:179], v[92:95]
	v_mfma_f32_16x16x32_bf16 v[92:95], v[100:103], v[180:183], v[92:95]
	v_mfma_f32_16x16x32_bf16 v[88:91], v[104:107], v[176:179], v[88:91]
	v_mfma_f32_16x16x32_bf16 v[88:91], v[116:119], v[180:183], v[88:91]
	v_mfma_f32_16x16x32_bf16 v[84:87], v[120:123], v[176:179], v[84:87]
	v_mfma_f32_16x16x32_bf16 v[84:87], v[124:127], v[180:183], v[84:87]
	v_mfma_f32_16x16x32_bf16 v[80:83], v[136:139], v[176:179], v[80:83]
	v_mfma_f32_16x16x32_bf16 v[80:83], v[148:151], v[180:183], v[80:83]
	v_mfma_f32_16x16x32_bf16 v[64:67], v[136:139], v[184:187], v[64:67]
	v_mfma_f32_16x16x32_bf16 v[64:67], v[148:151], v[188:191], v[64:67]
	v_mfma_f32_16x16x32_bf16 v[68:71], v[120:123], v[184:187], v[68:71]
	v_mfma_f32_16x16x32_bf16 v[68:71], v[124:127], v[188:191], v[68:71]
	v_mfma_f32_16x16x32_bf16 v[72:75], v[104:107], v[184:187], v[72:75]
	v_mfma_f32_16x16x32_bf16 v[72:75], v[116:119], v[188:191], v[72:75]
	v_mfma_f32_16x16x32_bf16 v[76:79], v[96:99], v[184:187], v[76:79]
	v_mfma_f32_16x16x32_bf16 v[76:79], v[100:103], v[188:191], v[76:79]
	s_setprio 0
	s_barrier
	s_add_i32 s57, s47, s30
	v_lshl_add_u64 v[192:193], s[24:25], 0, v[210:211]
	s_mov_b32 m0, s57
	ds_read_b128 v[160:163], v232 offset:16384
	ds_read_b128 v[164:167], v232 offset:17408
	ds_read_b128 v[168:171], v232 offset:18432
	ds_read_b128 v[172:175], v232 offset:19456
	ds_read_b128 v[176:179], v232 offset:20480
	ds_read_b128 v[180:183], v232 offset:21504
	ds_read_b128 v[184:187], v232 offset:22528
	ds_read_b128 v[188:191], v232 offset:23552
	global_load_lds_dwordx4 v[192:193], off
	s_add_i32 m0, s57, 0x2000
	s_add_u32 s58, s24, 0x40000
	v_lshl_add_u64 v[194:195], s[24:25], 0, v[214:215]
	s_addc_u32 s59, s25, 0
	s_add_i32 s57, s48, s30
	global_load_lds_dwordx4 v[194:195], off
	v_lshl_add_u64 v[196:197], s[58:59], 0, v[210:211]
	s_mov_b32 m0, s57
	v_lshl_add_u64 v[198:199], s[26:27], 0, v[212:213]
	global_load_lds_dwordx4 v[196:197], off
	v_lshl_add_u64 v[196:197], s[58:59], 0, v[214:215]
	s_add_i32 m0, s57, 0x2000
	s_nop 0
	global_load_lds_dwordx4 v[196:197], off
	v_lshl_add_u64 v[196:197], s[26:27], 0, v[208:209]
	s_mov_b32 m0, s31
	s_nop 0
	global_load_lds_dwordx4 v[196:197], off
	s_mov_b32 m0, s34
	s_nop 0
	global_load_lds_dwordx4 v[198:199], off
	s_waitcnt vmcnt(8)
	s_waitcnt lgkmcnt(0)
	s_barrier
; #define PG8_STAGE(bufoff, gbase, voff) do { _Pragma("unroll") for (int _i = 0; _i < 2; ++_i) \
;         __builtin_amdgcn_global_load_lds((const unsigned*)((const char*)(gbase) + (voff)[_i]), (LAS unsigned*)(lds + (bufoff) + ldsw + _i * 8192), 16, 0, 0); } while (0)
; #define PG8_LDA(dst, b, h) do { _Pragma("unroll") for (int m = 0; m < 4; ++m) _Pragma("unroll") for (int k = 0; k < 2; ++k) dst[m][k] = *(const LAS bf16x8*)(lds + PG8_SA(b, h) + aoff + m * 2048 + k * 1024); } while (0)
; #define PG8_LDB(dst, b, h) do { _Pragma("unroll") for (int n = 0; n < 2; ++n) _Pragma("unroll") for (int k = 0; k < 2; ++k) dst[n][k] = *(const LAS bf16x8*)(lds + PG8_SB(b, h) + boff + n * 2048 + k * 1024); } while (0)
; #define PG8_MMA(ai, bj, At, Bt) do { __builtin_amdgcn_s_setprio(1); _Pragma("unroll") for (int m = 0; m < 4; ++m) _Pragma("unroll") for (int n = 0; n < 2; ++n) _Pragma("unroll") for (int k = 0; k < 2; ++k) \
;         acc[ai][bj][m][n] = __builtin_amdgcn_mfma_f32_16x16x32_bf16(Bt[n][k], At[m][k], acc[ai][bj][m][n], 0, 0, 0); __builtin_amdgcn_s_setprio(0); } while (0)
; #define PG8_WAIT_V(n) asm volatile("s_waitcnt vmcnt(" #n ")" ::: "memory")
; #define PG8_WAIT_L(n) asm volatile("s_waitcnt lgkmcnt(" #n ")" ::: "memory")
; #define PG8_BAR __builtin_amdgcn_s_barrier()
; #define PG8_SCHED __builtin_amdgcn_sched_barrier(0)
; template <class Epi>
; __device__ __forceinline__ void gemm_phase(LAS unsigned char* lds, const Gemm g, const StaticOrder& S, const Epi& E) {
;     ...
;             PG8_WAIT_V(8); PG8_WAIT_L(0); PG8_BAR; PG8_MMA(1, 0, At, B0); PG8_MMA(1, 1, At, B1); PG8_BAR; PG8_SCHED;
;             PG8_LDB(B0, 1, 0); PG8_LDB(B1, 1, 1); PG8_SCHED; PG8_LDA(At, 1, 0); PG8_STAGE(PG8_SA(0, 1), a2 + hstepA, voffA);
;             PG8_WAIT_V(8); PG8_WAIT_L(0); PG8_BAR; PG8_MMA(0, 0, At, B0); PG8_MMA(0, 1, At, B1); PG8_BAR; PG8_SCHED;
	s_setprio 1
	s_waitcnt lgkmcnt(0)
	v_mfma_f32_16x16x32_bf16 v[60:63], v[96:99], v[160:163], v[60:63]
	v_mfma_f32_16x16x32_bf16 v[60:63], v[100:103], v[164:167], v[60:63]
	v_mfma_f32_16x16x32_bf16 v[56:59], v[104:107], v[160:163], v[56:59]
	v_mfma_f32_16x16x32_bf16 v[56:59], v[116:119], v[164:167], v[56:59]
	v_mfma_f32_16x16x32_bf16 v[52:55], v[120:123], v[160:163], v[52:55]
	v_mfma_f32_16x16x32_bf16 v[52:55], v[124:127], v[164:167], v[52:55]
	v_mfma_f32_16x16x32_bf16 v[48:51], v[136:139], v[160:163], v[48:51]
	v_mfma_f32_16x16x32_bf16 v[48:51], v[148:151], v[164:167], v[48:51]
	v_mfma_f32_16x16x32_bf16 v[32:35], v[136:139], v[168:171], v[32:35]
	v_mfma_f32_16x16x32_bf16 v[32:35], v[148:151], v[172:175], v[32:35]
	v_mfma_f32_16x16x32_bf16 v[36:39], v[120:123], v[168:171], v[36:39]
	v_mfma_f32_16x16x32_bf16 v[36:39], v[124:127], v[172:175], v[36:39]
	v_mfma_f32_16x16x32_bf16 v[40:43], v[104:107], v[168:171], v[40:43]
	v_mfma_f32_16x16x32_bf16 v[40:43], v[116:119], v[172:175], v[40:43]
	v_mfma_f32_16x16x32_bf16 v[44:47], v[96:99], v[168:171], v[44:47]
	v_mfma_f32_16x16x32_bf16 v[44:47], v[100:103], v[172:175], v[44:47]
	s_setprio 0
	s_setprio 1
	v_mfma_f32_16x16x32_bf16 v[28:31], v[96:99], v[176:179], v[28:31]
	v_mfma_f32_16x16x32_bf16 v[28:31], v[100:103], v[180:183], v[28:31]
	v_mfma_f32_16x16x32_bf16 v[24:27], v[104:107], v[176:179], v[24:27]
	v_mfma_f32_16x16x32_bf16 v[24:27], v[116:119], v[180:183], v[24:27]
	v_mfma_f32_16x16x32_bf16 v[20:23], v[120:123], v[176:179], v[20:23]
	v_mfma_f32_16x16x32_bf16 v[20:23], v[124:127], v[180:183], v[20:23]
	v_mfma_f32_16x16x32_bf16 v[16:19], v[136:139], v[176:179], v[16:19]
	v_mfma_f32_16x16x32_bf16 v[16:19], v[148:151], v[180:183], v[16:19]
	v_mfma_f32_16x16x32_bf16 v[0:3], v[136:139], v[184:187], v[0:3]
	v_mfma_f32_16x16x32_bf16 v[0:3], v[148:151], v[188:191], v[0:3]
	v_mfma_f32_16x16x32_bf16 v[4:7], v[120:123], v[184:187], v[4:7]
	v_mfma_f32_16x16x32_bf16 v[4:7], v[124:127], v[188:191], v[4:7]
	v_mfma_f32_16x16x32_bf16 v[8:11], v[104:107], v[184:187], v[8:11]
	v_mfma_f32_16x16x32_bf16 v[8:11], v[116:119], v[188:191], v[8:11]
	v_mfma_f32_16x16x32_bf16 v[12:15], v[96:99], v[184:187], v[12:15]
	v_mfma_f32_16x16x32_bf16 v[12:15], v[100:103], v[188:191], v[12:15]
	s_setprio 0
	s_barrier
	s_add_i32 s57, 0, 0x18000
	s_add_i32 s58, 0, 0x1c000
	v_add_u32_e32 v116, s57, v229
	v_add_u32_e32 v148, s58, v229
	ds_read_b128 v[96:99], v116
	ds_read_b128 v[100:103], v116 offset:1024
	ds_read_b128 v[104:107], v116 offset:2048
	ds_read_b128 v[116:119], v116 offset:3072
	ds_read_b128 v[120:123], v148
	ds_read_b128 v[124:127], v148 offset:1024
	ds_read_b128 v[136:139], v148 offset:2048
	ds_read_b128 v[148:151], v148 offset:3072
	s_add_u32 s26, s26, 0x40000
	s_addc_u32 s27, s27, 0
	s_mov_b32 m0, s35
	v_lshl_add_u64 v[200:201], s[26:27], 0, v[208:209]
	ds_read_b128 v[160:163], v232 offset:32768
	ds_read_b128 v[164:167], v232 offset:33792
	ds_read_b128 v[168:171], v232 offset:34816
	ds_read_b128 v[172:175], v232 offset:35840
	ds_read_b128 v[176:179], v232 offset:36864
	ds_read_b128 v[180:183], v232 offset:37888
	ds_read_b128 v[184:187], v232 offset:38912
	ds_read_b128 v[188:191], v232 offset:39936
	global_load_lds_dwordx4 v[200:201], off
	v_lshl_add_u64 v[200:201], s[26:27], 0, v[212:213]
	s_mov_b32 m0, s36
	s_nop 0
	global_load_lds_dwordx4 v[200:201], off
	s_waitcnt vmcnt(8)
	s_waitcnt lgkmcnt(0)
	s_barrier
	s_setprio 1
	s_waitcnt lgkmcnt(0)
	v_mfma_f32_16x16x32_bf16 v[156:159], v[96:99], v[160:163], v[156:159]
	v_mfma_f32_16x16x32_bf16 v[156:159], v[100:103], v[164:167], v[156:159]
	v_mfma_f32_16x16x32_bf16 v[152:155], v[104:107], v[160:163], v[152:155]
	v_mfma_f32_16x16x32_bf16 v[152:155], v[116:119], v[164:167], v[152:155]
	v_mfma_f32_16x16x32_bf16 v[144:147], v[120:123], v[160:163], v[144:147]
	v_mfma_f32_16x16x32_bf16 v[144:147], v[124:127], v[164:167], v[144:147]
	v_mfma_f32_16x16x32_bf16 v[140:143], v[136:139], v[160:163], v[140:143]
	v_mfma_f32_16x16x32_bf16 v[140:143], v[148:151], v[164:167], v[140:143]
	v_mfma_f32_16x16x32_bf16 v[108:111], v[136:139], v[168:171], v[108:111]
	v_mfma_f32_16x16x32_bf16 v[108:111], v[148:151], v[172:175], v[108:111]
	v_mfma_f32_16x16x32_bf16 v[112:115], v[120:123], v[168:171], v[112:115]
	v_mfma_f32_16x16x32_bf16 v[112:115], v[124:127], v[172:175], v[112:115]
	v_mfma_f32_16x16x32_bf16 v[128:131], v[104:107], v[168:171], v[128:131]
	v_mfma_f32_16x16x32_bf16 v[128:131], v[116:119], v[172:175], v[128:131]
	v_mfma_f32_16x16x32_bf16 v[132:135], v[96:99], v[168:171], v[132:135]
	v_mfma_f32_16x16x32_bf16 v[132:135], v[100:103], v[172:175], v[132:135]
	s_setprio 0
	s_setprio 1
	v_mfma_f32_16x16x32_bf16 v[92:95], v[96:99], v[176:179], v[92:95]
	v_mfma_f32_16x16x32_bf16 v[92:95], v[100:103], v[180:183], v[92:95]
	v_mfma_f32_16x16x32_bf16 v[88:91], v[104:107], v[176:179], v[88:91]
	v_mfma_f32_16x16x32_bf16 v[88:91], v[116:119], v[180:183], v[88:91]
	v_mfma_f32_16x16x32_bf16 v[84:87], v[120:123], v[176:179], v[84:87]
	v_mfma_f32_16x16x32_bf16 v[84:87], v[124:127], v[180:183], v[84:87]
	v_mfma_f32_16x16x32_bf16 v[80:83], v[136:139], v[176:179], v[80:83]
	v_mfma_f32_16x16x32_bf16 v[80:83], v[148:151], v[180:183], v[80:83]
	v_mfma_f32_16x16x32_bf16 v[64:67], v[136:139], v[184:187], v[64:67]
	v_mfma_f32_16x16x32_bf16 v[64:67], v[148:151], v[188:191], v[64:67]
	v_mfma_f32_16x16x32_bf16 v[68:71], v[120:123], v[184:187], v[68:71]
	v_mfma_f32_16x16x32_bf16 v[68:71], v[124:127], v[188:191], v[68:71]
	v_mfma_f32_16x16x32_bf16 v[72:75], v[104:107], v[184:187], v[72:75]
	v_mfma_f32_16x16x32_bf16 v[72:75], v[116:119], v[188:191], v[72:75]
	v_mfma_f32_16x16x32_bf16 v[76:79], v[96:99], v[184:187], v[76:79]
	v_mfma_f32_16x16x32_bf16 v[76:79], v[100:103], v[188:191], v[76:79]
	s_setprio 0
	s_barrier
; #define PG8_STAGE(bufoff, gbase, voff) do { _Pragma("unroll") for (int _i = 0; _i < 2; ++_i) \
;         __builtin_amdgcn_global_load_lds((const unsigned*)((const char*)(gbase) + (voff)[_i]), (LAS unsigned*)(lds + (bufoff) + ldsw + _i * 8192), 16, 0, 0); } while (0)
; #define PG8_LDA(dst, b, h) do { _Pragma("unroll") for (int m = 0; m < 4; ++m) _Pragma("unroll") for (int k = 0; k < 2; ++k) dst[m][k] = *(const LAS bf16x8*)(lds + PG8_SA(b, h) + aoff + m * 2048 + k * 1024); } while (0)
; #define PG8_MMA(ai, bj, At, Bt) do { __builtin_amdgcn_s_setprio(1); _Pragma("unroll") for (int m = 0; m < 4; ++m) _Pragma("unroll") for (int n = 0; n < 2; ++n) _Pragma("unroll") for (int k = 0; k < 2; ++k) \
;         acc[ai][bj][m][n] = __builtin_amdgcn_mfma_f32_16x16x32_bf16(Bt[n][k], At[m][k], acc[ai][bj][m][n], 0, 0, 0); __builtin_amdgcn_s_setprio(0); } while (0)
; #define PG8_WAIT_V(n) asm volatile("s_waitcnt vmcnt(" #n ")" ::: "memory")
; #define PG8_WAIT_L(n) asm volatile("s_waitcnt lgkmcnt(" #n ")" ::: "memory")
; #define PG8_BAR __builtin_amdgcn_s_barrier()
; #define PG8_SCHED __builtin_amdgcn_sched_barrier(0)
; template <class Epi>
; __device__ __forceinline__ void gemm_phase(LAS unsigned char* lds, const Gemm g, const StaticOrder& S, const Epi& E) {
;     ...
;             PG8_LDA(At, 1, 1); PG8_STAGE(PG8_SB(1, 0), b3, voffB); PG8_STAGE(PG8_SB(1, 1), b3 + hstepB, voffB); PG8_STAGE(PG8_SA(1, 0), a3, voffA);
;             PG8_WAIT_V(8); PG8_WAIT_L(0); PG8_BAR; PG8_MMA(1, 0, At, B0); PG8_MMA(1, 1, At, B1); PG8_BAR; PG8_SCHED;
;         }
	s_add_i32 s26, s57, s30
	v_lshl_add_u64 v[192:193], v[192:193], 0, s[10:11]
	s_mov_b32 m0, s26
	ds_read_b128 v[160:163], v232 offset:49152
	ds_read_b128 v[164:167], v232 offset:50176
	ds_read_b128 v[168:171], v232 offset:51200
	ds_read_b128 v[172:175], v232 offset:52224
	ds_read_b128 v[176:179], v232 offset:53248
	ds_read_b128 v[180:183], v232 offset:54272
	ds_read_b128 v[184:187], v232 offset:55296
	ds_read_b128 v[188:191], v232 offset:56320
	global_load_lds_dwordx4 v[192:193], off
	s_add_i32 m0, s26, 0x2000
	s_add_u32 s24, s24, 0x40080
	v_lshl_add_u64 v[192:193], v[194:195], 0, s[10:11]
	s_addc_u32 s25, s25, 0
	s_add_i32 s26, s58, s30
	global_load_lds_dwordx4 v[192:193], off
	v_lshl_add_u64 v[192:193], s[24:25], 0, v[210:211]
	s_mov_b32 m0, s26
	s_nop 0
	global_load_lds_dwordx4 v[192:193], off
	v_lshl_add_u64 v[192:193], s[24:25], 0, v[214:215]
	s_add_i32 m0, s26, 0x2000
	s_nop 0
	global_load_lds_dwordx4 v[192:193], off
	v_lshl_add_u64 v[192:193], v[196:197], 0, s[10:11]
	s_mov_b32 m0, s40
	s_nop 0
	global_load_lds_dwordx4 v[192:193], off
	v_lshl_add_u64 v[192:193], v[198:199], 0, s[10:11]
	s_mov_b32 m0, s41
	s_nop 0
	global_load_lds_dwordx4 v[192:193], off
	s_waitcnt vmcnt(8)
	s_waitcnt lgkmcnt(0)
	s_barrier
	s_setprio 1
	s_waitcnt lgkmcnt(0)
	v_mfma_f32_16x16x32_bf16 v[60:63], v[96:99], v[160:163], v[60:63]
	v_mfma_f32_16x16x32_bf16 v[60:63], v[100:103], v[164:167], v[60:63]
	v_mfma_f32_16x16x32_bf16 v[56:59], v[104:107], v[160:163], v[56:59]
	v_mfma_f32_16x16x32_bf16 v[56:59], v[116:119], v[164:167], v[56:59]
	v_mfma_f32_16x16x32_bf16 v[52:55], v[120:123], v[160:163], v[52:55]
	v_mfma_f32_16x16x32_bf16 v[52:55], v[124:127], v[164:167], v[52:55]
	v_mfma_f32_16x16x32_bf16 v[48:51], v[136:139], v[160:163], v[48:51]
	v_mfma_f32_16x16x32_bf16 v[48:51], v[148:151], v[164:167], v[48:51]
	v_mfma_f32_16x16x32_bf16 v[32:35], v[136:139], v[168:171], v[32:35]
	v_mfma_f32_16x16x32_bf16 v[32:35], v[148:151], v[172:175], v[32:35]
	v_mfma_f32_16x16x32_bf16 v[36:39], v[120:123], v[168:171], v[36:39]
	v_mfma_f32_16x16x32_bf16 v[36:39], v[124:127], v[172:175], v[36:39]
	v_mfma_f32_16x16x32_bf16 v[40:43], v[104:107], v[168:171], v[40:43]
	v_mfma_f32_16x16x32_bf16 v[40:43], v[116:119], v[172:175], v[40:43]
	v_mfma_f32_16x16x32_bf16 v[44:47], v[96:99], v[168:171], v[44:47]
	v_mfma_f32_16x16x32_bf16 v[44:47], v[100:103], v[172:175], v[44:47]
	s_setprio 0
	s_setprio 1
	v_mfma_f32_16x16x32_bf16 v[28:31], v[96:99], v[176:179], v[28:31]
	v_mfma_f32_16x16x32_bf16 v[28:31], v[100:103], v[180:183], v[28:31]
	v_mfma_f32_16x16x32_bf16 v[24:27], v[104:107], v[176:179], v[24:27]
	v_mfma_f32_16x16x32_bf16 v[24:27], v[116:119], v[180:183], v[24:27]
	v_mfma_f32_16x16x32_bf16 v[20:23], v[120:123], v[176:179], v[20:23]
	v_mfma_f32_16x16x32_bf16 v[20:23], v[124:127], v[180:183], v[20:23]
	v_mfma_f32_16x16x32_bf16 v[16:19], v[136:139], v[176:179], v[16:19]
	v_mfma_f32_16x16x32_bf16 v[16:19], v[148:151], v[180:183], v[16:19]
	v_mfma_f32_16x16x32_bf16 v[0:3], v[136:139], v[184:187], v[0:3]
	v_mfma_f32_16x16x32_bf16 v[0:3], v[148:151], v[188:191], v[0:3]
	v_mfma_f32_16x16x32_bf16 v[4:7], v[120:123], v[184:187], v[4:7]
	v_mfma_f32_16x16x32_bf16 v[4:7], v[124:127], v[188:191], v[4:7]
	v_mfma_f32_16x16x32_bf16 v[8:11], v[104:107], v[184:187], v[8:11]
	v_mfma_f32_16x16x32_bf16 v[8:11], v[116:119], v[188:191], v[8:11]
	v_mfma_f32_16x16x32_bf16 v[12:15], v[96:99], v[184:187], v[12:15]
	v_mfma_f32_16x16x32_bf16 v[12:15], v[100:103], v[188:191], v[12:15]
	s_setprio 0
	s_barrier
	s_add_u32 s4, s4, 0x100
	s_addc_u32 s5, s5, 0
	s_add_u32 s54, s54, 0x100
	s_addc_u32 s55, s55, 0
	s_cmp_ge_i32 s56, s39
	s_mov_b32 s24, s56
	s_cbranch_scc0 .LBB0_912

; #define PG8_STAGE(bufoff, gbase, voff) do { _Pragma("unroll") for (int _i = 0; _i < 2; ++_i) \
;         __builtin_amdgcn_global_load_lds((const unsigned*)((const char*)(gbase) + (voff)[_i]), (LAS unsigned*)(lds + (bufoff) + ldsw + _i * 8192), 16, 0, 0); } while (0)
; #define PG8_LDA(dst, b, h) do { _Pragma("unroll") for (int m = 0; m < 4; ++m) _Pragma("unroll") for (int k = 0; k < 2; ++k) dst[m][k] = *(const LAS bf16x8*)(lds + PG8_SA(b, h) + aoff + m * 2048 + k * 1024); } while (0)
; #define PG8_LDB(dst, b, h) do { _Pragma("unroll") for (int n = 0; n < 2; ++n) _Pragma("unroll") for (int k = 0; k < 2; ++k) dst[n][k] = *(const LAS bf16x8*)(lds + PG8_SB(b, h) + boff + n * 2048 + k * 1024); } while (0)
; #define PG8_MMA(ai, bj, At, Bt) do { __builtin_amdgcn_s_setprio(1); _Pragma("unroll") for (int m = 0; m < 4; ++m) _Pragma("unroll") for (int n = 0; n < 2; ++n) _Pragma("unroll") for (int k = 0; k < 2; ++k) \
;         acc[ai][bj][m][n] = __builtin_amdgcn_mfma_f32_16x16x32_bf16(Bt[n][k], At[m][k], acc[ai][bj][m][n], 0, 0, 0); __builtin_amdgcn_s_setprio(0); } while (0)
; #define PG8_WAIT_V(n) asm volatile("s_waitcnt vmcnt(" #n ")" ::: "memory")
; #define PG8_WAIT_L(n) asm volatile("s_waitcnt lgkmcnt(" #n ")" ::: "memory")
; #define PG8_BAR __builtin_amdgcn_s_barrier()
; #define PG8_SCHED __builtin_amdgcn_sched_barrier(0)
; template <class Epi>
; __device__ __forceinline__ void gemm_phase(LAS unsigned char* lds, const Gemm g, const StaticOrder& S, const Epi& E) {
;     ...
;             const char* a2 = last ? nA : cA + (size_t)(t + 2) * kstep; const char* b2 = last ? nB : cB + (size_t)(t + 2) * kstep;
;             const char* a3 = a2 + kstep; const char* b3 = b2 + kstep;
;             PG8_LDB(B0, 0, 0); PG8_LDB(B1, 0, 1); PG8_SCHED; PG8_LDA(At, 0, 0); PG8_STAGE(PG8_SA(1, 1), a1 + hstepA, voffA);
;             PG8_WAIT_V(8); PG8_WAIT_L(0); PG8_BAR; PG8_MMA(0, 0, At, B0); PG8_MMA(0, 1, At, B1); PG8_BAR; PG8_SCHED;
;             PG8_LDA(At, 0, 1); PG8_STAGE(PG8_SB(0, 0), b2, voffB); PG8_STAGE(PG8_SB(0, 1), b2 + hstepB, voffB); PG8_STAGE(PG8_SA(0, 0), a2, voffA);
;             PG8_WAIT_V(8); PG8_WAIT_L(0); PG8_BAR; PG8_MMA(1, 0, At, B0); PG8_MMA(1, 1, At, B1); PG8_BAR; PG8_SCHED;
.LBB0_1046:
	ds_read_b128 v[128:131], v185
	ds_read_b128 v[132:135], v185 offset:1024
	ds_read_b128 v[136:139], v185 offset:2048
	ds_read_b128 v[140:143], v185 offset:3072
	ds_read_b128 v[144:147], v186
	ds_read_b128 v[148:151], v186 offset:1024
	ds_read_b128 v[152:155], v186 offset:2048
	ds_read_b128 v[156:159], v186 offset:3072
	s_add_i32 s73, s46, 2
	s_add_u32 s47, s12, 0xfff80080
	s_addc_u32 s48, s13, -1
	s_cmp_eq_u32 s62, s46
	s_cselect_b32 s46, s41, s71
	s_cselect_b32 s49, s1, s48
	s_cselect_b32 s48, s33, s47
	s_cselect_b32 s47, s39, s72
	v_lshl_add_u64 v[182:183], s[12:13], 0, v[174:175]
	s_add_i32 m0, s5, 0xc000
	ds_read_b128 v[190:193], v187
	ds_read_b128 v[194:197], v187 offset:1024
	ds_read_b128 v[198:201], v187 offset:2048
	ds_read_b128 v[208:211], v187 offset:3072
	ds_read_b128 v[212:215], v187 offset:4096
	ds_read_b128 v[216:219], v187 offset:5120
	ds_read_b128 v[220:223], v187 offset:6144
	ds_read_b128 v[224:227], v187 offset:7168
	global_load_lds_dwordx4 v[182:183], off
	v_lshl_add_u64 v[182:183], s[12:13], 0, v[176:177]
	s_add_i32 m0, s5, 0xe000
	s_nop 0
	global_load_lds_dwordx4 v[182:183], off
	s_waitcnt vmcnt(8)
	s_waitcnt lgkmcnt(0)
	s_barrier
	s_setprio 1
	s_waitcnt lgkmcnt(0)
	v_mfma_f32_16x16x32_bf16 v[120:123], v[128:131], v[190:193], v[120:123]
	v_mfma_f32_16x16x32_bf16 v[120:123], v[132:135], v[194:197], v[120:123]
	v_mfma_f32_16x16x32_bf16 v[124:127], v[136:139], v[190:193], v[124:127]
	v_mfma_f32_16x16x32_bf16 v[124:127], v[140:143], v[194:197], v[124:127]
	v_mfma_f32_16x16x32_bf16 v[116:119], v[144:147], v[190:193], v[116:119]
	v_mfma_f32_16x16x32_bf16 v[116:119], v[148:151], v[194:197], v[116:119]
	v_mfma_f32_16x16x32_bf16 v[112:115], v[152:155], v[190:193], v[112:115]
	v_mfma_f32_16x16x32_bf16 v[112:115], v[156:159], v[194:197], v[112:115]
	v_mfma_f32_16x16x32_bf16 v[96:99], v[152:155], v[198:201], v[96:99]
	v_mfma_f32_16x16x32_bf16 v[96:99], v[156:159], v[208:211], v[96:99]
	v_mfma_f32_16x16x32_bf16 v[100:103], v[144:147], v[198:201], v[100:103]
	v_mfma_f32_16x16x32_bf16 v[100:103], v[148:151], v[208:211], v[100:103]
	v_mfma_f32_16x16x32_bf16 v[104:107], v[136:139], v[198:201], v[104:107]
	v_mfma_f32_16x16x32_bf16 v[104:107], v[140:143], v[208:211], v[104:107]
	v_mfma_f32_16x16x32_bf16 v[108:111], v[128:131], v[198:201], v[108:111]
	v_mfma_f32_16x16x32_bf16 v[108:111], v[132:135], v[208:211], v[108:111]
	s_setprio 0
	s_setprio 1
	v_mfma_f32_16x16x32_bf16 v[92:95], v[128:131], v[212:215], v[92:95]
	v_mfma_f32_16x16x32_bf16 v[92:95], v[132:135], v[216:219], v[92:95]
	v_mfma_f32_16x16x32_bf16 v[88:91], v[136:139], v[212:215], v[88:91]
	v_mfma_f32_16x16x32_bf16 v[88:91], v[140:143], v[216:219], v[88:91]
	v_mfma_f32_16x16x32_bf16 v[84:87], v[144:147], v[212:215], v[84:87]
	v_mfma_f32_16x16x32_bf16 v[84:87], v[148:151], v[216:219], v[84:87]
	v_mfma_f32_16x16x32_bf16 v[80:83], v[152:155], v[212:215], v[80:83]
	v_mfma_f32_16x16x32_bf16 v[80:83], v[156:159], v[216:219], v[80:83]
	v_mfma_f32_16x16x32_bf16 v[64:67], v[152:155], v[220:223], v[64:67]
	v_mfma_f32_16x16x32_bf16 v[64:67], v[156:159], v[224:227], v[64:67]
	v_mfma_f32_16x16x32_bf16 v[68:71], v[144:147], v[220:223], v[68:71]
	v_mfma_f32_16x16x32_bf16 v[68:71], v[148:151], v[224:227], v[68:71]
	v_mfma_f32_16x16x32_bf16 v[72:75], v[136:139], v[220:223], v[72:75]
	v_mfma_f32_16x16x32_bf16 v[72:75], v[140:143], v[224:227], v[72:75]
	v_mfma_f32_16x16x32_bf16 v[76:79], v[128:131], v[220:223], v[76:79]
	v_mfma_f32_16x16x32_bf16 v[76:79], v[132:135], v[224:227], v[76:79]
	s_setprio 0
	s_barrier
	s_add_i32 s76, s65, s54
	v_lshl_add_u64 v[182:183], s[46:47], 0, v[162:163]
	s_mov_b32 m0, s76
	ds_read_b128 v[190:193], v187 offset:16384
	ds_read_b128 v[194:197], v187 offset:17408
	ds_read_b128 v[198:201], v187 offset:18432
	ds_read_b128 v[208:211], v187 offset:19456
	ds_read_b128 v[212:215], v187 offset:20480
	ds_read_b128 v[216:219], v187 offset:21504
	ds_read_b128 v[220:223], v187 offset:22528
	ds_read_b128 v[224:227], v187 offset:23552
	global_load_lds_dwordx4 v[182:183], off
	s_add_i32 m0, s76, 0x2000
	s_add_u32 s76, s46, 0x80000
	v_lshl_add_u64 v[202:203], s[46:47], 0, v[166:167]
	s_addc_u32 s77, s47, 0
	s_add_i32 s78, s66, s54
	global_load_lds_dwordx4 v[202:203], off
	v_lshl_add_u64 v[230:231], s[76:77], 0, v[162:163]
	s_mov_b32 m0, s78
	v_lshl_add_u64 v[232:233], s[48:49], 0, v[164:165]
	global_load_lds_dwordx4 v[230:231], off
	v_lshl_add_u64 v[230:231], s[76:77], 0, v[166:167]
	s_add_i32 m0, s78, 0x2000
	s_nop 0
	global_load_lds_dwordx4 v[230:231], off
	v_lshl_add_u64 v[230:231], s[48:49], 0, v[160:161]
	s_mov_b32 m0, s5
	s_nop 0
	global_load_lds_dwordx4 v[230:231], off
	s_mov_b32 m0, s55
	s_nop 0
	global_load_lds_dwordx4 v[232:233], off
	s_waitcnt vmcnt(8)
	s_waitcnt lgkmcnt(0)
	s_barrier
; #define PG8_STAGE(bufoff, gbase, voff) do { _Pragma("unroll") for (int _i = 0; _i < 2; ++_i) \
;         __builtin_amdgcn_global_load_lds((const unsigned*)((const char*)(gbase) + (voff)[_i]), (LAS unsigned*)(lds + (bufoff) + ldsw + _i * 8192), 16, 0, 0); } while (0)
; #define PG8_LDA(dst, b, h) do { _Pragma("unroll") for (int m = 0; m < 4; ++m) _Pragma("unroll") for (int k = 0; k < 2; ++k) dst[m][k] = *(const LAS bf16x8*)(lds + PG8_SA(b, h) + aoff + m * 2048 + k * 1024); } while (0)
; #define PG8_LDB(dst, b, h) do { _Pragma("unroll") for (int n = 0; n < 2; ++n) _Pragma("unroll") for (int k = 0; k < 2; ++k) dst[n][k] = *(const LAS bf16x8*)(lds + PG8_SB(b, h) + boff + n * 2048 + k * 1024); } while (0)
; #define PG8_MMA(ai, bj, At, Bt) do { __builtin_amdgcn_s_setprio(1); _Pragma("unroll") for (int m = 0; m < 4; ++m) _Pragma("unroll") for (int n = 0; n < 2; ++n) _Pragma("unroll") for (int k = 0; k < 2; ++k) \
;         acc[ai][bj][m][n] = __builtin_amdgcn_mfma_f32_16x16x32_bf16(Bt[n][k], At[m][k], acc[ai][bj][m][n], 0, 0, 0); __builtin_amdgcn_s_setprio(0); } while (0)
; #define PG8_WAIT_V(n) asm volatile("s_waitcnt vmcnt(" #n ")" ::: "memory")
; #define PG8_WAIT_L(n) asm volatile("s_waitcnt lgkmcnt(" #n ")" ::: "memory")
; #define PG8_BAR __builtin_amdgcn_s_barrier()
; #define PG8_SCHED __builtin_amdgcn_sched_barrier(0)
; template <class Epi>
; __device__ __forceinline__ void gemm_phase(LAS unsigned char* lds, const Gemm g, const StaticOrder& S, const Epi& E) {
;     ...
;             PG8_WAIT_V(8); PG8_WAIT_L(0); PG8_BAR; PG8_MMA(1, 0, At, B0); PG8_MMA(1, 1, At, B1); PG8_BAR; PG8_SCHED;
;             PG8_LDB(B0, 1, 0); PG8_LDB(B1, 1, 1); PG8_SCHED; PG8_LDA(At, 1, 0); PG8_STAGE(PG8_SA(0, 1), a2 + hstepA, voffA);
;             PG8_WAIT_V(8); PG8_WAIT_L(0); PG8_BAR; PG8_MMA(0, 0, At, B0); PG8_MMA(0, 1, At, B1); PG8_BAR; PG8_SCHED;
	s_setprio 1
	s_waitcnt lgkmcnt(0)
	v_mfma_f32_16x16x32_bf16 v[60:63], v[128:131], v[190:193], v[60:63]
	v_mfma_f32_16x16x32_bf16 v[60:63], v[132:135], v[194:197], v[60:63]
	v_mfma_f32_16x16x32_bf16 v[56:59], v[136:139], v[190:193], v[56:59]
	v_mfma_f32_16x16x32_bf16 v[56:59], v[140:143], v[194:197], v[56:59]
	v_mfma_f32_16x16x32_bf16 v[52:55], v[144:147], v[190:193], v[52:55]
	v_mfma_f32_16x16x32_bf16 v[52:55], v[148:151], v[194:197], v[52:55]
	v_mfma_f32_16x16x32_bf16 v[48:51], v[152:155], v[190:193], v[48:51]
	v_mfma_f32_16x16x32_bf16 v[48:51], v[156:159], v[194:197], v[48:51]
	v_mfma_f32_16x16x32_bf16 v[32:35], v[152:155], v[198:201], v[32:35]
	v_mfma_f32_16x16x32_bf16 v[32:35], v[156:159], v[208:211], v[32:35]
	v_mfma_f32_16x16x32_bf16 v[36:39], v[144:147], v[198:201], v[36:39]
	v_mfma_f32_16x16x32_bf16 v[36:39], v[148:151], v[208:211], v[36:39]
	v_mfma_f32_16x16x32_bf16 v[40:43], v[136:139], v[198:201], v[40:43]
	v_mfma_f32_16x16x32_bf16 v[40:43], v[140:143], v[208:211], v[40:43]
	v_mfma_f32_16x16x32_bf16 v[44:47], v[128:131], v[198:201], v[44:47]
	v_mfma_f32_16x16x32_bf16 v[44:47], v[132:135], v[208:211], v[44:47]
	s_setprio 0
	s_setprio 1
	v_mfma_f32_16x16x32_bf16 v[28:31], v[128:131], v[212:215], v[28:31]
	v_mfma_f32_16x16x32_bf16 v[28:31], v[132:135], v[216:219], v[28:31]
	v_mfma_f32_16x16x32_bf16 v[24:27], v[136:139], v[212:215], v[24:27]
	v_mfma_f32_16x16x32_bf16 v[24:27], v[140:143], v[216:219], v[24:27]
	v_mfma_f32_16x16x32_bf16 v[20:23], v[144:147], v[212:215], v[20:23]
	v_mfma_f32_16x16x32_bf16 v[20:23], v[148:151], v[216:219], v[20:23]
	v_mfma_f32_16x16x32_bf16 v[16:19], v[152:155], v[212:215], v[16:19]
	v_mfma_f32_16x16x32_bf16 v[16:19], v[156:159], v[216:219], v[16:19]
	v_mfma_f32_16x16x32_bf16 v[0:3], v[152:155], v[220:223], v[0:3]
	v_mfma_f32_16x16x32_bf16 v[0:3], v[156:159], v[224:227], v[0:3]
	v_mfma_f32_16x16x32_bf16 v[4:7], v[144:147], v[220:223], v[4:7]
	v_mfma_f32_16x16x32_bf16 v[4:7], v[148:151], v[224:227], v[4:7]
	v_mfma_f32_16x16x32_bf16 v[8:11], v[136:139], v[220:223], v[8:11]
	v_mfma_f32_16x16x32_bf16 v[8:11], v[140:143], v[224:227], v[8:11]
	v_mfma_f32_16x16x32_bf16 v[12:15], v[128:131], v[220:223], v[12:15]
	v_mfma_f32_16x16x32_bf16 v[12:15], v[132:135], v[224:227], v[12:15]
	s_setprio 0
	s_barrier
	s_add_i32 s76, 0, 0x18000
	s_add_i32 s77, 0, 0x1c000
	v_add_u32_e32 v140, s76, v184
	v_add_u32_e32 v156, s77, v184
	ds_read_b128 v[128:131], v140
	ds_read_b128 v[132:135], v140 offset:1024
	ds_read_b128 v[136:139], v140 offset:2048
	ds_read_b128 v[140:143], v140 offset:3072
	ds_read_b128 v[144:147], v156
	ds_read_b128 v[148:151], v156 offset:1024
	ds_read_b128 v[152:155], v156 offset:2048
	ds_read_b128 v[156:159], v156 offset:3072
	s_add_u32 s48, s48, 0x80000
	s_addc_u32 s49, s49, 0
	s_mov_b32 m0, s56
	v_lshl_add_u64 v[234:235], s[48:49], 0, v[160:161]
	ds_read_b128 v[190:193], v187 offset:32768
	ds_read_b128 v[194:197], v187 offset:33792
	ds_read_b128 v[198:201], v187 offset:34816
	ds_read_b128 v[208:211], v187 offset:35840
	ds_read_b128 v[212:215], v187 offset:36864
	ds_read_b128 v[216:219], v187 offset:37888
	ds_read_b128 v[220:223], v187 offset:38912
	ds_read_b128 v[224:227], v187 offset:39936
	global_load_lds_dwordx4 v[234:235], off
	v_lshl_add_u64 v[234:235], s[48:49], 0, v[164:165]
	s_mov_b32 m0, s57
	s_nop 0
	global_load_lds_dwordx4 v[234:235], off
	s_waitcnt vmcnt(8)
	s_waitcnt lgkmcnt(0)
	s_barrier
	s_setprio 1
	s_waitcnt lgkmcnt(0)
	v_mfma_f32_16x16x32_bf16 v[120:123], v[128:131], v[190:193], v[120:123]
	v_mfma_f32_16x16x32_bf16 v[120:123], v[132:135], v[194:197], v[120:123]
	v_mfma_f32_16x16x32_bf16 v[124:127], v[136:139], v[190:193], v[124:127]
	v_mfma_f32_16x16x32_bf16 v[124:127], v[140:143], v[194:197], v[124:127]
	v_mfma_f32_16x16x32_bf16 v[116:119], v[144:147], v[190:193], v[116:119]
	v_mfma_f32_16x16x32_bf16 v[116:119], v[148:151], v[194:197], v[116:119]
	v_mfma_f32_16x16x32_bf16 v[112:115], v[152:155], v[190:193], v[112:115]
	v_mfma_f32_16x16x32_bf16 v[112:115], v[156:159], v[194:197], v[112:115]
	v_mfma_f32_16x16x32_bf16 v[96:99], v[152:155], v[198:201], v[96:99]
	v_mfma_f32_16x16x32_bf16 v[96:99], v[156:159], v[208:211], v[96:99]
	v_mfma_f32_16x16x32_bf16 v[100:103], v[144:147], v[198:201], v[100:103]
	v_mfma_f32_16x16x32_bf16 v[100:103], v[148:151], v[208:211], v[100:103]
	v_mfma_f32_16x16x32_bf16 v[104:107], v[136:139], v[198:201], v[104:107]
	v_mfma_f32_16x16x32_bf16 v[104:107], v[140:143], v[208:211], v[104:107]
	v_mfma_f32_16x16x32_bf16 v[108:111], v[128:131], v[198:201], v[108:111]
	v_mfma_f32_16x16x32_bf16 v[108:111], v[132:135], v[208:211], v[108:111]
	s_setprio 0
	s_setprio 1
	v_mfma_f32_16x16x32_bf16 v[92:95], v[128:131], v[212:215], v[92:95]
	v_mfma_f32_16x16x32_bf16 v[92:95], v[132:135], v[216:219], v[92:95]
	v_mfma_f32_16x16x32_bf16 v[88:91], v[136:139], v[212:215], v[88:91]
	v_mfma_f32_16x16x32_bf16 v[88:91], v[140:143], v[216:219], v[88:91]
	v_mfma_f32_16x16x32_bf16 v[84:87], v[144:147], v[212:215], v[84:87]
	v_mfma_f32_16x16x32_bf16 v[84:87], v[148:151], v[216:219], v[84:87]
	v_mfma_f32_16x16x32_bf16 v[80:83], v[152:155], v[212:215], v[80:83]
	v_mfma_f32_16x16x32_bf16 v[80:83], v[156:159], v[216:219], v[80:83]
	v_mfma_f32_16x16x32_bf16 v[64:67], v[152:155], v[220:223], v[64:67]
	v_mfma_f32_16x16x32_bf16 v[64:67], v[156:159], v[224:227], v[64:67]
	v_mfma_f32_16x16x32_bf16 v[68:71], v[144:147], v[220:223], v[68:71]
	v_mfma_f32_16x16x32_bf16 v[68:71], v[148:151], v[224:227], v[68:71]
	v_mfma_f32_16x16x32_bf16 v[72:75], v[136:139], v[220:223], v[72:75]
	v_mfma_f32_16x16x32_bf16 v[72:75], v[140:143], v[224:227], v[72:75]
	v_mfma_f32_16x16x32_bf16 v[76:79], v[128:131], v[220:223], v[76:79]
	v_mfma_f32_16x16x32_bf16 v[76:79], v[132:135], v[224:227], v[76:79]
	s_setprio 0
	s_barrier
; #define PG8_STAGE(bufoff, gbase, voff) do { _Pragma("unroll") for (int _i = 0; _i < 2; ++_i) \
;         __builtin_amdgcn_global_load_lds((const unsigned*)((const char*)(gbase) + (voff)[_i]), (LAS unsigned*)(lds + (bufoff) + ldsw + _i * 8192), 16, 0, 0); } while (0)
; #define PG8_LDA(dst, b, h) do { _Pragma("unroll") for (int m = 0; m < 4; ++m) _Pragma("unroll") for (int k = 0; k < 2; ++k) dst[m][k] = *(const LAS bf16x8*)(lds + PG8_SA(b, h) + aoff + m * 2048 + k * 1024); } while (0)
; #define PG8_MMA(ai, bj, At, Bt) do { __builtin_amdgcn_s_setprio(1); _Pragma("unroll") for (int m = 0; m < 4; ++m) _Pragma("unroll") for (int n = 0; n < 2; ++n) _Pragma("unroll") for (int k = 0; k < 2; ++k) \
;         acc[ai][bj][m][n] = __builtin_amdgcn_mfma_f32_16x16x32_bf16(Bt[n][k], At[m][k], acc[ai][bj][m][n], 0, 0, 0); __builtin_amdgcn_s_setprio(0); } while (0)
; #define PG8_WAIT_V(n) asm volatile("s_waitcnt vmcnt(" #n ")" ::: "memory")
; #define PG8_WAIT_L(n) asm volatile("s_waitcnt lgkmcnt(" #n ")" ::: "memory")
; #define PG8_BAR __builtin_amdgcn_s_barrier()
; #define PG8_SCHED __builtin_amdgcn_sched_barrier(0)
; template <class Epi>
; __device__ __forceinline__ void gemm_phase(LAS unsigned char* lds, const Gemm g, const StaticOrder& S, const Epi& E) {
;     ...
;             PG8_LDA(At, 1, 1); PG8_STAGE(PG8_SB(1, 0), b3, voffB); PG8_STAGE(PG8_SB(1, 1), b3 + hstepB, voffB); PG8_STAGE(PG8_SA(1, 0), a3, voffA);
;             PG8_WAIT_V(8); PG8_WAIT_L(0); PG8_BAR; PG8_MMA(1, 0, At, B0); PG8_MMA(1, 1, At, B1); PG8_BAR; PG8_SCHED;
;         }
	s_add_i32 s48, s76, s54
	v_lshl_add_u64 v[182:183], v[182:183], 0, s[16:17]
	s_mov_b32 m0, s48
	ds_read_b128 v[190:193], v187 offset:49152
	ds_read_b128 v[194:197], v187 offset:50176
	ds_read_b128 v[198:201], v187 offset:51200
	ds_read_b128 v[208:211], v187 offset:52224
	ds_read_b128 v[212:215], v187 offset:53248
	ds_read_b128 v[216:219], v187 offset:54272
	ds_read_b128 v[220:223], v187 offset:55296
	ds_read_b128 v[224:227], v187 offset:56320
	global_load_lds_dwordx4 v[182:183], off
	s_add_i32 m0, s48, 0x2000
	s_add_u32 s46, s46, 0x80080
	v_lshl_add_u64 v[182:183], v[202:203], 0, s[16:17]
	s_addc_u32 s47, s47, 0
	s_add_i32 s48, s77, s54
	global_load_lds_dwordx4 v[182:183], off
	v_lshl_add_u64 v[182:183], s[46:47], 0, v[162:163]
	s_mov_b32 m0, s48
	s_nop 0
	global_load_lds_dwordx4 v[182:183], off
	v_lshl_add_u64 v[182:183], s[46:47], 0, v[166:167]
	s_add_i32 m0, s48, 0x2000
	s_nop 0
	global_load_lds_dwordx4 v[182:183], off
	v_lshl_add_u64 v[182:183], v[230:231], 0, s[16:17]
	s_mov_b32 m0, s60
	s_nop 0
	global_load_lds_dwordx4 v[182:183], off
	v_lshl_add_u64 v[182:183], v[232:233], 0, s[16:17]
	s_mov_b32 m0, s61
	s_nop 0
	global_load_lds_dwordx4 v[182:183], off
	s_waitcnt vmcnt(8)
	s_waitcnt lgkmcnt(0)
	s_barrier
	s_setprio 1
	s_waitcnt lgkmcnt(0)
	v_mfma_f32_16x16x32_bf16 v[60:63], v[128:131], v[190:193], v[60:63]
	v_mfma_f32_16x16x32_bf16 v[60:63], v[132:135], v[194:197], v[60:63]
	v_mfma_f32_16x16x32_bf16 v[56:59], v[136:139], v[190:193], v[56:59]
	v_mfma_f32_16x16x32_bf16 v[56:59], v[140:143], v[194:197], v[56:59]
	v_mfma_f32_16x16x32_bf16 v[52:55], v[144:147], v[190:193], v[52:55]
	v_mfma_f32_16x16x32_bf16 v[52:55], v[148:151], v[194:197], v[52:55]
	v_mfma_f32_16x16x32_bf16 v[48:51], v[152:155], v[190:193], v[48:51]
	v_mfma_f32_16x16x32_bf16 v[48:51], v[156:159], v[194:197], v[48:51]
	v_mfma_f32_16x16x32_bf16 v[32:35], v[152:155], v[198:201], v[32:35]
	v_mfma_f32_16x16x32_bf16 v[32:35], v[156:159], v[208:211], v[32:35]
	v_mfma_f32_16x16x32_bf16 v[36:39], v[144:147], v[198:201], v[36:39]
	v_mfma_f32_16x16x32_bf16 v[36:39], v[148:151], v[208:211], v[36:39]
	v_mfma_f32_16x16x32_bf16 v[40:43], v[136:139], v[198:201], v[40:43]
	v_mfma_f32_16x16x32_bf16 v[40:43], v[140:143], v[208:211], v[40:43]
	v_mfma_f32_16x16x32_bf16 v[44:47], v[128:131], v[198:201], v[44:47]
	v_mfma_f32_16x16x32_bf16 v[44:47], v[132:135], v[208:211], v[44:47]
	s_setprio 0
	s_setprio 1
	v_mfma_f32_16x16x32_bf16 v[28:31], v[128:131], v[212:215], v[28:31]
	v_mfma_f32_16x16x32_bf16 v[28:31], v[132:135], v[216:219], v[28:31]
	v_mfma_f32_16x16x32_bf16 v[24:27], v[136:139], v[212:215], v[24:27]
	v_mfma_f32_16x16x32_bf16 v[24:27], v[140:143], v[216:219], v[24:27]
	v_mfma_f32_16x16x32_bf16 v[20:23], v[144:147], v[212:215], v[20:23]
	v_mfma_f32_16x16x32_bf16 v[20:23], v[148:151], v[216:219], v[20:23]
	v_mfma_f32_16x16x32_bf16 v[16:19], v[152:155], v[212:215], v[16:19]
	v_mfma_f32_16x16x32_bf16 v[16:19], v[156:159], v[216:219], v[16:19]
	v_mfma_f32_16x16x32_bf16 v[0:3], v[152:155], v[220:223], v[0:3]
	v_mfma_f32_16x16x32_bf16 v[0:3], v[156:159], v[224:227], v[0:3]
	v_mfma_f32_16x16x32_bf16 v[4:7], v[144:147], v[220:223], v[4:7]
	v_mfma_f32_16x16x32_bf16 v[4:7], v[148:151], v[224:227], v[4:7]
	v_mfma_f32_16x16x32_bf16 v[8:11], v[136:139], v[220:223], v[8:11]
	v_mfma_f32_16x16x32_bf16 v[8:11], v[140:143], v[224:227], v[8:11]
	v_mfma_f32_16x16x32_bf16 v[12:15], v[128:131], v[220:223], v[12:15]
	v_mfma_f32_16x16x32_bf16 v[12:15], v[132:135], v[224:227], v[12:15]
	s_setprio 0
	s_barrier
	s_add_u32 s12, s12, 0x100
	s_addc_u32 s13, s13, 0
	s_add_u32 s71, s71, 0x100
	s_addc_u32 s72, s72, 0
	s_cmp_ge_i32 s73, s59
	s_mov_b32 s46, s73
	s_cbranch_scc0 .LBB0_1046

; #define PG8_STAGE(bufoff, gbase, voff) do { _Pragma("unroll") for (int _i = 0; _i < 2; ++_i) \
;         __builtin_amdgcn_global_load_lds((const unsigned*)((const char*)(gbase) + (voff)[_i]), (LAS unsigned*)(lds + (bufoff) + ldsw + _i * 8192), 16, 0, 0); } while (0)
; #define PG8_LDA(dst, b, h) do { _Pragma("unroll") for (int m = 0; m < 4; ++m) _Pragma("unroll") for (int k = 0; k < 2; ++k) dst[m][k] = *(const LAS bf16x8*)(lds + PG8_SA(b, h) + aoff + m * 2048 + k * 1024); } while (0)
; #define PG8_LDB(dst, b, h) do { _Pragma("unroll") for (int n = 0; n < 2; ++n) _Pragma("unroll") for (int k = 0; k < 2; ++k) dst[n][k] = *(const LAS bf16x8*)(lds + PG8_SB(b, h) + boff + n * 2048 + k * 1024); } while (0)
; #define PG8_MMA(ai, bj, At, Bt) do { __builtin_amdgcn_s_setprio(1); _Pragma("unroll") for (int m = 0; m < 4; ++m) _Pragma("unroll") for (int n = 0; n < 2; ++n) _Pragma("unroll") for (int k = 0; k < 2; ++k) \
;         acc[ai][bj][m][n] = __builtin_amdgcn_mfma_f32_16x16x32_bf16(Bt[n][k], At[m][k], acc[ai][bj][m][n], 0, 0, 0); __builtin_amdgcn_s_setprio(0); } while (0)
; #define PG8_WAIT_V(n) asm volatile("s_waitcnt vmcnt(" #n ")" ::: "memory")
; #define PG8_WAIT_L(n) asm volatile("s_waitcnt lgkmcnt(" #n ")" ::: "memory")
; #define PG8_BAR __builtin_amdgcn_s_barrier()
; #define PG8_SCHED __builtin_amdgcn_sched_barrier(0)
; template <class Epi>
; __device__ __forceinline__ void gemm_phase(LAS unsigned char* lds, const Gemm g, const StaticOrder& S, const Epi& E) {
;     ...
;             const char* a2 = last ? nA : cA + (size_t)(t + 2) * kstep; const char* b2 = last ? nB : cB + (size_t)(t + 2) * kstep;
;             const char* a3 = a2 + kstep; const char* b3 = b2 + kstep;
;             PG8_LDB(B0, 0, 0); PG8_LDB(B1, 0, 1); PG8_SCHED; PG8_LDA(At, 0, 0); PG8_STAGE(PG8_SA(1, 1), a1 + hstepA, voffA);
;             PG8_WAIT_V(8); PG8_WAIT_L(0); PG8_BAR; PG8_MMA(0, 0, At, B0); PG8_MMA(0, 1, At, B1); PG8_BAR; PG8_SCHED;
;             PG8_LDA(At, 0, 1); PG8_STAGE(PG8_SB(0, 0), b2, voffB); PG8_STAGE(PG8_SB(0, 1), b2 + hstepB, voffB); PG8_STAGE(PG8_SA(0, 0), a2, voffA);
;             PG8_WAIT_V(8); PG8_WAIT_L(0); PG8_BAR; PG8_MMA(1, 0, At, B0); PG8_MMA(1, 1, At, B1); PG8_BAR; PG8_SCHED;
.LBB0_1131:
	ds_read_b128 v[164:167], v182
	ds_read_b128 v[168:171], v182 offset:1024
	ds_read_b128 v[172:175], v182 offset:2048
	ds_read_b128 v[176:179], v182 offset:3072
	ds_read_b128 v[186:189], v183
	ds_read_b128 v[190:193], v183 offset:1024
	ds_read_b128 v[194:197], v183 offset:2048
	ds_read_b128 v[198:201], v183 offset:3072
	s_add_i32 s22, s12, 2
	s_add_u32 s13, s10, 0xfff80080
	s_addc_u32 s14, s11, -1
	s_cmp_eq_u32 s58, s12
	s_cselect_b32 s12, s19, s20
	s_cselect_b32 s15, s16, s14
	s_cselect_b32 s14, s17, s13
	s_cselect_b32 s13, s18, s21
	v_lshl_add_u64 v[202:203], s[10:11], 0, v[140:141]
	s_add_i32 m0, s33, 0xc000
	ds_read_b128 v[208:211], v184
	ds_read_b128 v[212:215], v184 offset:1024
	ds_read_b128 v[216:219], v184 offset:2048
	ds_read_b128 v[220:223], v184 offset:3072
	ds_read_b128 v[224:227], v184 offset:4096
	ds_read_b128 v[230:233], v184 offset:5120
	ds_read_b128 v[234:237], v184 offset:6144
	ds_read_b128 v[238:241], v184 offset:7168
	global_load_lds_dwordx4 v[202:203], off
	v_lshl_add_u64 v[202:203], s[10:11], 0, v[142:143]
	s_add_i32 m0, s33, 0xe000
	s_nop 0
	global_load_lds_dwordx4 v[202:203], off
	s_waitcnt vmcnt(8)
	s_waitcnt lgkmcnt(0)
	s_barrier
	s_setprio 1
	s_waitcnt lgkmcnt(0)
	v_mfma_f32_16x16x32_bf16 v[120:123], v[164:167], v[208:211], v[120:123]
	v_mfma_f32_16x16x32_bf16 v[120:123], v[168:171], v[212:215], v[120:123]
	v_mfma_f32_16x16x32_bf16 v[116:119], v[172:175], v[208:211], v[116:119]
	v_mfma_f32_16x16x32_bf16 v[116:119], v[176:179], v[212:215], v[116:119]
	v_mfma_f32_16x16x32_bf16 v[124:127], v[186:189], v[208:211], v[124:127]
	v_mfma_f32_16x16x32_bf16 v[124:127], v[190:193], v[212:215], v[124:127]
	v_mfma_f32_16x16x32_bf16 v[112:115], v[194:197], v[208:211], v[112:115]
	v_mfma_f32_16x16x32_bf16 v[112:115], v[198:201], v[212:215], v[112:115]
	v_mfma_f32_16x16x32_bf16 v[96:99], v[194:197], v[216:219], v[96:99]
	v_mfma_f32_16x16x32_bf16 v[96:99], v[198:201], v[220:223], v[96:99]
	v_mfma_f32_16x16x32_bf16 v[104:107], v[186:189], v[216:219], v[104:107]
	v_mfma_f32_16x16x32_bf16 v[104:107], v[190:193], v[220:223], v[104:107]
	v_mfma_f32_16x16x32_bf16 v[100:103], v[172:175], v[216:219], v[100:103]
	v_mfma_f32_16x16x32_bf16 v[100:103], v[176:179], v[220:223], v[100:103]
	v_mfma_f32_16x16x32_bf16 v[108:111], v[164:167], v[216:219], v[108:111]
	v_mfma_f32_16x16x32_bf16 v[108:111], v[168:171], v[220:223], v[108:111]
	s_setprio 0
	s_setprio 1
	v_mfma_f32_16x16x32_bf16 v[92:95], v[164:167], v[224:227], v[92:95]
	v_mfma_f32_16x16x32_bf16 v[92:95], v[168:171], v[230:233], v[92:95]
	v_mfma_f32_16x16x32_bf16 v[84:87], v[172:175], v[224:227], v[84:87]
	v_mfma_f32_16x16x32_bf16 v[84:87], v[176:179], v[230:233], v[84:87]
	v_mfma_f32_16x16x32_bf16 v[88:91], v[186:189], v[224:227], v[88:91]
	v_mfma_f32_16x16x32_bf16 v[88:91], v[190:193], v[230:233], v[88:91]
	v_mfma_f32_16x16x32_bf16 v[80:83], v[194:197], v[224:227], v[80:83]
	v_mfma_f32_16x16x32_bf16 v[80:83], v[198:201], v[230:233], v[80:83]
	v_mfma_f32_16x16x32_bf16 v[64:67], v[194:197], v[234:237], v[64:67]
	v_mfma_f32_16x16x32_bf16 v[64:67], v[198:201], v[238:241], v[64:67]
	v_mfma_f32_16x16x32_bf16 v[72:75], v[186:189], v[234:237], v[72:75]
	v_mfma_f32_16x16x32_bf16 v[72:75], v[190:193], v[238:241], v[72:75]
	v_mfma_f32_16x16x32_bf16 v[68:71], v[172:175], v[234:237], v[68:71]
	v_mfma_f32_16x16x32_bf16 v[68:71], v[176:179], v[238:241], v[68:71]
	v_mfma_f32_16x16x32_bf16 v[76:79], v[164:167], v[234:237], v[76:79]
	v_mfma_f32_16x16x32_bf16 v[76:79], v[168:171], v[238:241], v[76:79]
	s_setprio 0
	s_barrier
	s_add_i32 s23, s62, s37
	v_lshl_add_u64 v[202:203], s[12:13], 0, v[132:133]
	s_mov_b32 m0, s23
	ds_read_b128 v[208:211], v184 offset:16384
	ds_read_b128 v[212:215], v184 offset:17408
	ds_read_b128 v[216:219], v184 offset:18432
	ds_read_b128 v[220:223], v184 offset:19456
	ds_read_b128 v[224:227], v184 offset:20480
	ds_read_b128 v[230:233], v184 offset:21504
	ds_read_b128 v[234:237], v184 offset:22528
	ds_read_b128 v[238:241], v184 offset:23552
	global_load_lds_dwordx4 v[202:203], off
	s_add_i32 m0, s23, 0x2000
	s_add_u32 s50, s12, 0x80000
	v_lshl_add_u64 v[242:243], s[12:13], 0, v[128:129]
	s_addc_u32 s51, s13, 0
	s_add_i32 s23, s63, s37
	global_load_lds_dwordx4 v[242:243], off
	v_lshl_add_u64 v[244:245], s[50:51], 0, v[132:133]
	s_mov_b32 m0, s23
	v_lshl_add_u64 v[246:247], s[14:15], 0, v[130:131]
	global_load_lds_dwordx4 v[244:245], off
	v_lshl_add_u64 v[244:245], s[50:51], 0, v[128:129]
	s_add_i32 m0, s23, 0x2000
	s_nop 0
	global_load_lds_dwordx4 v[244:245], off
	v_lshl_add_u64 v[244:245], s[14:15], 0, v[134:135]
	s_mov_b32 m0, s33
	s_nop 0
	global_load_lds_dwordx4 v[244:245], off
	s_mov_b32 m0, s52
	s_nop 0
	global_load_lds_dwordx4 v[246:247], off
	s_waitcnt vmcnt(8)
	s_waitcnt lgkmcnt(0)
	s_barrier
; #define PG8_STAGE(bufoff, gbase, voff) do { _Pragma("unroll") for (int _i = 0; _i < 2; ++_i) \
;         __builtin_amdgcn_global_load_lds((const unsigned*)((const char*)(gbase) + (voff)[_i]), (LAS unsigned*)(lds + (bufoff) + ldsw + _i * 8192), 16, 0, 0); } while (0)
; #define PG8_LDA(dst, b, h) do { _Pragma("unroll") for (int m = 0; m < 4; ++m) _Pragma("unroll") for (int k = 0; k < 2; ++k) dst[m][k] = *(const LAS bf16x8*)(lds + PG8_SA(b, h) + aoff + m * 2048 + k * 1024); } while (0)
; #define PG8_LDB(dst, b, h) do { _Pragma("unroll") for (int n = 0; n < 2; ++n) _Pragma("unroll") for (int k = 0; k < 2; ++k) dst[n][k] = *(const LAS bf16x8*)(lds + PG8_SB(b, h) + boff + n * 2048 + k * 1024); } while (0)
; #define PG8_MMA(ai, bj, At, Bt) do { __builtin_amdgcn_s_setprio(1); _Pragma("unroll") for (int m = 0; m < 4; ++m) _Pragma("unroll") for (int n = 0; n < 2; ++n) _Pragma("unroll") for (int k = 0; k < 2; ++k) \
;         acc[ai][bj][m][n] = __builtin_amdgcn_mfma_f32_16x16x32_bf16(Bt[n][k], At[m][k], acc[ai][bj][m][n], 0, 0, 0); __builtin_amdgcn_s_setprio(0); } while (0)
; #define PG8_WAIT_V(n) asm volatile("s_waitcnt vmcnt(" #n ")" ::: "memory")
; #define PG8_WAIT_L(n) asm volatile("s_waitcnt lgkmcnt(" #n ")" ::: "memory")
; #define PG8_BAR __builtin_amdgcn_s_barrier()
; #define PG8_SCHED __builtin_amdgcn_sched_barrier(0)
; template <class Epi>
; __device__ __forceinline__ void gemm_phase(LAS unsigned char* lds, const Gemm g, const StaticOrder& S, const Epi& E) {
;     ...
;             PG8_WAIT_V(8); PG8_WAIT_L(0); PG8_BAR; PG8_MMA(1, 0, At, B0); PG8_MMA(1, 1, At, B1); PG8_BAR; PG8_SCHED;
;             PG8_LDB(B0, 1, 0); PG8_LDB(B1, 1, 1); PG8_SCHED; PG8_LDA(At, 1, 0); PG8_STAGE(PG8_SA(0, 1), a2 + hstepA, voffA);
;             PG8_WAIT_V(8); PG8_WAIT_L(0); PG8_BAR; PG8_MMA(0, 0, At, B0); PG8_MMA(0, 1, At, B1); PG8_BAR; PG8_SCHED;
	s_setprio 1
	s_waitcnt lgkmcnt(0)
	v_mfma_f32_16x16x32_bf16 v[60:63], v[164:167], v[208:211], v[60:63]
	v_mfma_f32_16x16x32_bf16 v[60:63], v[168:171], v[212:215], v[60:63]
	v_mfma_f32_16x16x32_bf16 v[52:55], v[172:175], v[208:211], v[52:55]
	v_mfma_f32_16x16x32_bf16 v[52:55], v[176:179], v[212:215], v[52:55]
	v_mfma_f32_16x16x32_bf16 v[56:59], v[186:189], v[208:211], v[56:59]
	v_mfma_f32_16x16x32_bf16 v[56:59], v[190:193], v[212:215], v[56:59]
	v_mfma_f32_16x16x32_bf16 v[48:51], v[194:197], v[208:211], v[48:51]
	v_mfma_f32_16x16x32_bf16 v[48:51], v[198:201], v[212:215], v[48:51]
	v_mfma_f32_16x16x32_bf16 v[32:35], v[194:197], v[216:219], v[32:35]
	v_mfma_f32_16x16x32_bf16 v[32:35], v[198:201], v[220:223], v[32:35]
	v_mfma_f32_16x16x32_bf16 v[40:43], v[186:189], v[216:219], v[40:43]
	v_mfma_f32_16x16x32_bf16 v[40:43], v[190:193], v[220:223], v[40:43]
	v_mfma_f32_16x16x32_bf16 v[36:39], v[172:175], v[216:219], v[36:39]
	v_mfma_f32_16x16x32_bf16 v[36:39], v[176:179], v[220:223], v[36:39]
	v_mfma_f32_16x16x32_bf16 v[44:47], v[164:167], v[216:219], v[44:47]
	v_mfma_f32_16x16x32_bf16 v[44:47], v[168:171], v[220:223], v[44:47]
	s_setprio 0
	s_setprio 1
	v_mfma_f32_16x16x32_bf16 v[28:31], v[164:167], v[224:227], v[28:31]
	v_mfma_f32_16x16x32_bf16 v[28:31], v[168:171], v[230:233], v[28:31]
	v_mfma_f32_16x16x32_bf16 v[20:23], v[172:175], v[224:227], v[20:23]
	v_mfma_f32_16x16x32_bf16 v[20:23], v[176:179], v[230:233], v[20:23]
	v_mfma_f32_16x16x32_bf16 v[24:27], v[186:189], v[224:227], v[24:27]
	v_mfma_f32_16x16x32_bf16 v[24:27], v[190:193], v[230:233], v[24:27]
	v_mfma_f32_16x16x32_bf16 v[16:19], v[194:197], v[224:227], v[16:19]
	v_mfma_f32_16x16x32_bf16 v[16:19], v[198:201], v[230:233], v[16:19]
	v_mfma_f32_16x16x32_bf16 v[0:3], v[194:197], v[234:237], v[0:3]
	v_mfma_f32_16x16x32_bf16 v[0:3], v[198:201], v[238:241], v[0:3]
	v_mfma_f32_16x16x32_bf16 v[8:11], v[186:189], v[234:237], v[8:11]
	v_mfma_f32_16x16x32_bf16 v[8:11], v[190:193], v[238:241], v[8:11]
	v_mfma_f32_16x16x32_bf16 v[4:7], v[172:175], v[234:237], v[4:7]
	v_mfma_f32_16x16x32_bf16 v[4:7], v[176:179], v[238:241], v[4:7]
	v_mfma_f32_16x16x32_bf16 v[12:15], v[164:167], v[234:237], v[12:15]
	v_mfma_f32_16x16x32_bf16 v[12:15], v[168:171], v[238:241], v[12:15]
	s_setprio 0
	s_barrier
	s_add_i32 s23, 0, 0x18000
	s_add_i32 s25, 0, 0x1c000
	v_add_u32_e32 v176, s23, v180
	v_add_u32_e32 v185, s25, v180
	ds_read_b128 v[164:167], v176
	ds_read_b128 v[168:171], v176 offset:1024
	ds_read_b128 v[172:175], v176 offset:2048
	ds_read_b128 v[176:179], v176 offset:3072
	ds_read_b128 v[186:189], v185
	ds_read_b128 v[190:193], v185 offset:1024
	ds_read_b128 v[194:197], v185 offset:2048
	ds_read_b128 v[198:201], v185 offset:3072
	s_add_u32 s14, s14, 0x80000
	s_addc_u32 s15, s15, 0
	s_mov_b32 m0, s53
	v_lshl_add_u64 v[248:249], s[14:15], 0, v[134:135]
	ds_read_b128 v[208:211], v184 offset:32768
	ds_read_b128 v[212:215], v184 offset:33792
	ds_read_b128 v[216:219], v184 offset:34816
	ds_read_b128 v[220:223], v184 offset:35840
	ds_read_b128 v[224:227], v184 offset:36864
	ds_read_b128 v[230:233], v184 offset:37888
	ds_read_b128 v[234:237], v184 offset:38912
	ds_read_b128 v[238:241], v184 offset:39936
	global_load_lds_dwordx4 v[248:249], off
	v_lshl_add_u64 v[248:249], s[14:15], 0, v[130:131]
	s_mov_b32 m0, s54
	s_nop 0
	global_load_lds_dwordx4 v[248:249], off
	s_waitcnt vmcnt(8)
	s_waitcnt lgkmcnt(0)
	s_barrier
	s_setprio 1
	s_waitcnt lgkmcnt(0)
	v_mfma_f32_16x16x32_bf16 v[120:123], v[164:167], v[208:211], v[120:123]
	v_mfma_f32_16x16x32_bf16 v[120:123], v[168:171], v[212:215], v[120:123]
	v_mfma_f32_16x16x32_bf16 v[116:119], v[172:175], v[208:211], v[116:119]
	v_mfma_f32_16x16x32_bf16 v[116:119], v[176:179], v[212:215], v[116:119]
	v_mfma_f32_16x16x32_bf16 v[124:127], v[186:189], v[208:211], v[124:127]
	v_mfma_f32_16x16x32_bf16 v[124:127], v[190:193], v[212:215], v[124:127]
	v_mfma_f32_16x16x32_bf16 v[112:115], v[194:197], v[208:211], v[112:115]
	v_mfma_f32_16x16x32_bf16 v[112:115], v[198:201], v[212:215], v[112:115]
	v_mfma_f32_16x16x32_bf16 v[96:99], v[194:197], v[216:219], v[96:99]
	v_mfma_f32_16x16x32_bf16 v[96:99], v[198:201], v[220:223], v[96:99]
	v_mfma_f32_16x16x32_bf16 v[104:107], v[186:189], v[216:219], v[104:107]
	v_mfma_f32_16x16x32_bf16 v[104:107], v[190:193], v[220:223], v[104:107]
	v_mfma_f32_16x16x32_bf16 v[100:103], v[172:175], v[216:219], v[100:103]
	v_mfma_f32_16x16x32_bf16 v[100:103], v[176:179], v[220:223], v[100:103]
	v_mfma_f32_16x16x32_bf16 v[108:111], v[164:167], v[216:219], v[108:111]
	v_mfma_f32_16x16x32_bf16 v[108:111], v[168:171], v[220:223], v[108:111]
	s_setprio 0
	s_setprio 1
	v_mfma_f32_16x16x32_bf16 v[92:95], v[164:167], v[224:227], v[92:95]
	v_mfma_f32_16x16x32_bf16 v[92:95], v[168:171], v[230:233], v[92:95]
	v_mfma_f32_16x16x32_bf16 v[84:87], v[172:175], v[224:227], v[84:87]
	v_mfma_f32_16x16x32_bf16 v[84:87], v[176:179], v[230:233], v[84:87]
	v_mfma_f32_16x16x32_bf16 v[88:91], v[186:189], v[224:227], v[88:91]
	v_mfma_f32_16x16x32_bf16 v[88:91], v[190:193], v[230:233], v[88:91]
	v_mfma_f32_16x16x32_bf16 v[80:83], v[194:197], v[224:227], v[80:83]
	v_mfma_f32_16x16x32_bf16 v[80:83], v[198:201], v[230:233], v[80:83]
	v_mfma_f32_16x16x32_bf16 v[64:67], v[194:197], v[234:237], v[64:67]
	v_mfma_f32_16x16x32_bf16 v[64:67], v[198:201], v[238:241], v[64:67]
	v_mfma_f32_16x16x32_bf16 v[72:75], v[186:189], v[234:237], v[72:75]
	v_mfma_f32_16x16x32_bf16 v[72:75], v[190:193], v[238:241], v[72:75]
	v_mfma_f32_16x16x32_bf16 v[68:71], v[172:175], v[234:237], v[68:71]
	v_mfma_f32_16x16x32_bf16 v[68:71], v[176:179], v[238:241], v[68:71]
	v_mfma_f32_16x16x32_bf16 v[76:79], v[164:167], v[234:237], v[76:79]
	v_mfma_f32_16x16x32_bf16 v[76:79], v[168:171], v[238:241], v[76:79]
	s_setprio 0
	s_barrier
; #define PG8_STAGE(bufoff, gbase, voff) do { _Pragma("unroll") for (int _i = 0; _i < 2; ++_i) \
;         __builtin_amdgcn_global_load_lds((const unsigned*)((const char*)(gbase) + (voff)[_i]), (LAS unsigned*)(lds + (bufoff) + ldsw + _i * 8192), 16, 0, 0); } while (0)
; #define PG8_LDA(dst, b, h) do { _Pragma("unroll") for (int m = 0; m < 4; ++m) _Pragma("unroll") for (int k = 0; k < 2; ++k) dst[m][k] = *(const LAS bf16x8*)(lds + PG8_SA(b, h) + aoff + m * 2048 + k * 1024); } while (0)
; #define PG8_MMA(ai, bj, At, Bt) do { __builtin_amdgcn_s_setprio(1); _Pragma("unroll") for (int m = 0; m < 4; ++m) _Pragma("unroll") for (int n = 0; n < 2; ++n) _Pragma("unroll") for (int k = 0; k < 2; ++k) \
;         acc[ai][bj][m][n] = __builtin_amdgcn_mfma_f32_16x16x32_bf16(Bt[n][k], At[m][k], acc[ai][bj][m][n], 0, 0, 0); __builtin_amdgcn_s_setprio(0); } while (0)
; #define PG8_WAIT_V(n) asm volatile("s_waitcnt vmcnt(" #n ")" ::: "memory")
; #define PG8_WAIT_L(n) asm volatile("s_waitcnt lgkmcnt(" #n ")" ::: "memory")
; #define PG8_BAR __builtin_amdgcn_s_barrier()
; #define PG8_SCHED __builtin_amdgcn_sched_barrier(0)
; template <class Epi>
; __device__ __forceinline__ void gemm_phase(LAS unsigned char* lds, const Gemm g, const StaticOrder& S, const Epi& E) {
;     ...
;             PG8_LDA(At, 1, 1); PG8_STAGE(PG8_SB(1, 0), b3, voffB); PG8_STAGE(PG8_SB(1, 1), b3 + hstepB, voffB); PG8_STAGE(PG8_SA(1, 0), a3, voffA);
;             PG8_WAIT_V(8); PG8_WAIT_L(0); PG8_BAR; PG8_MMA(1, 0, At, B0); PG8_MMA(1, 1, At, B1); PG8_BAR; PG8_SCHED;
;         }
	s_add_i32 s14, s23, s37
	v_lshl_add_u64 v[202:203], v[202:203], 0, s[4:5]
	s_mov_b32 m0, s14
	ds_read_b128 v[208:211], v184 offset:49152
	ds_read_b128 v[212:215], v184 offset:50176
	ds_read_b128 v[216:219], v184 offset:51200
	ds_read_b128 v[220:223], v184 offset:52224
	ds_read_b128 v[224:227], v184 offset:53248
	ds_read_b128 v[230:233], v184 offset:54272
	ds_read_b128 v[234:237], v184 offset:55296
	ds_read_b128 v[238:241], v184 offset:56320
	global_load_lds_dwordx4 v[202:203], off
	s_add_i32 m0, s14, 0x2000
	s_add_u32 s12, s12, 0x80080
	v_lshl_add_u64 v[202:203], v[242:243], 0, s[4:5]
	s_addc_u32 s13, s13, 0
	s_add_i32 s14, s25, s37
	global_load_lds_dwordx4 v[202:203], off
	v_lshl_add_u64 v[202:203], s[12:13], 0, v[132:133]
	s_mov_b32 m0, s14
	s_nop 0
	global_load_lds_dwordx4 v[202:203], off
	v_lshl_add_u64 v[202:203], s[12:13], 0, v[128:129]
	s_add_i32 m0, s14, 0x2000
	s_nop 0
	global_load_lds_dwordx4 v[202:203], off
	v_lshl_add_u64 v[202:203], v[244:245], 0, s[4:5]
	s_mov_b32 m0, s56
	s_nop 0
	global_load_lds_dwordx4 v[202:203], off
	v_lshl_add_u64 v[202:203], v[246:247], 0, s[4:5]
	s_mov_b32 m0, s57
	s_nop 0
	global_load_lds_dwordx4 v[202:203], off
	s_waitcnt vmcnt(8)
	s_waitcnt lgkmcnt(0)
	s_barrier
	s_setprio 1
	s_waitcnt lgkmcnt(0)
	v_mfma_f32_16x16x32_bf16 v[60:63], v[164:167], v[208:211], v[60:63]
	v_mfma_f32_16x16x32_bf16 v[60:63], v[168:171], v[212:215], v[60:63]
	v_mfma_f32_16x16x32_bf16 v[52:55], v[172:175], v[208:211], v[52:55]
	v_mfma_f32_16x16x32_bf16 v[52:55], v[176:179], v[212:215], v[52:55]
	v_mfma_f32_16x16x32_bf16 v[56:59], v[186:189], v[208:211], v[56:59]
	v_mfma_f32_16x16x32_bf16 v[56:59], v[190:193], v[212:215], v[56:59]
	v_mfma_f32_16x16x32_bf16 v[48:51], v[194:197], v[208:211], v[48:51]
	v_mfma_f32_16x16x32_bf16 v[48:51], v[198:201], v[212:215], v[48:51]
	v_mfma_f32_16x16x32_bf16 v[32:35], v[194:197], v[216:219], v[32:35]
	v_mfma_f32_16x16x32_bf16 v[32:35], v[198:201], v[220:223], v[32:35]
	v_mfma_f32_16x16x32_bf16 v[40:43], v[186:189], v[216:219], v[40:43]
	v_mfma_f32_16x16x32_bf16 v[40:43], v[190:193], v[220:223], v[40:43]
	v_mfma_f32_16x16x32_bf16 v[36:39], v[172:175], v[216:219], v[36:39]
	v_mfma_f32_16x16x32_bf16 v[36:39], v[176:179], v[220:223], v[36:39]
	v_mfma_f32_16x16x32_bf16 v[44:47], v[164:167], v[216:219], v[44:47]
	v_mfma_f32_16x16x32_bf16 v[44:47], v[168:171], v[220:223], v[44:47]
	s_setprio 0
	s_setprio 1
	v_mfma_f32_16x16x32_bf16 v[28:31], v[164:167], v[224:227], v[28:31]
	v_mfma_f32_16x16x32_bf16 v[28:31], v[168:171], v[230:233], v[28:31]
	v_mfma_f32_16x16x32_bf16 v[20:23], v[172:175], v[224:227], v[20:23]
	v_mfma_f32_16x16x32_bf16 v[20:23], v[176:179], v[230:233], v[20:23]
	v_mfma_f32_16x16x32_bf16 v[24:27], v[186:189], v[224:227], v[24:27]
	v_mfma_f32_16x16x32_bf16 v[24:27], v[190:193], v[230:233], v[24:27]
	v_mfma_f32_16x16x32_bf16 v[16:19], v[194:197], v[224:227], v[16:19]
	v_mfma_f32_16x16x32_bf16 v[16:19], v[198:201], v[230:233], v[16:19]
	v_mfma_f32_16x16x32_bf16 v[0:3], v[194:197], v[234:237], v[0:3]
	v_mfma_f32_16x16x32_bf16 v[0:3], v[198:201], v[238:241], v[0:3]
	v_mfma_f32_16x16x32_bf16 v[8:11], v[186:189], v[234:237], v[8:11]
	v_mfma_f32_16x16x32_bf16 v[8:11], v[190:193], v[238:241], v[8:11]
	v_mfma_f32_16x16x32_bf16 v[4:7], v[172:175], v[234:237], v[4:7]
	v_mfma_f32_16x16x32_bf16 v[4:7], v[176:179], v[238:241], v[4:7]
	v_mfma_f32_16x16x32_bf16 v[12:15], v[164:167], v[234:237], v[12:15]
	v_mfma_f32_16x16x32_bf16 v[12:15], v[168:171], v[238:241], v[12:15]
	s_setprio 0
	s_barrier
	s_add_u32 s10, s10, 0x100
	s_addc_u32 s11, s11, 0
	s_add_u32 s20, s20, 0x100
	s_addc_u32 s21, s21, 0
	s_cmp_ge_i32 s22, s55
	s_mov_b32 s12, s22
	s_cbranch_scc0 .LBB0_1131

; #define PG8_STAGE(bufoff, gbase, voff) do { _Pragma("unroll") for (int _i = 0; _i < 2; ++_i) \
;         __builtin_amdgcn_global_load_lds((const unsigned*)((const char*)(gbase) + (voff)[_i]), (LAS unsigned*)(lds + (bufoff) + ldsw + _i * 8192), 16, 0, 0); } while (0)
; #define PG8_LDA(dst, b, h) do { _Pragma("unroll") for (int m = 0; m < 4; ++m) _Pragma("unroll") for (int k = 0; k < 2; ++k) dst[m][k] = *(const LAS bf16x8*)(lds + PG8_SA(b, h) + aoff + m * 2048 + k * 1024); } while (0)
; #define PG8_LDB(dst, b, h) do { _Pragma("unroll") for (int n = 0; n < 2; ++n) _Pragma("unroll") for (int k = 0; k < 2; ++k) dst[n][k] = *(const LAS bf16x8*)(lds + PG8_SB(b, h) + boff + n * 2048 + k * 1024); } while (0)
; #define PG8_MMA(ai, bj, At, Bt) do { __builtin_amdgcn_s_setprio(1); _Pragma("unroll") for (int m = 0; m < 4; ++m) _Pragma("unroll") for (int n = 0; n < 2; ++n) _Pragma("unroll") for (int k = 0; k < 2; ++k) \
;         acc[ai][bj][m][n] = __builtin_amdgcn_mfma_f32_16x16x32_bf16(Bt[n][k], At[m][k], acc[ai][bj][m][n], 0, 0, 0); __builtin_amdgcn_s_setprio(0); } while (0)
; #define PG8_WAIT_V(n) asm volatile("s_waitcnt vmcnt(" #n ")" ::: "memory")
; #define PG8_WAIT_L(n) asm volatile("s_waitcnt lgkmcnt(" #n ")" ::: "memory")
; #define PG8_BAR __builtin_amdgcn_s_barrier()
; #define PG8_SCHED __builtin_amdgcn_sched_barrier(0)
; template <class Epi>
; __device__ __forceinline__ void gemm_phase(LAS unsigned char* lds, const Gemm g, const StaticOrder& S, const Epi& E) {
;     ...
;             const char* a2 = last ? nA : cA + (size_t)(t + 2) * kstep; const char* b2 = last ? nB : cB + (size_t)(t + 2) * kstep;
;             const char* a3 = a2 + kstep; const char* b3 = b2 + kstep;
;             PG8_LDB(B0, 0, 0); PG8_LDB(B1, 0, 1); PG8_SCHED; PG8_LDA(At, 0, 0); PG8_STAGE(PG8_SA(1, 1), a1 + hstepA, voffA);
;             PG8_WAIT_V(8); PG8_WAIT_L(0); PG8_BAR; PG8_MMA(0, 0, At, B0); PG8_MMA(0, 1, At, B1); PG8_BAR; PG8_SCHED;
;             PG8_LDA(At, 0, 1); PG8_STAGE(PG8_SB(0, 0), b2, voffB); PG8_STAGE(PG8_SB(0, 1), b2 + hstepB, voffB); PG8_STAGE(PG8_SA(0, 0), a2, voffA);
;             PG8_WAIT_V(8); PG8_WAIT_L(0); PG8_BAR; PG8_MMA(1, 0, At, B0); PG8_MMA(1, 1, At, B1); PG8_BAR; PG8_SCHED;
.LBB0_1161:
	ds_read_b128 v[152:155], v149
	ds_read_b128 v[156:159], v149 offset:1024
	ds_read_b128 v[160:163], v149 offset:2048
	ds_read_b128 v[164:167], v149 offset:3072
	ds_read_b128 v[168:171], v150
	ds_read_b128 v[172:175], v150 offset:1024
	ds_read_b128 v[176:179], v150 offset:2048
	ds_read_b128 v[180:183], v150 offset:3072
	s_add_i32 s83, s46, 2
	s_add_u32 s47, s44, 0xffff0080
	s_addc_u32 s48, s45, -1
	s_cmp_eq_u32 s65, s46
	s_cselect_b32 s46, s78, s79
	s_cselect_b32 s49, s35, s48
	s_cselect_b32 s48, s37, s47
	s_cselect_b32 s47, s39, s82
	v_lshl_add_u64 v[220:221], s[44:45], 0, v[140:141]
	s_add_i32 m0, s56, 0xc000
	ds_read_b128 v[184:187], v151
	ds_read_b128 v[188:191], v151 offset:1024
	ds_read_b128 v[192:195], v151 offset:2048
	ds_read_b128 v[196:199], v151 offset:3072
	ds_read_b128 v[200:203], v151 offset:4096
	ds_read_b128 v[208:211], v151 offset:5120
	ds_read_b128 v[212:215], v151 offset:6144
	ds_read_b128 v[216:219], v151 offset:7168
	global_load_lds_dwordx4 v[220:221], off
	v_lshl_add_u64 v[220:221], s[44:45], 0, v[142:143]
	s_add_i32 m0, s56, 0xe000
	s_nop 0
	global_load_lds_dwordx4 v[220:221], off
	s_waitcnt vmcnt(8)
	s_waitcnt lgkmcnt(0)
	s_barrier
	s_setprio 1
	s_waitcnt lgkmcnt(0)
	v_mfma_f32_16x16x32_bf16 v[120:123], v[152:155], v[184:187], v[120:123]
	v_mfma_f32_16x16x32_bf16 v[120:123], v[156:159], v[188:191], v[120:123]
	v_mfma_f32_16x16x32_bf16 v[124:127], v[160:163], v[184:187], v[124:127]
	v_mfma_f32_16x16x32_bf16 v[124:127], v[164:167], v[188:191], v[124:127]
	v_mfma_f32_16x16x32_bf16 v[116:119], v[168:171], v[184:187], v[116:119]
	v_mfma_f32_16x16x32_bf16 v[116:119], v[172:175], v[188:191], v[116:119]
	v_mfma_f32_16x16x32_bf16 v[112:115], v[176:179], v[184:187], v[112:115]
	v_mfma_f32_16x16x32_bf16 v[112:115], v[180:183], v[188:191], v[112:115]
	v_mfma_f32_16x16x32_bf16 v[96:99], v[176:179], v[192:195], v[96:99]
	v_mfma_f32_16x16x32_bf16 v[96:99], v[180:183], v[196:199], v[96:99]
	v_mfma_f32_16x16x32_bf16 v[100:103], v[168:171], v[192:195], v[100:103]
	v_mfma_f32_16x16x32_bf16 v[100:103], v[172:175], v[196:199], v[100:103]
	v_mfma_f32_16x16x32_bf16 v[104:107], v[160:163], v[192:195], v[104:107]
	v_mfma_f32_16x16x32_bf16 v[104:107], v[164:167], v[196:199], v[104:107]
	v_mfma_f32_16x16x32_bf16 v[108:111], v[152:155], v[192:195], v[108:111]
	v_mfma_f32_16x16x32_bf16 v[108:111], v[156:159], v[196:199], v[108:111]
	s_setprio 0
	s_setprio 1
	v_mfma_f32_16x16x32_bf16 v[92:95], v[152:155], v[200:203], v[92:95]
	v_mfma_f32_16x16x32_bf16 v[92:95], v[156:159], v[208:211], v[92:95]
	v_mfma_f32_16x16x32_bf16 v[88:91], v[160:163], v[200:203], v[88:91]
	v_mfma_f32_16x16x32_bf16 v[88:91], v[164:167], v[208:211], v[88:91]
	v_mfma_f32_16x16x32_bf16 v[84:87], v[168:171], v[200:203], v[84:87]
	v_mfma_f32_16x16x32_bf16 v[84:87], v[172:175], v[208:211], v[84:87]
	v_mfma_f32_16x16x32_bf16 v[80:83], v[176:179], v[200:203], v[80:83]
	v_mfma_f32_16x16x32_bf16 v[80:83], v[180:183], v[208:211], v[80:83]
	v_mfma_f32_16x16x32_bf16 v[64:67], v[176:179], v[212:215], v[64:67]
	v_mfma_f32_16x16x32_bf16 v[64:67], v[180:183], v[216:219], v[64:67]
	v_mfma_f32_16x16x32_bf16 v[68:71], v[168:171], v[212:215], v[68:71]
	v_mfma_f32_16x16x32_bf16 v[68:71], v[172:175], v[216:219], v[68:71]
	v_mfma_f32_16x16x32_bf16 v[72:75], v[160:163], v[212:215], v[72:75]
	v_mfma_f32_16x16x32_bf16 v[72:75], v[164:167], v[216:219], v[72:75]
	v_mfma_f32_16x16x32_bf16 v[76:79], v[152:155], v[212:215], v[76:79]
	v_mfma_f32_16x16x32_bf16 v[76:79], v[156:159], v[216:219], v[76:79]
	s_setprio 0
	s_barrier
	s_add_i32 s84, s67, s51
	v_lshl_add_u64 v[220:221], s[46:47], 0, v[130:131]
	s_mov_b32 m0, s84
	ds_read_b128 v[184:187], v151 offset:16384
	ds_read_b128 v[188:191], v151 offset:17408
	ds_read_b128 v[192:195], v151 offset:18432
	ds_read_b128 v[196:199], v151 offset:19456
	ds_read_b128 v[200:203], v151 offset:20480
	ds_read_b128 v[208:211], v151 offset:21504
	ds_read_b128 v[212:215], v151 offset:22528
	ds_read_b128 v[216:219], v151 offset:23552
	global_load_lds_dwordx4 v[220:221], off
	s_add_i32 m0, s84, 0x2000
	s_add_u32 s84, s46, 0x10000
	v_lshl_add_u64 v[222:223], s[46:47], 0, v[134:135]
	s_addc_u32 s85, s47, 0
	s_add_i32 s86, s68, s51
	global_load_lds_dwordx4 v[222:223], off
	v_lshl_add_u64 v[224:225], s[84:85], 0, v[130:131]
	s_mov_b32 m0, s86
	v_lshl_add_u64 v[226:227], s[48:49], 0, v[132:133]
	global_load_lds_dwordx4 v[224:225], off
	v_lshl_add_u64 v[224:225], s[84:85], 0, v[134:135]
	s_add_i32 m0, s86, 0x2000
	s_nop 0
	global_load_lds_dwordx4 v[224:225], off
	v_lshl_add_u64 v[224:225], s[48:49], 0, v[128:129]
	s_mov_b32 m0, s56
	s_nop 0
	global_load_lds_dwordx4 v[224:225], off
	s_mov_b32 m0, s57
	s_nop 0
	global_load_lds_dwordx4 v[226:227], off
	s_waitcnt vmcnt(8)
	s_waitcnt lgkmcnt(0)
	s_barrier
; #define PG8_STAGE(bufoff, gbase, voff) do { _Pragma("unroll") for (int _i = 0; _i < 2; ++_i) \
;         __builtin_amdgcn_global_load_lds((const unsigned*)((const char*)(gbase) + (voff)[_i]), (LAS unsigned*)(lds + (bufoff) + ldsw + _i * 8192), 16, 0, 0); } while (0)
; #define PG8_LDA(dst, b, h) do { _Pragma("unroll") for (int m = 0; m < 4; ++m) _Pragma("unroll") for (int k = 0; k < 2; ++k) dst[m][k] = *(const LAS bf16x8*)(lds + PG8_SA(b, h) + aoff + m * 2048 + k * 1024); } while (0)
; #define PG8_LDB(dst, b, h) do { _Pragma("unroll") for (int n = 0; n < 2; ++n) _Pragma("unroll") for (int k = 0; k < 2; ++k) dst[n][k] = *(const LAS bf16x8*)(lds + PG8_SB(b, h) + boff + n * 2048 + k * 1024); } while (0)
; #define PG8_MMA(ai, bj, At, Bt) do { __builtin_amdgcn_s_setprio(1); _Pragma("unroll") for (int m = 0; m < 4; ++m) _Pragma("unroll") for (int n = 0; n < 2; ++n) _Pragma("unroll") for (int k = 0; k < 2; ++k) \
;         acc[ai][bj][m][n] = __builtin_amdgcn_mfma_f32_16x16x32_bf16(Bt[n][k], At[m][k], acc[ai][bj][m][n], 0, 0, 0); __builtin_amdgcn_s_setprio(0); } while (0)
; #define PG8_WAIT_V(n) asm volatile("s_waitcnt vmcnt(" #n ")" ::: "memory")
; #define PG8_WAIT_L(n) asm volatile("s_waitcnt lgkmcnt(" #n ")" ::: "memory")
; #define PG8_BAR __builtin_amdgcn_s_barrier()
; #define PG8_SCHED __builtin_amdgcn_sched_barrier(0)
; template <class Epi>
; __device__ __forceinline__ void gemm_phase(LAS unsigned char* lds, const Gemm g, const StaticOrder& S, const Epi& E) {
;     ...
;             PG8_WAIT_V(8); PG8_WAIT_L(0); PG8_BAR; PG8_MMA(1, 0, At, B0); PG8_MMA(1, 1, At, B1); PG8_BAR; PG8_SCHED;
;             PG8_LDB(B0, 1, 0); PG8_LDB(B1, 1, 1); PG8_SCHED; PG8_LDA(At, 1, 0); PG8_STAGE(PG8_SA(0, 1), a2 + hstepA, voffA);
;             PG8_WAIT_V(8); PG8_WAIT_L(0); PG8_BAR; PG8_MMA(0, 0, At, B0); PG8_MMA(0, 1, At, B1); PG8_BAR; PG8_SCHED;
	s_setprio 1
	s_waitcnt lgkmcnt(0)
	v_mfma_f32_16x16x32_bf16 v[60:63], v[152:155], v[184:187], v[60:63]
	v_mfma_f32_16x16x32_bf16 v[60:63], v[156:159], v[188:191], v[60:63]
	v_mfma_f32_16x16x32_bf16 v[56:59], v[160:163], v[184:187], v[56:59]
	v_mfma_f32_16x16x32_bf16 v[56:59], v[164:167], v[188:191], v[56:59]
	v_mfma_f32_16x16x32_bf16 v[52:55], v[168:171], v[184:187], v[52:55]
	v_mfma_f32_16x16x32_bf16 v[52:55], v[172:175], v[188:191], v[52:55]
	v_mfma_f32_16x16x32_bf16 v[48:51], v[176:179], v[184:187], v[48:51]
	v_mfma_f32_16x16x32_bf16 v[48:51], v[180:183], v[188:191], v[48:51]
	v_mfma_f32_16x16x32_bf16 v[32:35], v[176:179], v[192:195], v[32:35]
	v_mfma_f32_16x16x32_bf16 v[32:35], v[180:183], v[196:199], v[32:35]
	v_mfma_f32_16x16x32_bf16 v[36:39], v[168:171], v[192:195], v[36:39]
	v_mfma_f32_16x16x32_bf16 v[36:39], v[172:175], v[196:199], v[36:39]
	v_mfma_f32_16x16x32_bf16 v[40:43], v[160:163], v[192:195], v[40:43]
	v_mfma_f32_16x16x32_bf16 v[40:43], v[164:167], v[196:199], v[40:43]
	v_mfma_f32_16x16x32_bf16 v[44:47], v[152:155], v[192:195], v[44:47]
	v_mfma_f32_16x16x32_bf16 v[44:47], v[156:159], v[196:199], v[44:47]
	s_setprio 0
	s_setprio 1
	v_mfma_f32_16x16x32_bf16 v[28:31], v[152:155], v[200:203], v[28:31]
	v_mfma_f32_16x16x32_bf16 v[28:31], v[156:159], v[208:211], v[28:31]
	v_mfma_f32_16x16x32_bf16 v[24:27], v[160:163], v[200:203], v[24:27]
	v_mfma_f32_16x16x32_bf16 v[24:27], v[164:167], v[208:211], v[24:27]
	v_mfma_f32_16x16x32_bf16 v[20:23], v[168:171], v[200:203], v[20:23]
	v_mfma_f32_16x16x32_bf16 v[20:23], v[172:175], v[208:211], v[20:23]
	v_mfma_f32_16x16x32_bf16 v[16:19], v[176:179], v[200:203], v[16:19]
	v_mfma_f32_16x16x32_bf16 v[16:19], v[180:183], v[208:211], v[16:19]
	v_mfma_f32_16x16x32_bf16 v[0:3], v[176:179], v[212:215], v[0:3]
	v_mfma_f32_16x16x32_bf16 v[0:3], v[180:183], v[216:219], v[0:3]
	v_mfma_f32_16x16x32_bf16 v[4:7], v[168:171], v[212:215], v[4:7]
	v_mfma_f32_16x16x32_bf16 v[4:7], v[172:175], v[216:219], v[4:7]
	v_mfma_f32_16x16x32_bf16 v[8:11], v[160:163], v[212:215], v[8:11]
	v_mfma_f32_16x16x32_bf16 v[8:11], v[164:167], v[216:219], v[8:11]
	v_mfma_f32_16x16x32_bf16 v[12:15], v[152:155], v[212:215], v[12:15]
	v_mfma_f32_16x16x32_bf16 v[12:15], v[156:159], v[216:219], v[12:15]
	s_setprio 0
	s_barrier
	s_add_i32 s84, 0, 0x18000
	s_add_i32 s85, 0, 0x1c000
	v_add_u32_e32 v164, s84, v148
	v_add_u32_e32 v180, s85, v148
	ds_read_b128 v[152:155], v164
	ds_read_b128 v[156:159], v164 offset:1024
	ds_read_b128 v[160:163], v164 offset:2048
	ds_read_b128 v[164:167], v164 offset:3072
	ds_read_b128 v[168:171], v180
	ds_read_b128 v[172:175], v180 offset:1024
	ds_read_b128 v[176:179], v180 offset:2048
	ds_read_b128 v[180:183], v180 offset:3072
	s_add_u32 s48, s48, 0x10000
	s_addc_u32 s49, s49, 0
	s_mov_b32 m0, s58
	v_lshl_add_u64 v[230:231], s[48:49], 0, v[128:129]
	ds_read_b128 v[184:187], v151 offset:32768
	ds_read_b128 v[188:191], v151 offset:33792
	ds_read_b128 v[192:195], v151 offset:34816
	ds_read_b128 v[196:199], v151 offset:35840
	ds_read_b128 v[200:203], v151 offset:36864
	ds_read_b128 v[208:211], v151 offset:37888
	ds_read_b128 v[212:215], v151 offset:38912
	ds_read_b128 v[216:219], v151 offset:39936
	global_load_lds_dwordx4 v[230:231], off
	v_lshl_add_u64 v[230:231], s[48:49], 0, v[132:133]
	s_mov_b32 m0, s59
	s_nop 0
	global_load_lds_dwordx4 v[230:231], off
	s_waitcnt vmcnt(8)
	s_waitcnt lgkmcnt(0)
	s_barrier
	s_setprio 1
	s_waitcnt lgkmcnt(0)
	v_mfma_f32_16x16x32_bf16 v[120:123], v[152:155], v[184:187], v[120:123]
	v_mfma_f32_16x16x32_bf16 v[120:123], v[156:159], v[188:191], v[120:123]
	v_mfma_f32_16x16x32_bf16 v[124:127], v[160:163], v[184:187], v[124:127]
	v_mfma_f32_16x16x32_bf16 v[124:127], v[164:167], v[188:191], v[124:127]
	v_mfma_f32_16x16x32_bf16 v[116:119], v[168:171], v[184:187], v[116:119]
	v_mfma_f32_16x16x32_bf16 v[116:119], v[172:175], v[188:191], v[116:119]
	v_mfma_f32_16x16x32_bf16 v[112:115], v[176:179], v[184:187], v[112:115]
	v_mfma_f32_16x16x32_bf16 v[112:115], v[180:183], v[188:191], v[112:115]
	v_mfma_f32_16x16x32_bf16 v[96:99], v[176:179], v[192:195], v[96:99]
	v_mfma_f32_16x16x32_bf16 v[96:99], v[180:183], v[196:199], v[96:99]
	v_mfma_f32_16x16x32_bf16 v[100:103], v[168:171], v[192:195], v[100:103]
	v_mfma_f32_16x16x32_bf16 v[100:103], v[172:175], v[196:199], v[100:103]
	v_mfma_f32_16x16x32_bf16 v[104:107], v[160:163], v[192:195], v[104:107]
	v_mfma_f32_16x16x32_bf16 v[104:107], v[164:167], v[196:199], v[104:107]
	v_mfma_f32_16x16x32_bf16 v[108:111], v[152:155], v[192:195], v[108:111]
	v_mfma_f32_16x16x32_bf16 v[108:111], v[156:159], v[196:199], v[108:111]
	s_setprio 0
	s_setprio 1
	v_mfma_f32_16x16x32_bf16 v[92:95], v[152:155], v[200:203], v[92:95]
	v_mfma_f32_16x16x32_bf16 v[92:95], v[156:159], v[208:211], v[92:95]
	v_mfma_f32_16x16x32_bf16 v[88:91], v[160:163], v[200:203], v[88:91]
	v_mfma_f32_16x16x32_bf16 v[88:91], v[164:167], v[208:211], v[88:91]
	v_mfma_f32_16x16x32_bf16 v[84:87], v[168:171], v[200:203], v[84:87]
	v_mfma_f32_16x16x32_bf16 v[84:87], v[172:175], v[208:211], v[84:87]
	v_mfma_f32_16x16x32_bf16 v[80:83], v[176:179], v[200:203], v[80:83]
	v_mfma_f32_16x16x32_bf16 v[80:83], v[180:183], v[208:211], v[80:83]
	v_mfma_f32_16x16x32_bf16 v[64:67], v[176:179], v[212:215], v[64:67]
	v_mfma_f32_16x16x32_bf16 v[64:67], v[180:183], v[216:219], v[64:67]
	v_mfma_f32_16x16x32_bf16 v[68:71], v[168:171], v[212:215], v[68:71]
	v_mfma_f32_16x16x32_bf16 v[68:71], v[172:175], v[216:219], v[68:71]
	v_mfma_f32_16x16x32_bf16 v[72:75], v[160:163], v[212:215], v[72:75]
	v_mfma_f32_16x16x32_bf16 v[72:75], v[164:167], v[216:219], v[72:75]
	v_mfma_f32_16x16x32_bf16 v[76:79], v[152:155], v[212:215], v[76:79]
	v_mfma_f32_16x16x32_bf16 v[76:79], v[156:159], v[216:219], v[76:79]
	s_setprio 0
	s_barrier
; #define PG8_STAGE(bufoff, gbase, voff) do { _Pragma("unroll") for (int _i = 0; _i < 2; ++_i) \
;         __builtin_amdgcn_global_load_lds((const unsigned*)((const char*)(gbase) + (voff)[_i]), (LAS unsigned*)(lds + (bufoff) + ldsw + _i * 8192), 16, 0, 0); } while (0)
; #define PG8_LDA(dst, b, h) do { _Pragma("unroll") for (int m = 0; m < 4; ++m) _Pragma("unroll") for (int k = 0; k < 2; ++k) dst[m][k] = *(const LAS bf16x8*)(lds + PG8_SA(b, h) + aoff + m * 2048 + k * 1024); } while (0)
; #define PG8_MMA(ai, bj, At, Bt) do { __builtin_amdgcn_s_setprio(1); _Pragma("unroll") for (int m = 0; m < 4; ++m) _Pragma("unroll") for (int n = 0; n < 2; ++n) _Pragma("unroll") for (int k = 0; k < 2; ++k) \
;         acc[ai][bj][m][n] = __builtin_amdgcn_mfma_f32_16x16x32_bf16(Bt[n][k], At[m][k], acc[ai][bj][m][n], 0, 0, 0); __builtin_amdgcn_s_setprio(0); } while (0)
; #define PG8_WAIT_V(n) asm volatile("s_waitcnt vmcnt(" #n ")" ::: "memory")
; #define PG8_WAIT_L(n) asm volatile("s_waitcnt lgkmcnt(" #n ")" ::: "memory")
; #define PG8_BAR __builtin_amdgcn_s_barrier()
; #define PG8_SCHED __builtin_amdgcn_sched_barrier(0)
; template <class Epi>
; __device__ __forceinline__ void gemm_phase(LAS unsigned char* lds, const Gemm g, const StaticOrder& S, const Epi& E) {
;     ...
;             PG8_LDA(At, 1, 1); PG8_STAGE(PG8_SB(1, 0), b3, voffB); PG8_STAGE(PG8_SB(1, 1), b3 + hstepB, voffB); PG8_STAGE(PG8_SA(1, 0), a3, voffA);
;             PG8_WAIT_V(8); PG8_WAIT_L(0); PG8_BAR; PG8_MMA(1, 0, At, B0); PG8_MMA(1, 1, At, B1); PG8_BAR; PG8_SCHED;
;         }
	s_add_i32 s48, s84, s51
	v_lshl_add_u64 v[220:221], v[220:221], 0, s[12:13]
	s_mov_b32 m0, s48
	ds_read_b128 v[184:187], v151 offset:49152
	ds_read_b128 v[188:191], v151 offset:50176
	ds_read_b128 v[192:195], v151 offset:51200
	ds_read_b128 v[196:199], v151 offset:52224
	ds_read_b128 v[200:203], v151 offset:53248
	ds_read_b128 v[208:211], v151 offset:54272
	ds_read_b128 v[212:215], v151 offset:55296
	ds_read_b128 v[216:219], v151 offset:56320
	global_load_lds_dwordx4 v[220:221], off
	s_add_i32 m0, s48, 0x2000
	s_add_u32 s46, s46, 0x10080
	v_lshl_add_u64 v[220:221], v[222:223], 0, s[12:13]
	s_addc_u32 s47, s47, 0
	s_add_i32 s48, s85, s51
	global_load_lds_dwordx4 v[220:221], off
	v_lshl_add_u64 v[220:221], s[46:47], 0, v[130:131]
	s_mov_b32 m0, s48
	s_nop 0
	global_load_lds_dwordx4 v[220:221], off
	v_lshl_add_u64 v[220:221], s[46:47], 0, v[134:135]
	s_add_i32 m0, s48, 0x2000
	s_nop 0
	global_load_lds_dwordx4 v[220:221], off
	v_lshl_add_u64 v[220:221], v[224:225], 0, s[12:13]
	s_mov_b32 m0, s63
	s_nop 0
	global_load_lds_dwordx4 v[220:221], off
	v_lshl_add_u64 v[220:221], v[226:227], 0, s[12:13]
	s_mov_b32 m0, s64
	s_nop 0
	global_load_lds_dwordx4 v[220:221], off
	s_waitcnt vmcnt(8)
	s_waitcnt lgkmcnt(0)
	s_barrier
	s_setprio 1
	s_waitcnt lgkmcnt(0)
	v_mfma_f32_16x16x32_bf16 v[60:63], v[152:155], v[184:187], v[60:63]
	v_mfma_f32_16x16x32_bf16 v[60:63], v[156:159], v[188:191], v[60:63]
	v_mfma_f32_16x16x32_bf16 v[56:59], v[160:163], v[184:187], v[56:59]
	v_mfma_f32_16x16x32_bf16 v[56:59], v[164:167], v[188:191], v[56:59]
	v_mfma_f32_16x16x32_bf16 v[52:55], v[168:171], v[184:187], v[52:55]
	v_mfma_f32_16x16x32_bf16 v[52:55], v[172:175], v[188:191], v[52:55]
	v_mfma_f32_16x16x32_bf16 v[48:51], v[176:179], v[184:187], v[48:51]
	v_mfma_f32_16x16x32_bf16 v[48:51], v[180:183], v[188:191], v[48:51]
	v_mfma_f32_16x16x32_bf16 v[32:35], v[176:179], v[192:195], v[32:35]
	v_mfma_f32_16x16x32_bf16 v[32:35], v[180:183], v[196:199], v[32:35]
	v_mfma_f32_16x16x32_bf16 v[36:39], v[168:171], v[192:195], v[36:39]
	v_mfma_f32_16x16x32_bf16 v[36:39], v[172:175], v[196:199], v[36:39]
	v_mfma_f32_16x16x32_bf16 v[40:43], v[160:163], v[192:195], v[40:43]
	v_mfma_f32_16x16x32_bf16 v[40:43], v[164:167], v[196:199], v[40:43]
	v_mfma_f32_16x16x32_bf16 v[44:47], v[152:155], v[192:195], v[44:47]
	v_mfma_f32_16x16x32_bf16 v[44:47], v[156:159], v[196:199], v[44:47]
	s_setprio 0
	s_setprio 1
	v_mfma_f32_16x16x32_bf16 v[28:31], v[152:155], v[200:203], v[28:31]
	v_mfma_f32_16x16x32_bf16 v[28:31], v[156:159], v[208:211], v[28:31]
	v_mfma_f32_16x16x32_bf16 v[24:27], v[160:163], v[200:203], v[24:27]
	v_mfma_f32_16x16x32_bf16 v[24:27], v[164:167], v[208:211], v[24:27]
	v_mfma_f32_16x16x32_bf16 v[20:23], v[168:171], v[200:203], v[20:23]
	v_mfma_f32_16x16x32_bf16 v[20:23], v[172:175], v[208:211], v[20:23]
	v_mfma_f32_16x16x32_bf16 v[16:19], v[176:179], v[200:203], v[16:19]
	v_mfma_f32_16x16x32_bf16 v[16:19], v[180:183], v[208:211], v[16:19]
	v_mfma_f32_16x16x32_bf16 v[0:3], v[176:179], v[212:215], v[0:3]
	v_mfma_f32_16x16x32_bf16 v[0:3], v[180:183], v[216:219], v[0:3]
	v_mfma_f32_16x16x32_bf16 v[4:7], v[168:171], v[212:215], v[4:7]
	v_mfma_f32_16x16x32_bf16 v[4:7], v[172:175], v[216:219], v[4:7]
	v_mfma_f32_16x16x32_bf16 v[8:11], v[160:163], v[212:215], v[8:11]
	v_mfma_f32_16x16x32_bf16 v[8:11], v[164:167], v[216:219], v[8:11]
	v_mfma_f32_16x16x32_bf16 v[12:15], v[152:155], v[212:215], v[12:15]
	v_mfma_f32_16x16x32_bf16 v[12:15], v[156:159], v[216:219], v[12:15]
	s_setprio 0
	s_barrier
	s_add_u32 s44, s44, 0x100
	s_addc_u32 s45, s45, 0
	s_add_u32 s79, s79, 0x100
	s_addc_u32 s82, s82, 0
	s_cmp_ge_i32 s83, s61
	s_mov_b32 s46, s83
	s_cbranch_scc0 .LBB0_1161

; #define PG8_STAGE(bufoff, gbase, voff) do { _Pragma("unroll") for (int _i = 0; _i < 2; ++_i) \
;         __builtin_amdgcn_global_load_lds((const unsigned*)((const char*)(gbase) + (voff)[_i]), (LAS unsigned*)(lds + (bufoff) + ldsw + _i * 8192), 16, 0, 0); } while (0)
; #define PG8_LDA(dst, b, h) do { _Pragma("unroll") for (int m = 0; m < 4; ++m) _Pragma("unroll") for (int k = 0; k < 2; ++k) dst[m][k] = *(const LAS bf16x8*)(lds + PG8_SA(b, h) + aoff + m * 2048 + k * 1024); } while (0)
; #define PG8_LDB(dst, b, h) do { _Pragma("unroll") for (int n = 0; n < 2; ++n) _Pragma("unroll") for (int k = 0; k < 2; ++k) dst[n][k] = *(const LAS bf16x8*)(lds + PG8_SB(b, h) + boff + n * 2048 + k * 1024); } while (0)
; #define PG8_MMA(ai, bj, At, Bt) do { __builtin_amdgcn_s_setprio(1); _Pragma("unroll") for (int m = 0; m < 4; ++m) _Pragma("unroll") for (int n = 0; n < 2; ++n) _Pragma("unroll") for (int k = 0; k < 2; ++k) \
;         acc[ai][bj][m][n] = __builtin_amdgcn_mfma_f32_16x16x32_bf16(Bt[n][k], At[m][k], acc[ai][bj][m][n], 0, 0, 0); __builtin_amdgcn_s_setprio(0); } while (0)
; #define PG8_WAIT_V(n) asm volatile("s_waitcnt vmcnt(" #n ")" ::: "memory")
; #define PG8_WAIT_L(n) asm volatile("s_waitcnt lgkmcnt(" #n ")" ::: "memory")
; #define PG8_BAR __builtin_amdgcn_s_barrier()
; #define PG8_SCHED __builtin_amdgcn_sched_barrier(0)
; template <class Epi>
; __device__ __forceinline__ void gemm_phase(LAS unsigned char* lds, const Gemm g, const StaticOrder& S, const Epi& E) {
;     ...
;             const char* a2 = last ? nA : cA + (size_t)(t + 2) * kstep; const char* b2 = last ? nB : cB + (size_t)(t + 2) * kstep;
;             const char* a3 = a2 + kstep; const char* b3 = b2 + kstep;
;             PG8_LDB(B0, 0, 0); PG8_LDB(B1, 0, 1); PG8_SCHED; PG8_LDA(At, 0, 0); PG8_STAGE(PG8_SA(1, 1), a1 + hstepA, voffA);
;             PG8_WAIT_V(8); PG8_WAIT_L(0); PG8_BAR; PG8_MMA(0, 0, At, B0); PG8_MMA(0, 1, At, B1); PG8_BAR; PG8_SCHED;
;             PG8_LDA(At, 0, 1); PG8_STAGE(PG8_SB(0, 0), b2, voffB); PG8_STAGE(PG8_SB(0, 1), b2 + hstepB, voffB); PG8_STAGE(PG8_SA(0, 0), a2, voffA);
;             PG8_WAIT_V(8); PG8_WAIT_L(0); PG8_BAR; PG8_MMA(1, 0, At, B0); PG8_MMA(1, 1, At, B1); PG8_BAR; PG8_SCHED;
.LBB0_1244:
	ds_read_b128 v[150:153], v187
	ds_read_b128 v[154:157], v187 offset:1024
	ds_read_b128 v[158:161], v187 offset:2048
	ds_read_b128 v[162:165], v187 offset:3072
	ds_read_b128 v[166:169], v188
	ds_read_b128 v[170:173], v188 offset:1024
	ds_read_b128 v[174:177], v188 offset:2048
	ds_read_b128 v[178:181], v188 offset:3072
	s_add_i32 s84, s52, 2
	s_add_u32 s12, s4, 0x100
	s_addc_u32 s13, s5, 0
	s_cmp_eq_u32 s67, s52
	s_cselect_b32 s52, s50, s1
	s_cselect_b32 s55, s49, s13
	s_cselect_b32 s54, s48, s12
	s_cselect_b32 s53, s51, s77
	v_lshl_add_u64 v[224:225], s[4:5], 0, v[142:143]
	s_add_i32 m0, s59, 0xc000
	ds_read_b128 v[182:185], v189
	ds_read_b128 v[192:195], v189 offset:1024
	ds_read_b128 v[196:199], v189 offset:2048
	ds_read_b128 v[200:203], v189 offset:3072
	ds_read_b128 v[208:211], v189 offset:4096
	ds_read_b128 v[212:215], v189 offset:5120
	ds_read_b128 v[216:219], v189 offset:6144
	ds_read_b128 v[220:223], v189 offset:7168
	global_load_lds_dwordx4 v[224:225], off
	v_lshl_add_u64 v[224:225], s[4:5], 0, v[144:145]
	s_add_i32 m0, s59, 0xe000
	s_nop 0
	global_load_lds_dwordx4 v[224:225], off
	s_waitcnt vmcnt(8)
	s_waitcnt lgkmcnt(0)
	s_barrier
	s_setprio 1
	s_waitcnt lgkmcnt(0)
	v_mfma_f32_16x16x32_bf16 v[124:127], v[150:153], v[182:185], v[124:127]
	v_mfma_f32_16x16x32_bf16 v[124:127], v[154:157], v[192:195], v[124:127]
	v_mfma_f32_16x16x32_bf16 v[120:123], v[158:161], v[182:185], v[120:123]
	v_mfma_f32_16x16x32_bf16 v[120:123], v[162:165], v[192:195], v[120:123]
	v_mfma_f32_16x16x32_bf16 v[108:111], v[166:169], v[182:185], v[108:111]
	v_mfma_f32_16x16x32_bf16 v[108:111], v[170:173], v[192:195], v[108:111]
	v_mfma_f32_16x16x32_bf16 v[100:103], v[174:177], v[182:185], v[100:103]
	v_mfma_f32_16x16x32_bf16 v[100:103], v[178:181], v[192:195], v[100:103]
	v_mfma_f32_16x16x32_bf16 v[84:87], v[174:177], v[196:199], v[84:87]
	v_mfma_f32_16x16x32_bf16 v[84:87], v[178:181], v[200:203], v[84:87]
	v_mfma_f32_16x16x32_bf16 v[92:95], v[166:169], v[196:199], v[92:95]
	v_mfma_f32_16x16x32_bf16 v[92:95], v[170:173], v[200:203], v[92:95]
	v_mfma_f32_16x16x32_bf16 v[112:115], v[158:161], v[196:199], v[112:115]
	v_mfma_f32_16x16x32_bf16 v[112:115], v[162:165], v[200:203], v[112:115]
	v_mfma_f32_16x16x32_bf16 v[116:119], v[150:153], v[196:199], v[116:119]
	v_mfma_f32_16x16x32_bf16 v[116:119], v[154:157], v[200:203], v[116:119]
	s_setprio 0
	s_setprio 1
	v_mfma_f32_16x16x32_bf16 v[104:107], v[150:153], v[208:211], v[104:107]
	v_mfma_f32_16x16x32_bf16 v[104:107], v[154:157], v[212:215], v[104:107]
	v_mfma_f32_16x16x32_bf16 v[96:99], v[158:161], v[208:211], v[96:99]
	v_mfma_f32_16x16x32_bf16 v[96:99], v[162:165], v[212:215], v[96:99]
	v_mfma_f32_16x16x32_bf16 v[76:79], v[166:169], v[208:211], v[76:79]
	v_mfma_f32_16x16x32_bf16 v[76:79], v[170:173], v[212:215], v[76:79]
	v_mfma_f32_16x16x32_bf16 v[72:75], v[174:177], v[208:211], v[72:75]
	v_mfma_f32_16x16x32_bf16 v[72:75], v[178:181], v[212:215], v[72:75]
	v_mfma_f32_16x16x32_bf16 v[64:67], v[174:177], v[216:219], v[64:67]
	v_mfma_f32_16x16x32_bf16 v[64:67], v[178:181], v[220:223], v[64:67]
	v_mfma_f32_16x16x32_bf16 v[68:71], v[166:169], v[216:219], v[68:71]
	v_mfma_f32_16x16x32_bf16 v[68:71], v[170:173], v[220:223], v[68:71]
	v_mfma_f32_16x16x32_bf16 v[80:83], v[158:161], v[216:219], v[80:83]
	v_mfma_f32_16x16x32_bf16 v[80:83], v[162:165], v[220:223], v[80:83]
	v_mfma_f32_16x16x32_bf16 v[88:91], v[150:153], v[216:219], v[88:91]
	v_mfma_f32_16x16x32_bf16 v[88:91], v[154:157], v[220:223], v[88:91]
	s_setprio 0
	s_barrier
	s_add_i32 s4, s70, s58
	v_lshl_add_u64 v[224:225], s[52:53], 0, v[130:131]
	s_mov_b32 m0, s4
	ds_read_b128 v[182:185], v189 offset:16384
	ds_read_b128 v[192:195], v189 offset:17408
	ds_read_b128 v[196:199], v189 offset:18432
	ds_read_b128 v[200:203], v189 offset:19456
	ds_read_b128 v[208:211], v189 offset:20480
	ds_read_b128 v[212:215], v189 offset:21504
	ds_read_b128 v[216:219], v189 offset:22528
	ds_read_b128 v[220:223], v189 offset:23552
	global_load_lds_dwordx4 v[224:225], off
	s_add_i32 m0, s4, 0x2000
	s_add_u32 s4, s52, 0x158000
	v_lshl_add_u64 v[226:227], s[52:53], 0, v[134:135]
	s_addc_u32 s5, s53, 0
	s_add_i32 s85, s71, s58
	global_load_lds_dwordx4 v[226:227], off
	v_lshl_add_u64 v[230:231], s[4:5], 0, v[130:131]
	s_mov_b32 m0, s85
	v_lshl_add_u64 v[232:233], s[54:55], 0, v[132:133]
	global_load_lds_dwordx4 v[230:231], off
	v_lshl_add_u64 v[230:231], s[4:5], 0, v[134:135]
	s_add_i32 m0, s85, 0x2000
	s_nop 0
	global_load_lds_dwordx4 v[230:231], off
	v_lshl_add_u64 v[230:231], s[54:55], 0, v[128:129]
	s_mov_b32 m0, s59
	s_nop 0
	global_load_lds_dwordx4 v[230:231], off
	s_mov_b32 m0, s60
	s_nop 0
	global_load_lds_dwordx4 v[232:233], off
	s_waitcnt vmcnt(8)
	s_waitcnt lgkmcnt(0)
	s_barrier
; #define PG8_STAGE(bufoff, gbase, voff) do { _Pragma("unroll") for (int _i = 0; _i < 2; ++_i) \
;         __builtin_amdgcn_global_load_lds((const unsigned*)((const char*)(gbase) + (voff)[_i]), (LAS unsigned*)(lds + (bufoff) + ldsw + _i * 8192), 16, 0, 0); } while (0)
; #define PG8_LDA(dst, b, h) do { _Pragma("unroll") for (int m = 0; m < 4; ++m) _Pragma("unroll") for (int k = 0; k < 2; ++k) dst[m][k] = *(const LAS bf16x8*)(lds + PG8_SA(b, h) + aoff + m * 2048 + k * 1024); } while (0)
; #define PG8_LDB(dst, b, h) do { _Pragma("unroll") for (int n = 0; n < 2; ++n) _Pragma("unroll") for (int k = 0; k < 2; ++k) dst[n][k] = *(const LAS bf16x8*)(lds + PG8_SB(b, h) + boff + n * 2048 + k * 1024); } while (0)
; #define PG8_MMA(ai, bj, At, Bt) do { __builtin_amdgcn_s_setprio(1); _Pragma("unroll") for (int m = 0; m < 4; ++m) _Pragma("unroll") for (int n = 0; n < 2; ++n) _Pragma("unroll") for (int k = 0; k < 2; ++k) \
;         acc[ai][bj][m][n] = __builtin_amdgcn_mfma_f32_16x16x32_bf16(Bt[n][k], At[m][k], acc[ai][bj][m][n], 0, 0, 0); __builtin_amdgcn_s_setprio(0); } while (0)
; #define PG8_WAIT_V(n) asm volatile("s_waitcnt vmcnt(" #n ")" ::: "memory")
; #define PG8_WAIT_L(n) asm volatile("s_waitcnt lgkmcnt(" #n ")" ::: "memory")
; #define PG8_BAR __builtin_amdgcn_s_barrier()
; #define PG8_SCHED __builtin_amdgcn_sched_barrier(0)
; template <class Epi>
; __device__ __forceinline__ void gemm_phase(LAS unsigned char* lds, const Gemm g, const StaticOrder& S, const Epi& E) {
;     ...
;             PG8_WAIT_V(8); PG8_WAIT_L(0); PG8_BAR; PG8_MMA(1, 0, At, B0); PG8_MMA(1, 1, At, B1); PG8_BAR; PG8_SCHED;
;             PG8_LDB(B0, 1, 0); PG8_LDB(B1, 1, 1); PG8_SCHED; PG8_LDA(At, 1, 0); PG8_STAGE(PG8_SA(0, 1), a2 + hstepA, voffA);
;             PG8_WAIT_V(8); PG8_WAIT_L(0); PG8_BAR; PG8_MMA(0, 0, At, B0); PG8_MMA(0, 1, At, B1); PG8_BAR; PG8_SCHED;
	s_setprio 1
	s_waitcnt lgkmcnt(0)
	v_mfma_f32_16x16x32_bf16 v[60:63], v[150:153], v[182:185], v[60:63]
	v_mfma_f32_16x16x32_bf16 v[60:63], v[154:157], v[192:195], v[60:63]
	v_mfma_f32_16x16x32_bf16 v[56:59], v[158:161], v[182:185], v[56:59]
	v_mfma_f32_16x16x32_bf16 v[56:59], v[162:165], v[192:195], v[56:59]
	v_mfma_f32_16x16x32_bf16 v[44:47], v[166:169], v[182:185], v[44:47]
	v_mfma_f32_16x16x32_bf16 v[44:47], v[170:173], v[192:195], v[44:47]
	v_mfma_f32_16x16x32_bf16 v[36:39], v[174:177], v[182:185], v[36:39]
	v_mfma_f32_16x16x32_bf16 v[36:39], v[178:181], v[192:195], v[36:39]
	v_mfma_f32_16x16x32_bf16 v[20:23], v[174:177], v[196:199], v[20:23]
	v_mfma_f32_16x16x32_bf16 v[20:23], v[178:181], v[200:203], v[20:23]
	v_mfma_f32_16x16x32_bf16 v[28:31], v[166:169], v[196:199], v[28:31]
	v_mfma_f32_16x16x32_bf16 v[28:31], v[170:173], v[200:203], v[28:31]
	v_mfma_f32_16x16x32_bf16 v[48:51], v[158:161], v[196:199], v[48:51]
	v_mfma_f32_16x16x32_bf16 v[48:51], v[162:165], v[200:203], v[48:51]
	v_mfma_f32_16x16x32_bf16 v[52:55], v[150:153], v[196:199], v[52:55]
	v_mfma_f32_16x16x32_bf16 v[52:55], v[154:157], v[200:203], v[52:55]
	s_setprio 0
	s_setprio 1
	v_mfma_f32_16x16x32_bf16 v[40:43], v[150:153], v[208:211], v[40:43]
	v_mfma_f32_16x16x32_bf16 v[40:43], v[154:157], v[212:215], v[40:43]
	v_mfma_f32_16x16x32_bf16 v[32:35], v[158:161], v[208:211], v[32:35]
	v_mfma_f32_16x16x32_bf16 v[32:35], v[162:165], v[212:215], v[32:35]
	v_mfma_f32_16x16x32_bf16 v[12:15], v[166:169], v[208:211], v[12:15]
	v_mfma_f32_16x16x32_bf16 v[12:15], v[170:173], v[212:215], v[12:15]
	v_mfma_f32_16x16x32_bf16 v[8:11], v[174:177], v[208:211], v[8:11]
	v_mfma_f32_16x16x32_bf16 v[8:11], v[178:181], v[212:215], v[8:11]
	v_mfma_f32_16x16x32_bf16 v[0:3], v[174:177], v[216:219], v[0:3]
	v_mfma_f32_16x16x32_bf16 v[0:3], v[178:181], v[220:223], v[0:3]
	v_mfma_f32_16x16x32_bf16 v[4:7], v[166:169], v[216:219], v[4:7]
	v_mfma_f32_16x16x32_bf16 v[4:7], v[170:173], v[220:223], v[4:7]
	v_mfma_f32_16x16x32_bf16 v[16:19], v[158:161], v[216:219], v[16:19]
	v_mfma_f32_16x16x32_bf16 v[16:19], v[162:165], v[220:223], v[16:19]
	v_mfma_f32_16x16x32_bf16 v[24:27], v[150:153], v[216:219], v[24:27]
	v_mfma_f32_16x16x32_bf16 v[24:27], v[154:157], v[220:223], v[24:27]
	s_setprio 0
	s_barrier
	s_add_i32 s85, 0, 0x18000
	s_add_i32 s86, 0, 0x1c000
	v_add_u32_e32 v162, s85, v186
	v_add_u32_e32 v178, s86, v186
	ds_read_b128 v[150:153], v162
	ds_read_b128 v[154:157], v162 offset:1024
	ds_read_b128 v[158:161], v162 offset:2048
	ds_read_b128 v[162:165], v162 offset:3072
	ds_read_b128 v[166:169], v178
	ds_read_b128 v[170:173], v178 offset:1024
	ds_read_b128 v[174:177], v178 offset:2048
	ds_read_b128 v[178:181], v178 offset:3072
	s_add_u32 s4, s54, 0x158000
	s_addc_u32 s5, s55, 0
	s_mov_b32 m0, s61
	v_lshl_add_u64 v[234:235], s[4:5], 0, v[128:129]
	ds_read_b128 v[182:185], v189 offset:32768
	ds_read_b128 v[192:195], v189 offset:33792
	ds_read_b128 v[196:199], v189 offset:34816
	ds_read_b128 v[200:203], v189 offset:35840
	ds_read_b128 v[208:211], v189 offset:36864
	ds_read_b128 v[212:215], v189 offset:37888
	ds_read_b128 v[216:219], v189 offset:38912
	ds_read_b128 v[220:223], v189 offset:39936
	global_load_lds_dwordx4 v[234:235], off
	v_lshl_add_u64 v[234:235], s[4:5], 0, v[132:133]
	s_mov_b32 m0, s62
	s_nop 0
	global_load_lds_dwordx4 v[234:235], off
	s_waitcnt vmcnt(8)
	s_waitcnt lgkmcnt(0)
	s_barrier
	s_setprio 1
	s_waitcnt lgkmcnt(0)
	v_mfma_f32_16x16x32_bf16 v[124:127], v[150:153], v[182:185], v[124:127]
	v_mfma_f32_16x16x32_bf16 v[124:127], v[154:157], v[192:195], v[124:127]
	v_mfma_f32_16x16x32_bf16 v[120:123], v[158:161], v[182:185], v[120:123]
	v_mfma_f32_16x16x32_bf16 v[120:123], v[162:165], v[192:195], v[120:123]
	v_mfma_f32_16x16x32_bf16 v[108:111], v[166:169], v[182:185], v[108:111]
	v_mfma_f32_16x16x32_bf16 v[108:111], v[170:173], v[192:195], v[108:111]
	v_mfma_f32_16x16x32_bf16 v[100:103], v[174:177], v[182:185], v[100:103]
	v_mfma_f32_16x16x32_bf16 v[100:103], v[178:181], v[192:195], v[100:103]
	v_mfma_f32_16x16x32_bf16 v[84:87], v[174:177], v[196:199], v[84:87]
	v_mfma_f32_16x16x32_bf16 v[84:87], v[178:181], v[200:203], v[84:87]
	v_mfma_f32_16x16x32_bf16 v[92:95], v[166:169], v[196:199], v[92:95]
	v_mfma_f32_16x16x32_bf16 v[92:95], v[170:173], v[200:203], v[92:95]
	v_mfma_f32_16x16x32_bf16 v[112:115], v[158:161], v[196:199], v[112:115]
	v_mfma_f32_16x16x32_bf16 v[112:115], v[162:165], v[200:203], v[112:115]
	v_mfma_f32_16x16x32_bf16 v[116:119], v[150:153], v[196:199], v[116:119]
	v_mfma_f32_16x16x32_bf16 v[116:119], v[154:157], v[200:203], v[116:119]
	s_setprio 0
	s_setprio 1
	v_mfma_f32_16x16x32_bf16 v[104:107], v[150:153], v[208:211], v[104:107]
	v_mfma_f32_16x16x32_bf16 v[104:107], v[154:157], v[212:215], v[104:107]
	v_mfma_f32_16x16x32_bf16 v[96:99], v[158:161], v[208:211], v[96:99]
	v_mfma_f32_16x16x32_bf16 v[96:99], v[162:165], v[212:215], v[96:99]
	v_mfma_f32_16x16x32_bf16 v[76:79], v[166:169], v[208:211], v[76:79]
	v_mfma_f32_16x16x32_bf16 v[76:79], v[170:173], v[212:215], v[76:79]
	v_mfma_f32_16x16x32_bf16 v[72:75], v[174:177], v[208:211], v[72:75]
	v_mfma_f32_16x16x32_bf16 v[72:75], v[178:181], v[212:215], v[72:75]
	v_mfma_f32_16x16x32_bf16 v[64:67], v[174:177], v[216:219], v[64:67]
	v_mfma_f32_16x16x32_bf16 v[64:67], v[178:181], v[220:223], v[64:67]
	v_mfma_f32_16x16x32_bf16 v[68:71], v[166:169], v[216:219], v[68:71]
	v_mfma_f32_16x16x32_bf16 v[68:71], v[170:173], v[220:223], v[68:71]
	v_mfma_f32_16x16x32_bf16 v[80:83], v[158:161], v[216:219], v[80:83]
	v_mfma_f32_16x16x32_bf16 v[80:83], v[162:165], v[220:223], v[80:83]
	v_mfma_f32_16x16x32_bf16 v[88:91], v[150:153], v[216:219], v[88:91]
	v_mfma_f32_16x16x32_bf16 v[88:91], v[154:157], v[220:223], v[88:91]
	s_setprio 0
	s_barrier
; #define PG8_STAGE(bufoff, gbase, voff) do { _Pragma("unroll") for (int _i = 0; _i < 2; ++_i) \
;         __builtin_amdgcn_global_load_lds((const unsigned*)((const char*)(gbase) + (voff)[_i]), (LAS unsigned*)(lds + (bufoff) + ldsw + _i * 8192), 16, 0, 0); } while (0)
; #define PG8_LDA(dst, b, h) do { _Pragma("unroll") for (int m = 0; m < 4; ++m) _Pragma("unroll") for (int k = 0; k < 2; ++k) dst[m][k] = *(const LAS bf16x8*)(lds + PG8_SA(b, h) + aoff + m * 2048 + k * 1024); } while (0)
; #define PG8_MMA(ai, bj, At, Bt) do { __builtin_amdgcn_s_setprio(1); _Pragma("unroll") for (int m = 0; m < 4; ++m) _Pragma("unroll") for (int n = 0; n < 2; ++n) _Pragma("unroll") for (int k = 0; k < 2; ++k) \
;         acc[ai][bj][m][n] = __builtin_amdgcn_mfma_f32_16x16x32_bf16(Bt[n][k], At[m][k], acc[ai][bj][m][n], 0, 0, 0); __builtin_amdgcn_s_setprio(0); } while (0)
; #define PG8_WAIT_V(n) asm volatile("s_waitcnt vmcnt(" #n ")" ::: "memory")
; #define PG8_WAIT_L(n) asm volatile("s_waitcnt lgkmcnt(" #n ")" ::: "memory")
; #define PG8_BAR __builtin_amdgcn_s_barrier()
; #define PG8_SCHED __builtin_amdgcn_sched_barrier(0)
; template <class Epi>
; __device__ __forceinline__ void gemm_phase(LAS unsigned char* lds, const Gemm g, const StaticOrder& S, const Epi& E) {
;     ...
;             PG8_LDA(At, 1, 1); PG8_STAGE(PG8_SB(1, 0), b3, voffB); PG8_STAGE(PG8_SB(1, 1), b3 + hstepB, voffB); PG8_STAGE(PG8_SA(1, 0), a3, voffA);
;             PG8_WAIT_V(8); PG8_WAIT_L(0); PG8_BAR; PG8_MMA(1, 0, At, B0); PG8_MMA(1, 1, At, B1); PG8_BAR; PG8_SCHED;
;         }
	s_add_i32 s4, s85, s58
	v_lshl_add_u64 v[224:225], v[224:225], 0, s[16:17]
	s_mov_b32 m0, s4
	ds_read_b128 v[182:185], v189 offset:49152
	ds_read_b128 v[192:195], v189 offset:50176
	ds_read_b128 v[196:199], v189 offset:51200
	ds_read_b128 v[200:203], v189 offset:52224
	ds_read_b128 v[208:211], v189 offset:53248
	ds_read_b128 v[212:215], v189 offset:54272
	ds_read_b128 v[216:219], v189 offset:55296
	ds_read_b128 v[220:223], v189 offset:56320
	global_load_lds_dwordx4 v[224:225], off
	s_add_i32 m0, s4, 0x2000
	s_add_u32 s4, s52, 0x158080
	v_lshl_add_u64 v[224:225], v[226:227], 0, s[16:17]
	s_addc_u32 s5, s53, 0
	s_add_i32 s52, s86, s58
	global_load_lds_dwordx4 v[224:225], off
	v_lshl_add_u64 v[224:225], s[4:5], 0, v[130:131]
	s_mov_b32 m0, s52
	s_nop 0
	global_load_lds_dwordx4 v[224:225], off
	v_lshl_add_u64 v[224:225], s[4:5], 0, v[134:135]
	s_add_i32 m0, s52, 0x2000
	s_nop 0
	global_load_lds_dwordx4 v[224:225], off
	v_lshl_add_u64 v[224:225], v[230:231], 0, s[16:17]
	s_mov_b32 m0, s65
	s_nop 0
	global_load_lds_dwordx4 v[224:225], off
	v_lshl_add_u64 v[224:225], v[232:233], 0, s[16:17]
	s_mov_b32 m0, s66
	s_nop 0
	global_load_lds_dwordx4 v[224:225], off
	s_waitcnt vmcnt(8)
	s_waitcnt lgkmcnt(0)
	s_barrier
	s_setprio 1
	s_waitcnt lgkmcnt(0)
	v_mfma_f32_16x16x32_bf16 v[60:63], v[150:153], v[182:185], v[60:63]
	v_mfma_f32_16x16x32_bf16 v[60:63], v[154:157], v[192:195], v[60:63]
	v_mfma_f32_16x16x32_bf16 v[56:59], v[158:161], v[182:185], v[56:59]
	v_mfma_f32_16x16x32_bf16 v[56:59], v[162:165], v[192:195], v[56:59]
	v_mfma_f32_16x16x32_bf16 v[44:47], v[166:169], v[182:185], v[44:47]
	v_mfma_f32_16x16x32_bf16 v[44:47], v[170:173], v[192:195], v[44:47]
	v_mfma_f32_16x16x32_bf16 v[36:39], v[174:177], v[182:185], v[36:39]
	v_mfma_f32_16x16x32_bf16 v[36:39], v[178:181], v[192:195], v[36:39]
	v_mfma_f32_16x16x32_bf16 v[20:23], v[174:177], v[196:199], v[20:23]
	v_mfma_f32_16x16x32_bf16 v[20:23], v[178:181], v[200:203], v[20:23]
	v_mfma_f32_16x16x32_bf16 v[28:31], v[166:169], v[196:199], v[28:31]
	v_mfma_f32_16x16x32_bf16 v[28:31], v[170:173], v[200:203], v[28:31]
	v_mfma_f32_16x16x32_bf16 v[48:51], v[158:161], v[196:199], v[48:51]
	v_mfma_f32_16x16x32_bf16 v[48:51], v[162:165], v[200:203], v[48:51]
	v_mfma_f32_16x16x32_bf16 v[52:55], v[150:153], v[196:199], v[52:55]
	v_mfma_f32_16x16x32_bf16 v[52:55], v[154:157], v[200:203], v[52:55]
	s_setprio 0
	s_setprio 1
	v_mfma_f32_16x16x32_bf16 v[40:43], v[150:153], v[208:211], v[40:43]
	v_mfma_f32_16x16x32_bf16 v[40:43], v[154:157], v[212:215], v[40:43]
	v_mfma_f32_16x16x32_bf16 v[32:35], v[158:161], v[208:211], v[32:35]
	v_mfma_f32_16x16x32_bf16 v[32:35], v[162:165], v[212:215], v[32:35]
	v_mfma_f32_16x16x32_bf16 v[12:15], v[166:169], v[208:211], v[12:15]
	v_mfma_f32_16x16x32_bf16 v[12:15], v[170:173], v[212:215], v[12:15]
	v_mfma_f32_16x16x32_bf16 v[8:11], v[174:177], v[208:211], v[8:11]
	v_mfma_f32_16x16x32_bf16 v[8:11], v[178:181], v[212:215], v[8:11]
	v_mfma_f32_16x16x32_bf16 v[0:3], v[174:177], v[216:219], v[0:3]
	v_mfma_f32_16x16x32_bf16 v[0:3], v[178:181], v[220:223], v[0:3]
	v_mfma_f32_16x16x32_bf16 v[4:7], v[166:169], v[216:219], v[4:7]
	v_mfma_f32_16x16x32_bf16 v[4:7], v[170:173], v[220:223], v[4:7]
	v_mfma_f32_16x16x32_bf16 v[16:19], v[158:161], v[216:219], v[16:19]
	v_mfma_f32_16x16x32_bf16 v[16:19], v[162:165], v[220:223], v[16:19]
	v_mfma_f32_16x16x32_bf16 v[24:27], v[150:153], v[216:219], v[24:27]
	v_mfma_f32_16x16x32_bf16 v[24:27], v[154:157], v[220:223], v[24:27]
	s_setprio 0
	s_barrier
	s_add_u32 s1, s1, 0x100
	s_addc_u32 s77, s77, 0
	s_cmp_ge_i32 s84, s64
	s_mov_b64 s[4:5], s[12:13]
	s_mov_b32 s52, s84
	s_cbranch_scc0 .LBB0_1244
	v_pk_mul_f32 v[170:171], v[126:127], 0.5 op_sel_hi:[1,0]
	v_pk_mul_f32 v[172:173], v[124:125], 0.5 op_sel_hi:[1,0]
	v_pk_mul_f32 v[174:175], v[122:123], 0.5 op_sel_hi:[1,0]
	v_pk_mul_f32 v[176:177], v[120:121], 0.5 op_sel_hi:[1,0]
	v_pk_mul_f32 v[178:179], v[110:111], 0.5 op_sel_hi:[1,0]
	v_pk_mul_f32 v[180:181], v[108:109], 0.5 op_sel_hi:[1,0]
	v_pk_mul_f32 v[182:183], v[102:103], 0.5 op_sel_hi:[1,0]
	v_pk_mul_f32 v[184:185], v[100:101], 0.5 op_sel_hi:[1,0]
	v_pk_mul_f32 v[160:161], v[118:119], 0.5 op_sel_hi:[1,0]
	v_pk_mul_f32 v[158:159], v[116:117], 0.5 op_sel_hi:[1,0]
	v_pk_mul_f32 v[156:157], v[114:115], 0.5 op_sel_hi:[1,0]
	v_pk_mul_f32 v[154:155], v[112:113], 0.5 op_sel_hi:[1,0]
	v_pk_mul_f32 v[168:169], v[94:95], 0.5 op_sel_hi:[1,0]
	v_pk_mul_f32 v[166:167], v[92:93], 0.5 op_sel_hi:[1,0]
	v_pk_mul_f32 v[164:165], v[86:87], 0.5 op_sel_hi:[1,0]
	v_pk_mul_f32 v[162:163], v[84:85], 0.5 op_sel_hi:[1,0]
	v_pk_mul_f32 v[116:117], v[106:107], 0.5 op_sel_hi:[1,0]
	v_pk_mul_f32 v[118:119], v[104:105], 0.5 op_sel_hi:[1,0]
	v_pk_mul_f32 v[120:121], v[98:99], 0.5 op_sel_hi:[1,0]
	v_pk_mul_f32 v[122:123], v[96:97], 0.5 op_sel_hi:[1,0]
	v_pk_mul_f32 v[124:125], v[78:79], 0.5 op_sel_hi:[1,0]
	v_pk_mul_f32 v[126:127], v[76:77], 0.5 op_sel_hi:[1,0]
	v_pk_mul_f32 v[150:151], v[74:75], 0.5 op_sel_hi:[1,0]
	v_pk_mul_f32 v[152:153], v[72:73], 0.5 op_sel_hi:[1,0]
	v_pk_mul_f32 v[104:105], v[90:91], 0.5 op_sel_hi:[1,0]
	v_pk_mul_f32 v[102:103], v[88:89], 0.5 op_sel_hi:[1,0]
	v_pk_mul_f32 v[100:101], v[82:83], 0.5 op_sel_hi:[1,0]
	v_pk_mul_f32 v[98:99], v[80:81], 0.5 op_sel_hi:[1,0]
	v_pk_mul_f32 v[112:113], v[70:71], 0.5 op_sel_hi:[1,0]
	v_pk_mul_f32 v[110:111], v[68:69], 0.5 op_sel_hi:[1,0]
	v_pk_mul_f32 v[108:109], v[66:67], 0.5 op_sel_hi:[1,0]
	v_pk_mul_f32 v[106:107], v[64:65], 0.5 op_sel_hi:[1,0]
	v_pk_mul_f32 v[80:81], v[62:63], 0.5 op_sel_hi:[1,0]
	v_pk_mul_f32 v[82:83], v[60:61], 0.5 op_sel_hi:[1,0]
	v_pk_mul_f32 v[84:85], v[58:59], 0.5 op_sel_hi:[1,0]
	v_pk_mul_f32 v[86:87], v[56:57], 0.5 op_sel_hi:[1,0]
	v_pk_mul_f32 v[88:89], v[46:47], 0.5 op_sel_hi:[1,0]
	v_pk_mul_f32 v[90:91], v[44:45], 0.5 op_sel_hi:[1,0]
	v_pk_mul_f32 v[92:93], v[38:39], 0.5 op_sel_hi:[1,0]
	v_pk_mul_f32 v[94:95], v[36:37], 0.5 op_sel_hi:[1,0]
	v_pk_mul_f32 v[70:71], v[54:55], 0.5 op_sel_hi:[1,0]
	v_pk_mul_f32 v[68:69], v[52:53], 0.5 op_sel_hi:[1,0]
	v_pk_mul_f32 v[66:67], v[50:51], 0.5 op_sel_hi:[1,0]
	v_pk_mul_f32 v[64:65], v[48:49], 0.5 op_sel_hi:[1,0]
	v_pk_mul_f32 v[78:79], v[30:31], 0.5 op_sel_hi:[1,0]
	v_pk_mul_f32 v[76:77], v[28:29], 0.5 op_sel_hi:[1,0]
	v_pk_mul_f32 v[74:75], v[22:23], 0.5 op_sel_hi:[1,0]
	v_pk_mul_f32 v[72:73], v[20:21], 0.5 op_sel_hi:[1,0]
	v_pk_mul_f32 v[54:55], v[42:43], 0.5 op_sel_hi:[1,0]
	v_pk_mul_f32 v[52:53], v[40:41], 0.5 op_sel_hi:[1,0]
	v_pk_mul_f32 v[50:51], v[34:35], 0.5 op_sel_hi:[1,0]
	v_pk_mul_f32 v[48:49], v[32:33], 0.5 op_sel_hi:[1,0]
	v_pk_mul_f32 v[62:63], v[14:15], 0.5 op_sel_hi:[1,0]
	v_pk_mul_f32 v[60:61], v[12:13], 0.5 op_sel_hi:[1,0]
	v_pk_mul_f32 v[58:59], v[10:11], 0.5 op_sel_hi:[1,0]
	v_pk_mul_f32 v[56:57], v[8:9], 0.5 op_sel_hi:[1,0]
	v_pk_mul_f32 v[38:39], v[26:27], 0.5 op_sel_hi:[1,0]
	v_pk_mul_f32 v[36:37], v[24:25], 0.5 op_sel_hi:[1,0]
	v_pk_mul_f32 v[34:35], v[18:19], 0.5 op_sel_hi:[1,0]
	v_pk_mul_f32 v[32:33], v[16:17], 0.5 op_sel_hi:[1,0]
	v_pk_mul_f32 v[46:47], v[6:7], 0.5 op_sel_hi:[1,0]
	v_pk_mul_f32 v[44:45], v[4:5], 0.5 op_sel_hi:[1,0]
	v_pk_mul_f32 v[42:43], v[2:3], 0.5 op_sel_hi:[1,0]
	v_pk_mul_f32 v[40:41], v[0:1], 0.5 op_sel_hi:[1,0]

; #define PG8_STAGE(bufoff, gbase, voff) do { _Pragma("unroll") for (int _i = 0; _i < 2; ++_i) \
;         __builtin_amdgcn_global_load_lds((const unsigned*)((const char*)(gbase) + (voff)[_i]), (LAS unsigned*)(lds + (bufoff) + ldsw + _i * 8192), 16, 0, 0); } while (0)
; #define PG8_LDA(dst, b, h) do { _Pragma("unroll") for (int m = 0; m < 4; ++m) _Pragma("unroll") for (int k = 0; k < 2; ++k) dst[m][k] = *(const LAS bf16x8*)(lds + PG8_SA(b, h) + aoff + m * 2048 + k * 1024); } while (0)
; #define PG8_LDB(dst, b, h) do { _Pragma("unroll") for (int n = 0; n < 2; ++n) _Pragma("unroll") for (int k = 0; k < 2; ++k) dst[n][k] = *(const LAS bf16x8*)(lds + PG8_SB(b, h) + boff + n * 2048 + k * 1024); } while (0)
; #define PG8_MMA(ai, bj, At, Bt) do { __builtin_amdgcn_s_setprio(1); _Pragma("unroll") for (int m = 0; m < 4; ++m) _Pragma("unroll") for (int n = 0; n < 2; ++n) _Pragma("unroll") for (int k = 0; k < 2; ++k) \
;         acc[ai][bj][m][n] = __builtin_amdgcn_mfma_f32_16x16x32_bf16(Bt[n][k], At[m][k], acc[ai][bj][m][n], 0, 0, 0); __builtin_amdgcn_s_setprio(0); } while (0)
; #define PG8_WAIT_V(n) asm volatile("s_waitcnt vmcnt(" #n ")" ::: "memory")
; #define PG8_WAIT_L(n) asm volatile("s_waitcnt lgkmcnt(" #n ")" ::: "memory")
; #define PG8_BAR __builtin_amdgcn_s_barrier()
; #define PG8_SCHED __builtin_amdgcn_sched_barrier(0)
; template <class Epi>
; __device__ __forceinline__ void gemm_phase(LAS unsigned char* lds, const Gemm g, const StaticOrder& S, const Epi& E) {
;     ...
;             const char* a2 = last ? nA : cA + (size_t)(t + 2) * kstep; const char* b2 = last ? nB : cB + (size_t)(t + 2) * kstep;
;             const char* a3 = a2 + kstep; const char* b3 = b2 + kstep;
;             PG8_LDB(B0, 0, 0); PG8_LDB(B1, 0, 1); PG8_SCHED; PG8_LDA(At, 0, 0); PG8_STAGE(PG8_SA(1, 1), a1 + hstepA, voffA);
;             PG8_WAIT_V(8); PG8_WAIT_L(0); PG8_BAR; PG8_MMA(0, 0, At, B0); PG8_MMA(0, 1, At, B1); PG8_BAR; PG8_SCHED;
;             PG8_LDA(At, 0, 1); PG8_STAGE(PG8_SB(0, 0), b2, voffB); PG8_STAGE(PG8_SB(0, 1), b2 + hstepB, voffB); PG8_STAGE(PG8_SA(0, 0), a2, voffA);
;             PG8_WAIT_V(8); PG8_WAIT_L(0); PG8_BAR; PG8_MMA(1, 0, At, B0); PG8_MMA(1, 1, At, B1); PG8_BAR; PG8_SCHED;
.LBB0_1338:
	ds_read_b128 v[128:131], v173
	ds_read_b128 v[132:135], v173 offset:1024
	ds_read_b128 v[136:139], v173 offset:2048
	ds_read_b128 v[140:143], v173 offset:3072
	ds_read_b128 v[144:147], v175
	ds_read_b128 v[148:151], v175 offset:1024
	ds_read_b128 v[176:179], v175 offset:2048
	ds_read_b128 v[184:187], v175 offset:3072
	s_add_i32 s20, s10, 2
	s_add_u32 s11, s8, 0xfff80080
	s_addc_u32 s12, s9, -1
	s_cmp_eq_u32 s56, s10
	s_cselect_b32 s10, s17, s18
	s_cselect_b32 s13, s1, s12
	s_cselect_b32 s12, s15, s11
	s_cselect_b32 s11, s16, s19
	v_lshl_add_u64 v[224:225], s[8:9], 0, v[164:165]
	s_add_i32 m0, s47, 0xc000
	ds_read_b128 v[188:191], v181
	ds_read_b128 v[192:195], v181 offset:1024
	ds_read_b128 v[196:199], v181 offset:2048
	ds_read_b128 v[200:203], v181 offset:3072
	ds_read_b128 v[208:211], v181 offset:4096
	ds_read_b128 v[212:215], v181 offset:5120
	ds_read_b128 v[216:219], v181 offset:6144
	ds_read_b128 v[220:223], v181 offset:7168
	global_load_lds_dwordx4 v[224:225], off
	v_lshl_add_u64 v[224:225], s[8:9], 0, v[166:167]
	s_add_i32 m0, s47, 0xe000
	s_nop 0
	global_load_lds_dwordx4 v[224:225], off
	s_waitcnt vmcnt(8)
	s_waitcnt lgkmcnt(0)
	s_barrier
	s_setprio 1
	s_waitcnt lgkmcnt(0)
	v_mfma_f32_16x16x32_bf16 v[124:127], v[128:131], v[188:191], v[124:127]
	v_mfma_f32_16x16x32_bf16 v[124:127], v[132:135], v[192:195], v[124:127]
	v_mfma_f32_16x16x32_bf16 v[120:123], v[136:139], v[188:191], v[120:123]
	v_mfma_f32_16x16x32_bf16 v[120:123], v[140:143], v[192:195], v[120:123]
	v_mfma_f32_16x16x32_bf16 v[116:119], v[144:147], v[188:191], v[116:119]
	v_mfma_f32_16x16x32_bf16 v[116:119], v[148:151], v[192:195], v[116:119]
	v_mfma_f32_16x16x32_bf16 v[112:115], v[176:179], v[188:191], v[112:115]
	v_mfma_f32_16x16x32_bf16 v[112:115], v[184:187], v[192:195], v[112:115]
	v_mfma_f32_16x16x32_bf16 v[96:99], v[176:179], v[196:199], v[96:99]
	v_mfma_f32_16x16x32_bf16 v[96:99], v[184:187], v[200:203], v[96:99]
	v_mfma_f32_16x16x32_bf16 v[100:103], v[144:147], v[196:199], v[100:103]
	v_mfma_f32_16x16x32_bf16 v[100:103], v[148:151], v[200:203], v[100:103]
	v_mfma_f32_16x16x32_bf16 v[104:107], v[136:139], v[196:199], v[104:107]
	v_mfma_f32_16x16x32_bf16 v[104:107], v[140:143], v[200:203], v[104:107]
	v_mfma_f32_16x16x32_bf16 v[108:111], v[128:131], v[196:199], v[108:111]
	v_mfma_f32_16x16x32_bf16 v[108:111], v[132:135], v[200:203], v[108:111]
	s_setprio 0
	s_setprio 1
	v_mfma_f32_16x16x32_bf16 v[92:95], v[128:131], v[208:211], v[92:95]
	v_mfma_f32_16x16x32_bf16 v[92:95], v[132:135], v[212:215], v[92:95]
	v_mfma_f32_16x16x32_bf16 v[88:91], v[136:139], v[208:211], v[88:91]
	v_mfma_f32_16x16x32_bf16 v[88:91], v[140:143], v[212:215], v[88:91]
	v_mfma_f32_16x16x32_bf16 v[84:87], v[144:147], v[208:211], v[84:87]
	v_mfma_f32_16x16x32_bf16 v[84:87], v[148:151], v[212:215], v[84:87]
	v_mfma_f32_16x16x32_bf16 v[80:83], v[176:179], v[208:211], v[80:83]
	v_mfma_f32_16x16x32_bf16 v[80:83], v[184:187], v[212:215], v[80:83]
	v_mfma_f32_16x16x32_bf16 v[64:67], v[176:179], v[216:219], v[64:67]
	v_mfma_f32_16x16x32_bf16 v[64:67], v[184:187], v[220:223], v[64:67]
	v_mfma_f32_16x16x32_bf16 v[68:71], v[144:147], v[216:219], v[68:71]
	v_mfma_f32_16x16x32_bf16 v[68:71], v[148:151], v[220:223], v[68:71]
	v_mfma_f32_16x16x32_bf16 v[72:75], v[136:139], v[216:219], v[72:75]
	v_mfma_f32_16x16x32_bf16 v[72:75], v[140:143], v[220:223], v[72:75]
	v_mfma_f32_16x16x32_bf16 v[76:79], v[128:131], v[216:219], v[76:79]
	v_mfma_f32_16x16x32_bf16 v[76:79], v[132:135], v[220:223], v[76:79]
	s_setprio 0
	s_barrier
	s_add_i32 s21, s59, s46
	v_lshl_add_u64 v[224:225], s[10:11], 0, v[154:155]
	s_mov_b32 m0, s21
	ds_read_b128 v[188:191], v181 offset:16384
	ds_read_b128 v[192:195], v181 offset:17408
	ds_read_b128 v[196:199], v181 offset:18432
	ds_read_b128 v[200:203], v181 offset:19456
	ds_read_b128 v[208:211], v181 offset:20480
	ds_read_b128 v[212:215], v181 offset:21504
	ds_read_b128 v[216:219], v181 offset:22528
	ds_read_b128 v[220:223], v181 offset:23552
	global_load_lds_dwordx4 v[224:225], off
	s_add_i32 m0, s21, 0x2000
	s_add_u32 s68, s10, 0x80000
	v_lshl_add_u64 v[226:227], s[10:11], 0, v[158:159]
	s_addc_u32 s69, s11, 0
	s_add_i32 s21, s60, s46
	global_load_lds_dwordx4 v[226:227], off
	v_lshl_add_u64 v[230:231], s[68:69], 0, v[154:155]
	s_mov_b32 m0, s21
	v_lshl_add_u64 v[232:233], s[12:13], 0, v[156:157]
	global_load_lds_dwordx4 v[230:231], off
	v_lshl_add_u64 v[230:231], s[68:69], 0, v[158:159]
	s_add_i32 m0, s21, 0x2000
	s_nop 0
	global_load_lds_dwordx4 v[230:231], off
	v_lshl_add_u64 v[230:231], s[12:13], 0, v[152:153]
	s_mov_b32 m0, s47
	s_nop 0
	global_load_lds_dwordx4 v[230:231], off
	s_mov_b32 m0, s48
	s_nop 0
	global_load_lds_dwordx4 v[232:233], off
	s_waitcnt vmcnt(8)
	s_waitcnt lgkmcnt(0)
	s_barrier
; #define PG8_STAGE(bufoff, gbase, voff) do { _Pragma("unroll") for (int _i = 0; _i < 2; ++_i) \
;         __builtin_amdgcn_global_load_lds((const unsigned*)((const char*)(gbase) + (voff)[_i]), (LAS unsigned*)(lds + (bufoff) + ldsw + _i * 8192), 16, 0, 0); } while (0)
; #define PG8_LDA(dst, b, h) do { _Pragma("unroll") for (int m = 0; m < 4; ++m) _Pragma("unroll") for (int k = 0; k < 2; ++k) dst[m][k] = *(const LAS bf16x8*)(lds + PG8_SA(b, h) + aoff + m * 2048 + k * 1024); } while (0)
; #define PG8_LDB(dst, b, h) do { _Pragma("unroll") for (int n = 0; n < 2; ++n) _Pragma("unroll") for (int k = 0; k < 2; ++k) dst[n][k] = *(const LAS bf16x8*)(lds + PG8_SB(b, h) + boff + n * 2048 + k * 1024); } while (0)
; #define PG8_MMA(ai, bj, At, Bt) do { __builtin_amdgcn_s_setprio(1); _Pragma("unroll") for (int m = 0; m < 4; ++m) _Pragma("unroll") for (int n = 0; n < 2; ++n) _Pragma("unroll") for (int k = 0; k < 2; ++k) \
;         acc[ai][bj][m][n] = __builtin_amdgcn_mfma_f32_16x16x32_bf16(Bt[n][k], At[m][k], acc[ai][bj][m][n], 0, 0, 0); __builtin_amdgcn_s_setprio(0); } while (0)
; #define PG8_WAIT_V(n) asm volatile("s_waitcnt vmcnt(" #n ")" ::: "memory")
; #define PG8_WAIT_L(n) asm volatile("s_waitcnt lgkmcnt(" #n ")" ::: "memory")
; #define PG8_BAR __builtin_amdgcn_s_barrier()
; #define PG8_SCHED __builtin_amdgcn_sched_barrier(0)
; template <class Epi>
; __device__ __forceinline__ void gemm_phase(LAS unsigned char* lds, const Gemm g, const StaticOrder& S, const Epi& E) {
;     ...
;             PG8_WAIT_V(8); PG8_WAIT_L(0); PG8_BAR; PG8_MMA(1, 0, At, B0); PG8_MMA(1, 1, At, B1); PG8_BAR; PG8_SCHED;
;             PG8_LDB(B0, 1, 0); PG8_LDB(B1, 1, 1); PG8_SCHED; PG8_LDA(At, 1, 0); PG8_STAGE(PG8_SA(0, 1), a2 + hstepA, voffA);
;             PG8_WAIT_V(8); PG8_WAIT_L(0); PG8_BAR; PG8_MMA(0, 0, At, B0); PG8_MMA(0, 1, At, B1); PG8_BAR; PG8_SCHED;
	s_setprio 1
	s_waitcnt lgkmcnt(0)
	v_mfma_f32_16x16x32_bf16 v[60:63], v[128:131], v[188:191], v[60:63]
	v_mfma_f32_16x16x32_bf16 v[60:63], v[132:135], v[192:195], v[60:63]
	v_mfma_f32_16x16x32_bf16 v[56:59], v[136:139], v[188:191], v[56:59]
	v_mfma_f32_16x16x32_bf16 v[56:59], v[140:143], v[192:195], v[56:59]
	v_mfma_f32_16x16x32_bf16 v[52:55], v[144:147], v[188:191], v[52:55]
	v_mfma_f32_16x16x32_bf16 v[52:55], v[148:151], v[192:195], v[52:55]
	v_mfma_f32_16x16x32_bf16 v[48:51], v[176:179], v[188:191], v[48:51]
	v_mfma_f32_16x16x32_bf16 v[48:51], v[184:187], v[192:195], v[48:51]
	v_mfma_f32_16x16x32_bf16 v[32:35], v[176:179], v[196:199], v[32:35]
	v_mfma_f32_16x16x32_bf16 v[32:35], v[184:187], v[200:203], v[32:35]
	v_mfma_f32_16x16x32_bf16 v[36:39], v[144:147], v[196:199], v[36:39]
	v_mfma_f32_16x16x32_bf16 v[36:39], v[148:151], v[200:203], v[36:39]
	v_mfma_f32_16x16x32_bf16 v[40:43], v[136:139], v[196:199], v[40:43]
	v_mfma_f32_16x16x32_bf16 v[40:43], v[140:143], v[200:203], v[40:43]
	v_mfma_f32_16x16x32_bf16 v[44:47], v[128:131], v[196:199], v[44:47]
	v_mfma_f32_16x16x32_bf16 v[44:47], v[132:135], v[200:203], v[44:47]
	s_setprio 0
	s_setprio 1
	v_mfma_f32_16x16x32_bf16 v[28:31], v[128:131], v[208:211], v[28:31]
	v_mfma_f32_16x16x32_bf16 v[28:31], v[132:135], v[212:215], v[28:31]
	v_mfma_f32_16x16x32_bf16 v[24:27], v[136:139], v[208:211], v[24:27]
	v_mfma_f32_16x16x32_bf16 v[24:27], v[140:143], v[212:215], v[24:27]
	v_mfma_f32_16x16x32_bf16 v[20:23], v[144:147], v[208:211], v[20:23]
	v_mfma_f32_16x16x32_bf16 v[20:23], v[148:151], v[212:215], v[20:23]
	v_mfma_f32_16x16x32_bf16 v[16:19], v[176:179], v[208:211], v[16:19]
	v_mfma_f32_16x16x32_bf16 v[16:19], v[184:187], v[212:215], v[16:19]
	v_mfma_f32_16x16x32_bf16 v[0:3], v[176:179], v[216:219], v[0:3]
	v_mfma_f32_16x16x32_bf16 v[0:3], v[184:187], v[220:223], v[0:3]
	v_mfma_f32_16x16x32_bf16 v[4:7], v[144:147], v[216:219], v[4:7]
	v_mfma_f32_16x16x32_bf16 v[4:7], v[148:151], v[220:223], v[4:7]
	v_mfma_f32_16x16x32_bf16 v[8:11], v[136:139], v[216:219], v[8:11]
	v_mfma_f32_16x16x32_bf16 v[8:11], v[140:143], v[220:223], v[8:11]
	v_mfma_f32_16x16x32_bf16 v[12:15], v[128:131], v[216:219], v[12:15]
	v_mfma_f32_16x16x32_bf16 v[12:15], v[132:135], v[220:223], v[12:15]
	s_setprio 0
	s_barrier
	s_add_i32 s21, 0, 0x18000
	s_add_i32 s33, 0, 0x1c000
	v_add_u32_e32 v140, s21, v163
	v_add_u32_e32 v172, s33, v163
	ds_read_b128 v[128:131], v140
	ds_read_b128 v[132:135], v140 offset:1024
	ds_read_b128 v[136:139], v140 offset:2048
	ds_read_b128 v[140:143], v140 offset:3072
	ds_read_b128 v[144:147], v172
	ds_read_b128 v[148:151], v172 offset:1024
	ds_read_b128 v[176:179], v172 offset:2048
	ds_read_b128 v[184:187], v172 offset:3072
	s_add_u32 s12, s12, 0x80000
	s_addc_u32 s13, s13, 0
	s_mov_b32 m0, s49
	v_lshl_add_u64 v[234:235], s[12:13], 0, v[152:153]
	ds_read_b128 v[188:191], v181 offset:32768
	ds_read_b128 v[192:195], v181 offset:33792
	ds_read_b128 v[196:199], v181 offset:34816
	ds_read_b128 v[200:203], v181 offset:35840
	ds_read_b128 v[208:211], v181 offset:36864
	ds_read_b128 v[212:215], v181 offset:37888
	ds_read_b128 v[216:219], v181 offset:38912
	ds_read_b128 v[220:223], v181 offset:39936
	global_load_lds_dwordx4 v[234:235], off
	v_lshl_add_u64 v[234:235], s[12:13], 0, v[156:157]
	s_mov_b32 m0, s50
	s_nop 0
	global_load_lds_dwordx4 v[234:235], off
	s_waitcnt vmcnt(8)
	s_waitcnt lgkmcnt(0)
	s_barrier
	s_setprio 1
	s_waitcnt lgkmcnt(0)
	v_mfma_f32_16x16x32_bf16 v[124:127], v[128:131], v[188:191], v[124:127]
	v_mfma_f32_16x16x32_bf16 v[124:127], v[132:135], v[192:195], v[124:127]
	v_mfma_f32_16x16x32_bf16 v[120:123], v[136:139], v[188:191], v[120:123]
	v_mfma_f32_16x16x32_bf16 v[120:123], v[140:143], v[192:195], v[120:123]
	v_mfma_f32_16x16x32_bf16 v[116:119], v[144:147], v[188:191], v[116:119]
	v_mfma_f32_16x16x32_bf16 v[116:119], v[148:151], v[192:195], v[116:119]
	v_mfma_f32_16x16x32_bf16 v[112:115], v[176:179], v[188:191], v[112:115]
	v_mfma_f32_16x16x32_bf16 v[112:115], v[184:187], v[192:195], v[112:115]
	v_mfma_f32_16x16x32_bf16 v[96:99], v[176:179], v[196:199], v[96:99]
	v_mfma_f32_16x16x32_bf16 v[96:99], v[184:187], v[200:203], v[96:99]
	v_mfma_f32_16x16x32_bf16 v[100:103], v[144:147], v[196:199], v[100:103]
	v_mfma_f32_16x16x32_bf16 v[100:103], v[148:151], v[200:203], v[100:103]
	v_mfma_f32_16x16x32_bf16 v[104:107], v[136:139], v[196:199], v[104:107]
	v_mfma_f32_16x16x32_bf16 v[104:107], v[140:143], v[200:203], v[104:107]
	v_mfma_f32_16x16x32_bf16 v[108:111], v[128:131], v[196:199], v[108:111]
	v_mfma_f32_16x16x32_bf16 v[108:111], v[132:135], v[200:203], v[108:111]
	s_setprio 0
	s_setprio 1
	v_mfma_f32_16x16x32_bf16 v[92:95], v[128:131], v[208:211], v[92:95]
	v_mfma_f32_16x16x32_bf16 v[92:95], v[132:135], v[212:215], v[92:95]
	v_mfma_f32_16x16x32_bf16 v[88:91], v[136:139], v[208:211], v[88:91]
	v_mfma_f32_16x16x32_bf16 v[88:91], v[140:143], v[212:215], v[88:91]
	v_mfma_f32_16x16x32_bf16 v[84:87], v[144:147], v[208:211], v[84:87]
	v_mfma_f32_16x16x32_bf16 v[84:87], v[148:151], v[212:215], v[84:87]
	v_mfma_f32_16x16x32_bf16 v[80:83], v[176:179], v[208:211], v[80:83]
	v_mfma_f32_16x16x32_bf16 v[80:83], v[184:187], v[212:215], v[80:83]
	v_mfma_f32_16x16x32_bf16 v[64:67], v[176:179], v[216:219], v[64:67]
	v_mfma_f32_16x16x32_bf16 v[64:67], v[184:187], v[220:223], v[64:67]
	v_mfma_f32_16x16x32_bf16 v[68:71], v[144:147], v[216:219], v[68:71]
	v_mfma_f32_16x16x32_bf16 v[68:71], v[148:151], v[220:223], v[68:71]
	v_mfma_f32_16x16x32_bf16 v[72:75], v[136:139], v[216:219], v[72:75]
	v_mfma_f32_16x16x32_bf16 v[72:75], v[140:143], v[220:223], v[72:75]
	v_mfma_f32_16x16x32_bf16 v[76:79], v[128:131], v[216:219], v[76:79]
	v_mfma_f32_16x16x32_bf16 v[76:79], v[132:135], v[220:223], v[76:79]
	s_setprio 0
	s_barrier
; #define PG8_STAGE(bufoff, gbase, voff) do { _Pragma("unroll") for (int _i = 0; _i < 2; ++_i) \
;         __builtin_amdgcn_global_load_lds((const unsigned*)((const char*)(gbase) + (voff)[_i]), (LAS unsigned*)(lds + (bufoff) + ldsw + _i * 8192), 16, 0, 0); } while (0)
; #define PG8_LDA(dst, b, h) do { _Pragma("unroll") for (int m = 0; m < 4; ++m) _Pragma("unroll") for (int k = 0; k < 2; ++k) dst[m][k] = *(const LAS bf16x8*)(lds + PG8_SA(b, h) + aoff + m * 2048 + k * 1024); } while (0)
; #define PG8_MMA(ai, bj, At, Bt) do { __builtin_amdgcn_s_setprio(1); _Pragma("unroll") for (int m = 0; m < 4; ++m) _Pragma("unroll") for (int n = 0; n < 2; ++n) _Pragma("unroll") for (int k = 0; k < 2; ++k) \
;         acc[ai][bj][m][n] = __builtin_amdgcn_mfma_f32_16x16x32_bf16(Bt[n][k], At[m][k], acc[ai][bj][m][n], 0, 0, 0); __builtin_amdgcn_s_setprio(0); } while (0)
; #define PG8_WAIT_V(n) asm volatile("s_waitcnt vmcnt(" #n ")" ::: "memory")
; #define PG8_WAIT_L(n) asm volatile("s_waitcnt lgkmcnt(" #n ")" ::: "memory")
; #define PG8_BAR __builtin_amdgcn_s_barrier()
; #define PG8_SCHED __builtin_amdgcn_sched_barrier(0)
; template <class Epi>
; __device__ __forceinline__ void gemm_phase(LAS unsigned char* lds, const Gemm g, const StaticOrder& S, const Epi& E) {
;     ...
;             PG8_LDA(At, 1, 1); PG8_STAGE(PG8_SB(1, 0), b3, voffB); PG8_STAGE(PG8_SB(1, 1), b3 + hstepB, voffB); PG8_STAGE(PG8_SA(1, 0), a3, voffA);
;             PG8_WAIT_V(8); PG8_WAIT_L(0); PG8_BAR; PG8_MMA(1, 0, At, B0); PG8_MMA(1, 1, At, B1); PG8_BAR; PG8_SCHED;
;         }
	s_add_i32 s12, s21, s46
	v_lshl_add_u64 v[224:225], v[224:225], 0, s[28:29]
	s_mov_b32 m0, s12
	ds_read_b128 v[188:191], v181 offset:49152
	ds_read_b128 v[192:195], v181 offset:50176
	ds_read_b128 v[196:199], v181 offset:51200
	ds_read_b128 v[200:203], v181 offset:52224
	ds_read_b128 v[208:211], v181 offset:53248
	ds_read_b128 v[212:215], v181 offset:54272
	ds_read_b128 v[216:219], v181 offset:55296
	ds_read_b128 v[220:223], v181 offset:56320
	global_load_lds_dwordx4 v[224:225], off
	s_add_i32 m0, s12, 0x2000
	s_add_u32 s10, s10, 0x80080
	v_lshl_add_u64 v[224:225], v[226:227], 0, s[28:29]
	s_addc_u32 s11, s11, 0
	s_add_i32 s12, s33, s46
	global_load_lds_dwordx4 v[224:225], off
	v_lshl_add_u64 v[224:225], s[10:11], 0, v[154:155]
	s_mov_b32 m0, s12
	s_nop 0
	global_load_lds_dwordx4 v[224:225], off
	v_lshl_add_u64 v[224:225], s[10:11], 0, v[158:159]
	s_add_i32 m0, s12, 0x2000
	s_nop 0
	global_load_lds_dwordx4 v[224:225], off
	v_lshl_add_u64 v[224:225], v[230:231], 0, s[28:29]
	s_mov_b32 m0, s54
	s_nop 0
	global_load_lds_dwordx4 v[224:225], off
	v_lshl_add_u64 v[224:225], v[232:233], 0, s[28:29]
	s_mov_b32 m0, s55
	s_nop 0
	global_load_lds_dwordx4 v[224:225], off
	s_waitcnt vmcnt(8)
	s_waitcnt lgkmcnt(0)
	s_barrier
	s_setprio 1
	s_waitcnt lgkmcnt(0)
	v_mfma_f32_16x16x32_bf16 v[60:63], v[128:131], v[188:191], v[60:63]
	v_mfma_f32_16x16x32_bf16 v[60:63], v[132:135], v[192:195], v[60:63]
	v_mfma_f32_16x16x32_bf16 v[56:59], v[136:139], v[188:191], v[56:59]
	v_mfma_f32_16x16x32_bf16 v[56:59], v[140:143], v[192:195], v[56:59]
	v_mfma_f32_16x16x32_bf16 v[52:55], v[144:147], v[188:191], v[52:55]
	v_mfma_f32_16x16x32_bf16 v[52:55], v[148:151], v[192:195], v[52:55]
	v_mfma_f32_16x16x32_bf16 v[48:51], v[176:179], v[188:191], v[48:51]
	v_mfma_f32_16x16x32_bf16 v[48:51], v[184:187], v[192:195], v[48:51]
	v_mfma_f32_16x16x32_bf16 v[32:35], v[176:179], v[196:199], v[32:35]
	v_mfma_f32_16x16x32_bf16 v[32:35], v[184:187], v[200:203], v[32:35]
	v_mfma_f32_16x16x32_bf16 v[36:39], v[144:147], v[196:199], v[36:39]
	v_mfma_f32_16x16x32_bf16 v[36:39], v[148:151], v[200:203], v[36:39]
	v_mfma_f32_16x16x32_bf16 v[40:43], v[136:139], v[196:199], v[40:43]
	v_mfma_f32_16x16x32_bf16 v[40:43], v[140:143], v[200:203], v[40:43]
	v_mfma_f32_16x16x32_bf16 v[44:47], v[128:131], v[196:199], v[44:47]
	v_mfma_f32_16x16x32_bf16 v[44:47], v[132:135], v[200:203], v[44:47]
	s_setprio 0
	s_setprio 1
	v_mfma_f32_16x16x32_bf16 v[28:31], v[128:131], v[208:211], v[28:31]
	v_mfma_f32_16x16x32_bf16 v[28:31], v[132:135], v[212:215], v[28:31]
	v_mfma_f32_16x16x32_bf16 v[24:27], v[136:139], v[208:211], v[24:27]
	v_mfma_f32_16x16x32_bf16 v[24:27], v[140:143], v[212:215], v[24:27]
	v_mfma_f32_16x16x32_bf16 v[20:23], v[144:147], v[208:211], v[20:23]
	v_mfma_f32_16x16x32_bf16 v[20:23], v[148:151], v[212:215], v[20:23]
	v_mfma_f32_16x16x32_bf16 v[16:19], v[176:179], v[208:211], v[16:19]
	v_mfma_f32_16x16x32_bf16 v[16:19], v[184:187], v[212:215], v[16:19]
	v_mfma_f32_16x16x32_bf16 v[0:3], v[176:179], v[216:219], v[0:3]
	v_mfma_f32_16x16x32_bf16 v[0:3], v[184:187], v[220:223], v[0:3]
	v_mfma_f32_16x16x32_bf16 v[4:7], v[144:147], v[216:219], v[4:7]
	v_mfma_f32_16x16x32_bf16 v[4:7], v[148:151], v[220:223], v[4:7]
	v_mfma_f32_16x16x32_bf16 v[8:11], v[136:139], v[216:219], v[8:11]
	v_mfma_f32_16x16x32_bf16 v[8:11], v[140:143], v[220:223], v[8:11]
	v_mfma_f32_16x16x32_bf16 v[12:15], v[128:131], v[216:219], v[12:15]
	v_mfma_f32_16x16x32_bf16 v[12:15], v[132:135], v[220:223], v[12:15]
	s_setprio 0
	s_barrier
	s_add_u32 s8, s8, 0x100
	s_addc_u32 s9, s9, 0
	s_add_u32 s18, s18, 0x100
	s_addc_u32 s19, s19, 0
	s_cmp_ge_i32 s20, s53
	s_mov_b32 s10, s20
	s_cbranch_scc0 .LBB0_1338
